# speedup vs baseline: 1.1645x; 1.0680x over previous
; __device__ __forceinline__ float bf2f(bf16_t h) { return __uint_as_float(((unsigned)h) << 16); }
; __device__ __forceinline__ void phase_hyena_post(const Params& p, int l, const int tidx) {
;     ...
;   for (int task = blockIdx.x; task < T / 32; task += gridDim.x) {
;     const int row0 = task * 32;
;     const int t0 = row0 % SEQ;
;     bf16_t* pv = P + (size_t)row0 * NP + OFF_BU + 512 + c;
;     bf16_t* pz = P + (size_t)row0 * NP + OFF_BZ + c;
;     const u32x4* src = (const u32x4*)(YT + (size_t)c * T + row0);
;     u32x4 yv[4];
; #pragma unroll
;     for (int q = 0; q < 4; q++) yv[q] = src[q];
;     float xm = (t0 > 0) ? bf2f(pv[-(ptrdiff_t)NP]) : 0.f, xc = bf2f(pv[0]);
;     bf16_t zbr[32], xnr[32];
; #pragma unroll
;     for (int i = 0; i < 32; i++) {
;       zbr[i] = pz[(size_t)i * NP];
;       xnr[i] = (t0 + i < SEQ - 1) ? pv[(size_t)(i + 1) * NP] : (bf16_t)0;
;     }
.LBB0_95:
	v_lshlrev_b32_e32 v8, 1, v150
	v_add_u32_e32 v9, 0x1400, v8
	s_waitcnt vmcnt(0)
.Lhp_loop:
	v_mov_b32_e32 v26, 0
	v_mov_b32_e32 v27, 0
	v_mov_b32_e32 v28, 0
	v_mov_b32_e32 v29, 0
	v_mov_b32_e32 v30, 0
	v_mov_b32_e32 v31, 0
	v_mov_b32_e32 v32, 0
	v_mov_b32_e32 v33, 0
	v_mov_b32_e32 v34, 0
	v_mov_b32_e32 v35, 0
	v_mov_b32_e32 v36, 0
	v_mov_b32_e32 v37, 0
	v_mov_b32_e32 v38, 0
	v_mov_b32_e32 v39, 0
	v_mov_b32_e32 v40, 0
	v_mov_b32_e32 v41, 0
	v_mov_b32_e32 v42, 0
	v_mov_b32_e32 v43, 0
	v_mov_b32_e32 v44, 0
	v_mov_b32_e32 v45, 0
	v_mov_b32_e32 v46, 0
	v_mov_b32_e32 v47, 0
	v_mov_b32_e32 v48, 0
	v_mov_b32_e32 v49, 0
	v_mov_b32_e32 v50, 0
	v_mov_b32_e32 v51, 0
	v_mov_b32_e32 v52, 0
	v_mov_b32_e32 v53, 0
	v_mov_b32_e32 v54, 0
	v_mov_b32_e32 v55, 0
	v_mov_b32_e32 v56, 0
	v_mov_b32_e32 v57, 0
	v_mov_b32_e32 v58, 0
	v_mov_b32_e32 v59, 0
	v_mov_b32_e32 v92, 0
	v_mov_b32_e32 v93, 0
	v_mov_b32_e32 v94, 0
	v_mov_b32_e32 v95, 0
	v_mov_b32_e32 v96, 0
	v_mov_b32_e32 v97, 0
	v_mov_b32_e32 v98, 0
	v_mov_b32_e32 v99, 0
	v_mov_b32_e32 v100, 0
	v_mov_b32_e32 v101, 0
	v_mov_b32_e32 v102, 0
	v_mov_b32_e32 v103, 0
	v_mov_b32_e32 v104, 0
	v_mov_b32_e32 v105, 0
	v_mov_b32_e32 v106, 0
	v_mov_b32_e32 v107, 0
	v_mov_b32_e32 v108, 0
	v_mov_b32_e32 v109, 0
	v_mov_b32_e32 v110, 0
	v_mov_b32_e32 v111, 0
	v_mov_b32_e32 v112, 0
	v_mov_b32_e32 v113, 0
	v_mov_b32_e32 v114, 0
	v_mov_b32_e32 v115, 0
	v_mov_b32_e32 v116, 0
	v_mov_b32_e32 v117, 0
	v_mov_b32_e32 v118, 0
	v_mov_b32_e32 v119, 0
	v_mov_b32_e32 v120, 0
	v_mov_b32_e32 v121, 0
	v_mov_b32_e32 v122, 0
	v_mov_b32_e32 v123, 0
	s_mov_b32 s13, 0
	v_lshl_add_u64 v[10:11], s[12:13], 1, v[24:25]
	global_load_dwordx4 v[124:127], v[10:11], off
	global_load_dwordx4 v[128:131], v[10:11], off offset:16
	global_load_dwordx4 v[132:135], v[10:11], off offset:32
	global_load_dwordx4 v[136:139], v[10:11], off offset:48
	s_and_b32 s5, s12, 0xfff
	s_mul_i32 s14, s12, 0x3a00
	s_mul_hi_u32 s15, s12, 0x3a00
	s_add_u32 s14, s14, s94
	s_addc_u32 s15, s15, s95
	s_mov_b32 s66, s14
	s_mov_b32 s67, s15
	s_cmp_eq_u32 s5, 0
	s_cbranch_scc1 .Lhp_rows
	s_sub_u32 s98, s14, 0x3a00
	s_subb_u32 s99, s15, 0
	global_load_short_d16_hi v26, v8, s[98:99] offset:3072
.Lhp_rows:
	global_load_short_d16_hi v27, v8, s[14:15] offset:3072
	global_load_short_d16_hi v92, v9, s[14:15]
	s_add_u32 s14, s14, 0x3a00
	s_addc_u32 s15, s15, 0
	global_load_short_d16_hi v28, v8, s[14:15] offset:3072
	global_load_short_d16_hi v93, v9, s[14:15]
	s_add_u32 s14, s14, 0x3a00
	s_addc_u32 s15, s15, 0
	global_load_short_d16_hi v29, v8, s[14:15] offset:3072
	global_load_short_d16_hi v94, v9, s[14:15]
	s_add_u32 s14, s14, 0x3a00
	s_addc_u32 s15, s15, 0
	global_load_short_d16_hi v30, v8, s[14:15] offset:3072
	global_load_short_d16_hi v95, v9, s[14:15]
	s_add_u32 s14, s14, 0x3a00
	s_addc_u32 s15, s15, 0
	global_load_short_d16_hi v31, v8, s[14:15] offset:3072
	global_load_short_d16_hi v96, v9, s[14:15]
	s_add_u32 s14, s14, 0x3a00
	s_addc_u32 s15, s15, 0
	global_load_short_d16_hi v32, v8, s[14:15] offset:3072
	global_load_short_d16_hi v97, v9, s[14:15]
	s_add_u32 s14, s14, 0x3a00
	s_addc_u32 s15, s15, 0
	global_load_short_d16_hi v33, v8, s[14:15] offset:3072
	global_load_short_d16_hi v98, v9, s[14:15]
	s_add_u32 s14, s14, 0x3a00
	s_addc_u32 s15, s15, 0
	global_load_short_d16_hi v34, v8, s[14:15] offset:3072
	global_load_short_d16_hi v99, v9, s[14:15]
	s_add_u32 s14, s14, 0x3a00
	s_addc_u32 s15, s15, 0
	global_load_short_d16_hi v35, v8, s[14:15] offset:3072
	global_load_short_d16_hi v100, v9, s[14:15]
	s_add_u32 s14, s14, 0x3a00
	s_addc_u32 s15, s15, 0
	global_load_short_d16_hi v36, v8, s[14:15] offset:3072
	global_load_short_d16_hi v101, v9, s[14:15]
	s_add_u32 s14, s14, 0x3a00
	s_addc_u32 s15, s15, 0
	global_load_short_d16_hi v37, v8, s[14:15] offset:3072
	global_load_short_d16_hi v102, v9, s[14:15]
	s_add_u32 s14, s14, 0x3a00
	s_addc_u32 s15, s15, 0
	global_load_short_d16_hi v38, v8, s[14:15] offset:3072
	global_load_short_d16_hi v103, v9, s[14:15]
	s_add_u32 s14, s14, 0x3a00
	s_addc_u32 s15, s15, 0
	global_load_short_d16_hi v39, v8, s[14:15] offset:3072
	global_load_short_d16_hi v104, v9, s[14:15]
	s_add_u32 s14, s14, 0x3a00
	s_addc_u32 s15, s15, 0
	global_load_short_d16_hi v40, v8, s[14:15] offset:3072
	global_load_short_d16_hi v105, v9, s[14:15]
	s_add_u32 s14, s14, 0x3a00
	s_addc_u32 s15, s15, 0
	global_load_short_d16_hi v41, v8, s[14:15] offset:3072
	global_load_short_d16_hi v106, v9, s[14:15]
	s_add_u32 s14, s14, 0x3a00
	s_addc_u32 s15, s15, 0
	global_load_short_d16_hi v42, v8, s[14:15] offset:3072
	global_load_short_d16_hi v107, v9, s[14:15]
	s_add_u32 s14, s14, 0x3a00
	s_addc_u32 s15, s15, 0
	global_load_short_d16_hi v43, v8, s[14:15] offset:3072
	global_load_short_d16_hi v108, v9, s[14:15]
	s_add_u32 s14, s14, 0x3a00
	s_addc_u32 s15, s15, 0
	global_load_short_d16_hi v44, v8, s[14:15] offset:3072
	global_load_short_d16_hi v109, v9, s[14:15]
	s_add_u32 s14, s14, 0x3a00
	s_addc_u32 s15, s15, 0
	global_load_short_d16_hi v45, v8, s[14:15] offset:3072
	global_load_short_d16_hi v110, v9, s[14:15]
	s_add_u32 s14, s14, 0x3a00
	s_addc_u32 s15, s15, 0
	global_load_short_d16_hi v46, v8, s[14:15] offset:3072
	global_load_short_d16_hi v111, v9, s[14:15]
	s_add_u32 s14, s14, 0x3a00
	s_addc_u32 s15, s15, 0
	global_load_short_d16_hi v47, v8, s[14:15] offset:3072
	global_load_short_d16_hi v112, v9, s[14:15]
	s_add_u32 s14, s14, 0x3a00
	s_addc_u32 s15, s15, 0
	global_load_short_d16_hi v48, v8, s[14:15] offset:3072
	global_load_short_d16_hi v113, v9, s[14:15]
	s_add_u32 s14, s14, 0x3a00
	s_addc_u32 s15, s15, 0
	global_load_short_d16_hi v49, v8, s[14:15] offset:3072
	global_load_short_d16_hi v114, v9, s[14:15]
; __device__ __forceinline__ float bf2f(bf16_t h) { return __uint_as_float(((unsigned)h) << 16); }
; __device__ __forceinline__ float siluf_(float x) { return x * __builtin_amdgcn_rcpf(1.f + __expf(-x)); }
; __device__ __forceinline__ void phase_hyena_post(const Params& p, int l, const int tidx) {
;     ...
;     for (int i = 0; i < 32; i++) {
;       zbr[i] = pz[(size_t)i * NP];
;       xnr[i] = (t0 + i < SEQ - 1) ? pv[(size_t)(i + 1) * NP] : (bf16_t)0;
;     }
; #pragma unroll
;     for (int i = 0; i < 32; i++) {
;       float xn = bf2f(xnr[i]);
;       float x0 = w0 * xm + w1 * xc + w2 * xn + bx;
;       unsigned wd = yv[i >> 3][(i >> 1) & 3];
;       float y = bf2f((bf16_t)((i & 1) ? (wd >> 16) : (wd & 0xffff)));
;       float zb = bf2f(zbr[i]);
;       pz[(size_t)i * NP] = f2bf(x0 * y * siluf_(zb));
;       xm = xc; xc = xn;
;     }
	s_add_u32 s14, s14, 0x3a00
	s_addc_u32 s15, s15, 0
	global_load_short_d16_hi v50, v8, s[14:15] offset:3072
	global_load_short_d16_hi v115, v9, s[14:15]
	s_add_u32 s14, s14, 0x3a00
	s_addc_u32 s15, s15, 0
	global_load_short_d16_hi v51, v8, s[14:15] offset:3072
	global_load_short_d16_hi v116, v9, s[14:15]
	s_add_u32 s14, s14, 0x3a00
	s_addc_u32 s15, s15, 0
	global_load_short_d16_hi v52, v8, s[14:15] offset:3072
	global_load_short_d16_hi v117, v9, s[14:15]
	s_add_u32 s14, s14, 0x3a00
	s_addc_u32 s15, s15, 0
	global_load_short_d16_hi v53, v8, s[14:15] offset:3072
	global_load_short_d16_hi v118, v9, s[14:15]
	s_add_u32 s14, s14, 0x3a00
	s_addc_u32 s15, s15, 0
	global_load_short_d16_hi v54, v8, s[14:15] offset:3072
	global_load_short_d16_hi v119, v9, s[14:15]
	s_add_u32 s14, s14, 0x3a00
	s_addc_u32 s15, s15, 0
	global_load_short_d16_hi v55, v8, s[14:15] offset:3072
	global_load_short_d16_hi v120, v9, s[14:15]
	s_add_u32 s14, s14, 0x3a00
	s_addc_u32 s15, s15, 0
	global_load_short_d16_hi v56, v8, s[14:15] offset:3072
	global_load_short_d16_hi v121, v9, s[14:15]
	s_add_u32 s14, s14, 0x3a00
	s_addc_u32 s15, s15, 0
	global_load_short_d16_hi v57, v8, s[14:15] offset:3072
	global_load_short_d16_hi v122, v9, s[14:15]
	s_add_u32 s14, s14, 0x3a00
	s_addc_u32 s15, s15, 0
	global_load_short_d16_hi v58, v8, s[14:15] offset:3072
	global_load_short_d16_hi v123, v9, s[14:15]
	s_add_u32 s14, s14, 0x3a00
	s_addc_u32 s15, s15, 0
	s_cmpk_eq_i32 s5, 0xfe0
	s_cbranch_scc1 .Lhp_comp
	global_load_short_d16_hi v59, v8, s[14:15] offset:3072
.Lhp_comp:
	s_waitcnt vmcnt(0)
	v_mul_f32_e32 v10, v89, v27
	v_mul_f32_e32 v11, 0xbfb8aa3b, v92
	v_fmac_f32_e32 v10, v0, v26
	v_exp_f32_e32 v11, v11
	v_fmac_f32_e32 v10, v90, v28
	v_lshlrev_b32_e32 v12, 16, v124
	v_add_f32_e32 v10, v91, v10
	v_add_f32_e32 v11, 1.0, v11
	v_mul_f32_e32 v10, v10, v12
	v_rcp_f32_e32 v11, v11
	v_mul_f32_e32 v13, v89, v28
	v_mul_f32_e32 v14, 0xbfb8aa3b, v93
	v_fmac_f32_e32 v13, v0, v27
	v_exp_f32_e32 v14, v14
	v_fmac_f32_e32 v13, v90, v29
	v_and_b32_e32 v15, 0xffff0000, v124
	v_add_f32_e32 v13, v91, v13
	v_add_f32_e32 v14, 1.0, v14
	v_mul_f32_e32 v13, v13, v15
	v_rcp_f32_e32 v14, v14
	v_mul_f32_e32 v11, v11, v92
	v_mul_f32_e32 v10, v11, v10
	v_mul_f32_e32 v14, v14, v93
	v_mul_f32_e32 v13, v14, v13
	v_cvt_pk_bf16_f32 v92, v10, v13
	global_store_short v9, v92, s[66:67]
	s_add_u32 s66, s66, 0x3a00
	s_addc_u32 s67, s67, 0
	global_store_short_d16_hi v9, v92, s[66:67]
	s_add_u32 s66, s66, 0x3a00
	s_addc_u32 s67, s67, 0
	v_mul_f32_e32 v10, v89, v29
	v_mul_f32_e32 v11, 0xbfb8aa3b, v94
	v_fmac_f32_e32 v10, v0, v28
	v_exp_f32_e32 v11, v11
	v_fmac_f32_e32 v10, v90, v30
	v_lshlrev_b32_e32 v12, 16, v125
	v_add_f32_e32 v10, v91, v10
	v_add_f32_e32 v11, 1.0, v11
	v_mul_f32_e32 v10, v10, v12
	v_rcp_f32_e32 v11, v11
	v_mul_f32_e32 v13, v89, v30
	v_mul_f32_e32 v14, 0xbfb8aa3b, v95
	v_fmac_f32_e32 v13, v0, v29
	v_exp_f32_e32 v14, v14
	v_fmac_f32_e32 v13, v90, v31
	v_and_b32_e32 v15, 0xffff0000, v125
	v_add_f32_e32 v13, v91, v13
	v_add_f32_e32 v14, 1.0, v14
	v_mul_f32_e32 v13, v13, v15
	v_rcp_f32_e32 v14, v14
	v_mul_f32_e32 v11, v11, v94
	v_mul_f32_e32 v10, v11, v10
	v_mul_f32_e32 v14, v14, v95
	v_mul_f32_e32 v13, v14, v13
	v_cvt_pk_bf16_f32 v94, v10, v13
	global_store_short v9, v94, s[66:67]
	s_add_u32 s66, s66, 0x3a00
	s_addc_u32 s67, s67, 0
	global_store_short_d16_hi v9, v94, s[66:67]
	s_add_u32 s66, s66, 0x3a00
	s_addc_u32 s67, s67, 0
	v_mul_f32_e32 v10, v89, v31
	v_mul_f32_e32 v11, 0xbfb8aa3b, v96
	v_fmac_f32_e32 v10, v0, v30
	v_exp_f32_e32 v11, v11
	v_fmac_f32_e32 v10, v90, v32
	v_lshlrev_b32_e32 v12, 16, v126
	v_add_f32_e32 v10, v91, v10
	v_add_f32_e32 v11, 1.0, v11
	v_mul_f32_e32 v10, v10, v12
	v_rcp_f32_e32 v11, v11
	v_mul_f32_e32 v13, v89, v32
	v_mul_f32_e32 v14, 0xbfb8aa3b, v97
	v_fmac_f32_e32 v13, v0, v31
	v_exp_f32_e32 v14, v14
	v_fmac_f32_e32 v13, v90, v33
	v_and_b32_e32 v15, 0xffff0000, v126
	v_add_f32_e32 v13, v91, v13
	v_add_f32_e32 v14, 1.0, v14
	v_mul_f32_e32 v13, v13, v15
	v_rcp_f32_e32 v14, v14
	v_mul_f32_e32 v11, v11, v96
	v_mul_f32_e32 v10, v11, v10
	v_mul_f32_e32 v14, v14, v97
	v_mul_f32_e32 v13, v14, v13
	v_cvt_pk_bf16_f32 v96, v10, v13
	global_store_short v9, v96, s[66:67]
	s_add_u32 s66, s66, 0x3a00
	s_addc_u32 s67, s67, 0
	global_store_short_d16_hi v9, v96, s[66:67]
	s_add_u32 s66, s66, 0x3a00
	s_addc_u32 s67, s67, 0
	v_mul_f32_e32 v10, v89, v33
	v_mul_f32_e32 v11, 0xbfb8aa3b, v98
	v_fmac_f32_e32 v10, v0, v32
	v_exp_f32_e32 v11, v11
	v_fmac_f32_e32 v10, v90, v34
	v_lshlrev_b32_e32 v12, 16, v127
	v_add_f32_e32 v10, v91, v10
	v_add_f32_e32 v11, 1.0, v11
	v_mul_f32_e32 v10, v10, v12
	v_rcp_f32_e32 v11, v11
	v_mul_f32_e32 v13, v89, v34
	v_mul_f32_e32 v14, 0xbfb8aa3b, v99
	v_fmac_f32_e32 v13, v0, v33
	v_exp_f32_e32 v14, v14
	v_fmac_f32_e32 v13, v90, v35
	v_and_b32_e32 v15, 0xffff0000, v127
	v_add_f32_e32 v13, v91, v13
	v_add_f32_e32 v14, 1.0, v14
	v_mul_f32_e32 v13, v13, v15
	v_rcp_f32_e32 v14, v14
	v_mul_f32_e32 v11, v11, v98
	v_mul_f32_e32 v10, v11, v10
	v_mul_f32_e32 v14, v14, v99
	v_mul_f32_e32 v13, v14, v13
	v_cvt_pk_bf16_f32 v98, v10, v13
	global_store_short v9, v98, s[66:67]
	s_add_u32 s66, s66, 0x3a00
	s_addc_u32 s67, s67, 0
	global_store_short_d16_hi v9, v98, s[66:67]
	s_add_u32 s66, s66, 0x3a00
	s_addc_u32 s67, s67, 0
	v_mul_f32_e32 v10, v89, v35
	v_mul_f32_e32 v11, 0xbfb8aa3b, v100
	v_fmac_f32_e32 v10, v0, v34
	v_exp_f32_e32 v11, v11
	v_fmac_f32_e32 v10, v90, v36
	v_lshlrev_b32_e32 v12, 16, v128
	v_add_f32_e32 v10, v91, v10
	v_add_f32_e32 v11, 1.0, v11
	v_mul_f32_e32 v10, v10, v12
	v_rcp_f32_e32 v11, v11
	v_mul_f32_e32 v13, v89, v36
	v_mul_f32_e32 v14, 0xbfb8aa3b, v101
	v_fmac_f32_e32 v13, v0, v35
; __device__ __forceinline__ float bf2f(bf16_t h) { return __uint_as_float(((unsigned)h) << 16); }
; __device__ __forceinline__ float siluf_(float x) { return x * __builtin_amdgcn_rcpf(1.f + __expf(-x)); }
; __device__ __forceinline__ void phase_hyena_post(const Params& p, int l, const int tidx) {
;     ...
;     for (int i = 0; i < 32; i++) {
;       float xn = bf2f(xnr[i]);
;       float x0 = w0 * xm + w1 * xc + w2 * xn + bx;
;       unsigned wd = yv[i >> 3][(i >> 1) & 3];
;       float y = bf2f((bf16_t)((i & 1) ? (wd >> 16) : (wd & 0xffff)));
;       float zb = bf2f(zbr[i]);
;       pz[(size_t)i * NP] = f2bf(x0 * y * siluf_(zb));
;       xm = xc; xc = xn;
;     }
	v_exp_f32_e32 v14, v14
	v_fmac_f32_e32 v13, v90, v37
	v_and_b32_e32 v15, 0xffff0000, v128
	v_add_f32_e32 v13, v91, v13
	v_add_f32_e32 v14, 1.0, v14
	v_mul_f32_e32 v13, v13, v15
	v_rcp_f32_e32 v14, v14
	v_mul_f32_e32 v11, v11, v100
	v_mul_f32_e32 v10, v11, v10
	v_mul_f32_e32 v14, v14, v101
	v_mul_f32_e32 v13, v14, v13
	v_cvt_pk_bf16_f32 v100, v10, v13
	global_store_short v9, v100, s[66:67]
	s_add_u32 s66, s66, 0x3a00
	s_addc_u32 s67, s67, 0
	global_store_short_d16_hi v9, v100, s[66:67]
	s_add_u32 s66, s66, 0x3a00
	s_addc_u32 s67, s67, 0
	v_mul_f32_e32 v10, v89, v37
	v_mul_f32_e32 v11, 0xbfb8aa3b, v102
	v_fmac_f32_e32 v10, v0, v36
	v_exp_f32_e32 v11, v11
	v_fmac_f32_e32 v10, v90, v38
	v_lshlrev_b32_e32 v12, 16, v129
	v_add_f32_e32 v10, v91, v10
	v_add_f32_e32 v11, 1.0, v11
	v_mul_f32_e32 v10, v10, v12
	v_rcp_f32_e32 v11, v11
	v_mul_f32_e32 v13, v89, v38
	v_mul_f32_e32 v14, 0xbfb8aa3b, v103
	v_fmac_f32_e32 v13, v0, v37
	v_exp_f32_e32 v14, v14
	v_fmac_f32_e32 v13, v90, v39
	v_and_b32_e32 v15, 0xffff0000, v129
	v_add_f32_e32 v13, v91, v13
	v_add_f32_e32 v14, 1.0, v14
	v_mul_f32_e32 v13, v13, v15
	v_rcp_f32_e32 v14, v14
	v_mul_f32_e32 v11, v11, v102
	v_mul_f32_e32 v10, v11, v10
	v_mul_f32_e32 v14, v14, v103
	v_mul_f32_e32 v13, v14, v13
	v_cvt_pk_bf16_f32 v102, v10, v13
	global_store_short v9, v102, s[66:67]
	s_add_u32 s66, s66, 0x3a00
	s_addc_u32 s67, s67, 0
	global_store_short_d16_hi v9, v102, s[66:67]
	s_add_u32 s66, s66, 0x3a00
	s_addc_u32 s67, s67, 0
	v_mul_f32_e32 v10, v89, v39
	v_mul_f32_e32 v11, 0xbfb8aa3b, v104
	v_fmac_f32_e32 v10, v0, v38
	v_exp_f32_e32 v11, v11
	v_fmac_f32_e32 v10, v90, v40
	v_lshlrev_b32_e32 v12, 16, v130
	v_add_f32_e32 v10, v91, v10
	v_add_f32_e32 v11, 1.0, v11
	v_mul_f32_e32 v10, v10, v12
	v_rcp_f32_e32 v11, v11
	v_mul_f32_e32 v13, v89, v40
	v_mul_f32_e32 v14, 0xbfb8aa3b, v105
	v_fmac_f32_e32 v13, v0, v39
	v_exp_f32_e32 v14, v14
	v_fmac_f32_e32 v13, v90, v41
	v_and_b32_e32 v15, 0xffff0000, v130
	v_add_f32_e32 v13, v91, v13
	v_add_f32_e32 v14, 1.0, v14
	v_mul_f32_e32 v13, v13, v15
	v_rcp_f32_e32 v14, v14
	v_mul_f32_e32 v11, v11, v104
	v_mul_f32_e32 v10, v11, v10
	v_mul_f32_e32 v14, v14, v105
	v_mul_f32_e32 v13, v14, v13
	v_cvt_pk_bf16_f32 v104, v10, v13
	global_store_short v9, v104, s[66:67]
	s_add_u32 s66, s66, 0x3a00
	s_addc_u32 s67, s67, 0
	global_store_short_d16_hi v9, v104, s[66:67]
	s_add_u32 s66, s66, 0x3a00
	s_addc_u32 s67, s67, 0
	v_mul_f32_e32 v10, v89, v41
	v_mul_f32_e32 v11, 0xbfb8aa3b, v106
	v_fmac_f32_e32 v10, v0, v40
	v_exp_f32_e32 v11, v11
	v_fmac_f32_e32 v10, v90, v42
	v_lshlrev_b32_e32 v12, 16, v131
	v_add_f32_e32 v10, v91, v10
	v_add_f32_e32 v11, 1.0, v11
	v_mul_f32_e32 v10, v10, v12
	v_rcp_f32_e32 v11, v11
	v_mul_f32_e32 v13, v89, v42
	v_mul_f32_e32 v14, 0xbfb8aa3b, v107
	v_fmac_f32_e32 v13, v0, v41
	v_exp_f32_e32 v14, v14
	v_fmac_f32_e32 v13, v90, v43
	v_and_b32_e32 v15, 0xffff0000, v131
	v_add_f32_e32 v13, v91, v13
	v_add_f32_e32 v14, 1.0, v14
	v_mul_f32_e32 v13, v13, v15
	v_rcp_f32_e32 v14, v14
	v_mul_f32_e32 v11, v11, v106
	v_mul_f32_e32 v10, v11, v10
	v_mul_f32_e32 v14, v14, v107
	v_mul_f32_e32 v13, v14, v13
	v_cvt_pk_bf16_f32 v106, v10, v13
	global_store_short v9, v106, s[66:67]
	s_add_u32 s66, s66, 0x3a00
	s_addc_u32 s67, s67, 0
	global_store_short_d16_hi v9, v106, s[66:67]
	s_add_u32 s66, s66, 0x3a00
	s_addc_u32 s67, s67, 0
	v_mul_f32_e32 v10, v89, v43
	v_mul_f32_e32 v11, 0xbfb8aa3b, v108
	v_fmac_f32_e32 v10, v0, v42
	v_exp_f32_e32 v11, v11
	v_fmac_f32_e32 v10, v90, v44
	v_lshlrev_b32_e32 v12, 16, v132
	v_add_f32_e32 v10, v91, v10
	v_add_f32_e32 v11, 1.0, v11
	v_mul_f32_e32 v10, v10, v12
	v_rcp_f32_e32 v11, v11
	v_mul_f32_e32 v13, v89, v44
	v_mul_f32_e32 v14, 0xbfb8aa3b, v109
	v_fmac_f32_e32 v13, v0, v43
	v_exp_f32_e32 v14, v14
	v_fmac_f32_e32 v13, v90, v45
	v_and_b32_e32 v15, 0xffff0000, v132
	v_add_f32_e32 v13, v91, v13
	v_add_f32_e32 v14, 1.0, v14
	v_mul_f32_e32 v13, v13, v15
	v_rcp_f32_e32 v14, v14
	v_mul_f32_e32 v11, v11, v108
	v_mul_f32_e32 v10, v11, v10
	v_mul_f32_e32 v14, v14, v109
	v_mul_f32_e32 v13, v14, v13
	v_cvt_pk_bf16_f32 v108, v10, v13
	global_store_short v9, v108, s[66:67]
	s_add_u32 s66, s66, 0x3a00
	s_addc_u32 s67, s67, 0
	global_store_short_d16_hi v9, v108, s[66:67]
	s_add_u32 s66, s66, 0x3a00
	s_addc_u32 s67, s67, 0
	v_mul_f32_e32 v10, v89, v45
	v_mul_f32_e32 v11, 0xbfb8aa3b, v110
	v_fmac_f32_e32 v10, v0, v44
	v_exp_f32_e32 v11, v11
	v_fmac_f32_e32 v10, v90, v46
	v_lshlrev_b32_e32 v12, 16, v133
	v_add_f32_e32 v10, v91, v10
	v_add_f32_e32 v11, 1.0, v11
	v_mul_f32_e32 v10, v10, v12
	v_rcp_f32_e32 v11, v11
	v_mul_f32_e32 v13, v89, v46
	v_mul_f32_e32 v14, 0xbfb8aa3b, v111
	v_fmac_f32_e32 v13, v0, v45
	v_exp_f32_e32 v14, v14
	v_fmac_f32_e32 v13, v90, v47
	v_and_b32_e32 v15, 0xffff0000, v133
	v_add_f32_e32 v13, v91, v13
	v_add_f32_e32 v14, 1.0, v14
	v_mul_f32_e32 v13, v13, v15
	v_rcp_f32_e32 v14, v14
	v_mul_f32_e32 v11, v11, v110
	v_mul_f32_e32 v10, v11, v10
	v_mul_f32_e32 v14, v14, v111
	v_mul_f32_e32 v13, v14, v13
	v_cvt_pk_bf16_f32 v110, v10, v13
	global_store_short v9, v110, s[66:67]
	s_add_u32 s66, s66, 0x3a00
	s_addc_u32 s67, s67, 0
	global_store_short_d16_hi v9, v110, s[66:67]
	s_add_u32 s66, s66, 0x3a00
	s_addc_u32 s67, s67, 0
	v_mul_f32_e32 v10, v89, v47
	v_mul_f32_e32 v11, 0xbfb8aa3b, v112
	v_fmac_f32_e32 v10, v0, v46
	v_exp_f32_e32 v11, v11
	v_fmac_f32_e32 v10, v90, v48
	v_lshlrev_b32_e32 v12, 16, v134
	v_add_f32_e32 v10, v91, v10
	v_add_f32_e32 v11, 1.0, v11
	v_mul_f32_e32 v10, v10, v12
; __device__ __forceinline__ float bf2f(bf16_t h) { return __uint_as_float(((unsigned)h) << 16); }
; __device__ __forceinline__ float siluf_(float x) { return x * __builtin_amdgcn_rcpf(1.f + __expf(-x)); }
; __device__ __forceinline__ void phase_hyena_post(const Params& p, int l, const int tidx) {
;     ...
;   for (int task = blockIdx.x; task < T / 32; task += gridDim.x) {
;     const int row0 = task * 32;
;     const int t0 = row0 % SEQ;
;     bf16_t* pv = P + (size_t)row0 * NP + OFF_BU + 512 + c;
;     bf16_t* pz = P + (size_t)row0 * NP + OFF_BZ + c;
;     const u32x4* src = (const u32x4*)(YT + (size_t)c * T + row0);
;     u32x4 yv[4];
; #pragma unroll
;     for (int q = 0; q < 4; q++) yv[q] = src[q];
;     float xm = (t0 > 0) ? bf2f(pv[-(ptrdiff_t)NP]) : 0.f, xc = bf2f(pv[0]);
;     bf16_t zbr[32], xnr[32];
; #pragma unroll
;     for (int i = 0; i < 32; i++) {
;       zbr[i] = pz[(size_t)i * NP];
;       xnr[i] = (t0 + i < SEQ - 1) ? pv[(size_t)(i + 1) * NP] : (bf16_t)0;
;     }
; #pragma unroll
;     for (int i = 0; i < 32; i++) {
;       float xn = bf2f(xnr[i]);
;       float x0 = w0 * xm + w1 * xc + w2 * xn + bx;
;       unsigned wd = yv[i >> 3][(i >> 1) & 3];
;       float y = bf2f((bf16_t)((i & 1) ? (wd >> 16) : (wd & 0xffff)));
;       float zb = bf2f(zbr[i]);
;       pz[(size_t)i * NP] = f2bf(x0 * y * siluf_(zb));
;       xm = xc; xc = xn;
;     }
;   }
	v_rcp_f32_e32 v11, v11
	v_mul_f32_e32 v13, v89, v48
	v_mul_f32_e32 v14, 0xbfb8aa3b, v113
	v_fmac_f32_e32 v13, v0, v47
	v_exp_f32_e32 v14, v14
	v_fmac_f32_e32 v13, v90, v49
	v_and_b32_e32 v15, 0xffff0000, v134
	v_add_f32_e32 v13, v91, v13
	v_add_f32_e32 v14, 1.0, v14
	v_mul_f32_e32 v13, v13, v15
	v_rcp_f32_e32 v14, v14
	v_mul_f32_e32 v11, v11, v112
	v_mul_f32_e32 v10, v11, v10
	v_mul_f32_e32 v14, v14, v113
	v_mul_f32_e32 v13, v14, v13
	v_cvt_pk_bf16_f32 v112, v10, v13
	global_store_short v9, v112, s[66:67]
	s_add_u32 s66, s66, 0x3a00
	s_addc_u32 s67, s67, 0
	global_store_short_d16_hi v9, v112, s[66:67]
	s_add_u32 s66, s66, 0x3a00
	s_addc_u32 s67, s67, 0
	v_mul_f32_e32 v10, v89, v49
	v_mul_f32_e32 v11, 0xbfb8aa3b, v114
	v_fmac_f32_e32 v10, v0, v48
	v_exp_f32_e32 v11, v11
	v_fmac_f32_e32 v10, v90, v50
	v_lshlrev_b32_e32 v12, 16, v135
	v_add_f32_e32 v10, v91, v10
	v_add_f32_e32 v11, 1.0, v11
	v_mul_f32_e32 v10, v10, v12
	v_rcp_f32_e32 v11, v11
	v_mul_f32_e32 v13, v89, v50
	v_mul_f32_e32 v14, 0xbfb8aa3b, v115
	v_fmac_f32_e32 v13, v0, v49
	v_exp_f32_e32 v14, v14
	v_fmac_f32_e32 v13, v90, v51
	v_and_b32_e32 v15, 0xffff0000, v135
	v_add_f32_e32 v13, v91, v13
	v_add_f32_e32 v14, 1.0, v14
	v_mul_f32_e32 v13, v13, v15
	v_rcp_f32_e32 v14, v14
	v_mul_f32_e32 v11, v11, v114
	v_mul_f32_e32 v10, v11, v10
	v_mul_f32_e32 v14, v14, v115
	v_mul_f32_e32 v13, v14, v13
	v_cvt_pk_bf16_f32 v114, v10, v13
	global_store_short v9, v114, s[66:67]
	s_add_u32 s66, s66, 0x3a00
	s_addc_u32 s67, s67, 0
	global_store_short_d16_hi v9, v114, s[66:67]
	s_add_u32 s66, s66, 0x3a00
	s_addc_u32 s67, s67, 0
	v_mul_f32_e32 v10, v89, v51
	v_mul_f32_e32 v11, 0xbfb8aa3b, v116
	v_fmac_f32_e32 v10, v0, v50
	v_exp_f32_e32 v11, v11
	v_fmac_f32_e32 v10, v90, v52
	v_lshlrev_b32_e32 v12, 16, v136
	v_add_f32_e32 v10, v91, v10
	v_add_f32_e32 v11, 1.0, v11
	v_mul_f32_e32 v10, v10, v12
	v_rcp_f32_e32 v11, v11
	v_mul_f32_e32 v13, v89, v52
	v_mul_f32_e32 v14, 0xbfb8aa3b, v117
	v_fmac_f32_e32 v13, v0, v51
	v_exp_f32_e32 v14, v14
	v_fmac_f32_e32 v13, v90, v53
	v_and_b32_e32 v15, 0xffff0000, v136
	v_add_f32_e32 v13, v91, v13
	v_add_f32_e32 v14, 1.0, v14
	v_mul_f32_e32 v13, v13, v15
	v_rcp_f32_e32 v14, v14
	v_mul_f32_e32 v11, v11, v116
	v_mul_f32_e32 v10, v11, v10
	v_mul_f32_e32 v14, v14, v117
	v_mul_f32_e32 v13, v14, v13
	v_cvt_pk_bf16_f32 v116, v10, v13
	global_store_short v9, v116, s[66:67]
	s_add_u32 s66, s66, 0x3a00
	s_addc_u32 s67, s67, 0
	global_store_short_d16_hi v9, v116, s[66:67]
	s_add_u32 s66, s66, 0x3a00
	s_addc_u32 s67, s67, 0
	v_mul_f32_e32 v10, v89, v53
	v_mul_f32_e32 v11, 0xbfb8aa3b, v118
	v_fmac_f32_e32 v10, v0, v52
	v_exp_f32_e32 v11, v11
	v_fmac_f32_e32 v10, v90, v54
	v_lshlrev_b32_e32 v12, 16, v137
	v_add_f32_e32 v10, v91, v10
	v_add_f32_e32 v11, 1.0, v11
	v_mul_f32_e32 v10, v10, v12
	v_rcp_f32_e32 v11, v11
	v_mul_f32_e32 v13, v89, v54
	v_mul_f32_e32 v14, 0xbfb8aa3b, v119
	v_fmac_f32_e32 v13, v0, v53
	v_exp_f32_e32 v14, v14
	v_fmac_f32_e32 v13, v90, v55
	v_and_b32_e32 v15, 0xffff0000, v137
	v_add_f32_e32 v13, v91, v13
	v_add_f32_e32 v14, 1.0, v14
	v_mul_f32_e32 v13, v13, v15
	v_rcp_f32_e32 v14, v14
	v_mul_f32_e32 v11, v11, v118
	v_mul_f32_e32 v10, v11, v10
	v_mul_f32_e32 v14, v14, v119
	v_mul_f32_e32 v13, v14, v13
	v_cvt_pk_bf16_f32 v118, v10, v13
	global_store_short v9, v118, s[66:67]
	s_add_u32 s66, s66, 0x3a00
	s_addc_u32 s67, s67, 0
	global_store_short_d16_hi v9, v118, s[66:67]
	s_add_u32 s66, s66, 0x3a00
	s_addc_u32 s67, s67, 0
	v_mul_f32_e32 v10, v89, v55
	v_mul_f32_e32 v11, 0xbfb8aa3b, v120
	v_fmac_f32_e32 v10, v0, v54
	v_exp_f32_e32 v11, v11
	v_fmac_f32_e32 v10, v90, v56
	v_lshlrev_b32_e32 v12, 16, v138
	v_add_f32_e32 v10, v91, v10
	v_add_f32_e32 v11, 1.0, v11
	v_mul_f32_e32 v10, v10, v12
	v_rcp_f32_e32 v11, v11
	v_mul_f32_e32 v13, v89, v56
	v_mul_f32_e32 v14, 0xbfb8aa3b, v121
	v_fmac_f32_e32 v13, v0, v55
	v_exp_f32_e32 v14, v14
	v_fmac_f32_e32 v13, v90, v57
	v_and_b32_e32 v15, 0xffff0000, v138
	v_add_f32_e32 v13, v91, v13
	v_add_f32_e32 v14, 1.0, v14
	v_mul_f32_e32 v13, v13, v15
	v_rcp_f32_e32 v14, v14
	v_mul_f32_e32 v11, v11, v120
	v_mul_f32_e32 v10, v11, v10
	v_mul_f32_e32 v14, v14, v121
	v_mul_f32_e32 v13, v14, v13
	v_cvt_pk_bf16_f32 v120, v10, v13
	global_store_short v9, v120, s[66:67]
	s_add_u32 s66, s66, 0x3a00
	s_addc_u32 s67, s67, 0
	global_store_short_d16_hi v9, v120, s[66:67]
	s_add_u32 s66, s66, 0x3a00
	s_addc_u32 s67, s67, 0
	v_mul_f32_e32 v10, v89, v57
	v_mul_f32_e32 v11, 0xbfb8aa3b, v122
	v_fmac_f32_e32 v10, v0, v56
	v_exp_f32_e32 v11, v11
	v_fmac_f32_e32 v10, v90, v58
	v_lshlrev_b32_e32 v12, 16, v139
	v_add_f32_e32 v10, v91, v10
	v_add_f32_e32 v11, 1.0, v11
	v_mul_f32_e32 v10, v10, v12
	v_rcp_f32_e32 v11, v11
	v_mul_f32_e32 v13, v89, v58
	v_mul_f32_e32 v14, 0xbfb8aa3b, v123
	v_fmac_f32_e32 v13, v0, v57
	v_exp_f32_e32 v14, v14
	v_fmac_f32_e32 v13, v90, v59
	v_and_b32_e32 v15, 0xffff0000, v139
	v_add_f32_e32 v13, v91, v13
	v_add_f32_e32 v14, 1.0, v14
	v_mul_f32_e32 v13, v13, v15
	v_rcp_f32_e32 v14, v14
	v_mul_f32_e32 v11, v11, v122
	v_mul_f32_e32 v10, v11, v10
	v_mul_f32_e32 v14, v14, v123
	v_mul_f32_e32 v13, v14, v13
	v_cvt_pk_bf16_f32 v122, v10, v13
	global_store_short v9, v122, s[66:67]
	s_add_u32 s66, s66, 0x3a00
	s_addc_u32 s67, s67, 0
	global_store_short_d16_hi v9, v122, s[66:67]
	s_add_u32 s66, s66, 0x3a00
	s_addc_u32 s67, s67, 0
	v_readlane_b32 s5, v251, 1
	s_add_i32 s0, s0, s5
	v_readlane_b32 s5, v253, 21
	s_add_i32 s12, s12, s5
	s_cmpk_lt_i32 s0, 0x400
	s_cbranch_scc1 .Lhp_loop

; __device__ __forceinline__ float bf2f(bf16_t h) { return __uint_as_float(((unsigned)h) << 16); }
; __device__ __forceinline__ void phase_hyena_z(const Params& p, int l, const int tidx) {
;     ...
;   for (int task = blockIdx.x; task < T / 32; task += gridDim.x) {
;     const int row0 = task * 32;
;     const int t0 = row0 % SEQ;
;     const bf16_t* pv = P + (size_t)row0 * NP + OFF_BU + c;
;     float vm = (t0 > 0) ? bf2f(pv[-(ptrdiff_t)NP]) : 0.f, vc = bf2f(pv[0]);
;     float xm = (t0 > 0) ? bf2f(pv[-(ptrdiff_t)NP + 1024]) : 0.f, xc = bf2f(pv[1024]);
;     unsigned pk[16];
; #pragma unroll
;     for (int i = 0; i < 32; i++) {
;       bool has = (t0 + i < SEQ - 1);
;       float vn = has ? bf2f(pv[(size_t)(i + 1) * NP]) : 0.f;
;       float xn = has ? bf2f(pv[(size_t)(i + 1) * NP + 1024]) : 0.f;
.LBB0_252:
	v_lshlrev_b32_e32 v0, 1, v150
	s_waitcnt vmcnt(0)
.Lhz_loop:
	v_mov_b32_e32 v26, 0
	v_mov_b32_e32 v60, 0
	v_mov_b32_e32 v27, 0
	v_mov_b32_e32 v61, 0
	v_mov_b32_e32 v28, 0
	v_mov_b32_e32 v62, 0
	v_mov_b32_e32 v29, 0
	v_mov_b32_e32 v63, 0
	v_mov_b32_e32 v30, 0
	v_mov_b32_e32 v64, 0
	v_mov_b32_e32 v31, 0
	v_mov_b32_e32 v65, 0
	v_mov_b32_e32 v32, 0
	v_mov_b32_e32 v66, 0
	v_mov_b32_e32 v33, 0
	v_mov_b32_e32 v67, 0
	v_mov_b32_e32 v34, 0
	v_mov_b32_e32 v68, 0
	v_mov_b32_e32 v35, 0
	v_mov_b32_e32 v69, 0
	v_mov_b32_e32 v36, 0
	v_mov_b32_e32 v70, 0
	v_mov_b32_e32 v37, 0
	v_mov_b32_e32 v71, 0
	v_mov_b32_e32 v38, 0
	v_mov_b32_e32 v72, 0
	v_mov_b32_e32 v39, 0
	v_mov_b32_e32 v73, 0
	v_mov_b32_e32 v40, 0
	v_mov_b32_e32 v74, 0
	v_mov_b32_e32 v41, 0
	v_mov_b32_e32 v75, 0
	v_mov_b32_e32 v42, 0
	v_mov_b32_e32 v76, 0
	v_mov_b32_e32 v43, 0
	v_mov_b32_e32 v77, 0
	v_mov_b32_e32 v44, 0
	v_mov_b32_e32 v78, 0
	v_mov_b32_e32 v45, 0
	v_mov_b32_e32 v79, 0
	v_mov_b32_e32 v46, 0
	v_mov_b32_e32 v80, 0
	v_mov_b32_e32 v47, 0
	v_mov_b32_e32 v81, 0
	v_mov_b32_e32 v48, 0
	v_mov_b32_e32 v82, 0
	v_mov_b32_e32 v49, 0
	v_mov_b32_e32 v83, 0
	v_mov_b32_e32 v50, 0
	v_mov_b32_e32 v84, 0
	v_mov_b32_e32 v51, 0
	v_mov_b32_e32 v85, 0
	v_mov_b32_e32 v52, 0
	v_mov_b32_e32 v86, 0
	v_mov_b32_e32 v53, 0
	v_mov_b32_e32 v87, 0
	v_mov_b32_e32 v54, 0
	v_mov_b32_e32 v88, 0
	v_mov_b32_e32 v55, 0
	v_mov_b32_e32 v89, 0
	v_mov_b32_e32 v56, 0
	v_mov_b32_e32 v8, 0
	v_mov_b32_e32 v57, 0
	v_mov_b32_e32 v9, 0
	v_mov_b32_e32 v58, 0
	v_mov_b32_e32 v10, 0
	v_mov_b32_e32 v59, 0
	v_mov_b32_e32 v11, 0
	s_and_b32 s14, s10, 0xfff
	s_mul_i32 s12, s10, 0x3a00
	s_mul_hi_u32 s13, s10, 0x3a00
	s_add_u32 s12, s12, s94
	s_addc_u32 s13, s13, s95
	s_add_u32 s12, s12, 0x800
	s_addc_u32 s13, s13, 0
	s_cmp_eq_u32 s14, 0
	s_cbranch_scc1 .Lhz_rows
	s_sub_u32 s66, s12, 0x3a00
	s_subb_u32 s67, s13, 0
	global_load_short_d16_hi v26, v0, s[66:67]
	global_load_short_d16_hi v60, v0, s[66:67] offset:2048
.Lhz_rows:
	global_load_short_d16_hi v27, v0, s[12:13]
	global_load_short_d16_hi v61, v0, s[12:13] offset:2048
	s_add_u32 s12, s12, 0x3a00
	s_addc_u32 s13, s13, 0
	global_load_short_d16_hi v28, v0, s[12:13]
	global_load_short_d16_hi v62, v0, s[12:13] offset:2048
	s_add_u32 s12, s12, 0x3a00
	s_addc_u32 s13, s13, 0
	global_load_short_d16_hi v29, v0, s[12:13]
	global_load_short_d16_hi v63, v0, s[12:13] offset:2048
	s_add_u32 s12, s12, 0x3a00
	s_addc_u32 s13, s13, 0
	global_load_short_d16_hi v30, v0, s[12:13]
	global_load_short_d16_hi v64, v0, s[12:13] offset:2048
	s_add_u32 s12, s12, 0x3a00
	s_addc_u32 s13, s13, 0
	global_load_short_d16_hi v31, v0, s[12:13]
	global_load_short_d16_hi v65, v0, s[12:13] offset:2048
	s_add_u32 s12, s12, 0x3a00
	s_addc_u32 s13, s13, 0
	global_load_short_d16_hi v32, v0, s[12:13]
	global_load_short_d16_hi v66, v0, s[12:13] offset:2048
	s_add_u32 s12, s12, 0x3a00
	s_addc_u32 s13, s13, 0
	global_load_short_d16_hi v33, v0, s[12:13]
	global_load_short_d16_hi v67, v0, s[12:13] offset:2048
	s_add_u32 s12, s12, 0x3a00
	s_addc_u32 s13, s13, 0
	global_load_short_d16_hi v34, v0, s[12:13]
	global_load_short_d16_hi v68, v0, s[12:13] offset:2048
	s_add_u32 s12, s12, 0x3a00
	s_addc_u32 s13, s13, 0
	global_load_short_d16_hi v35, v0, s[12:13]
	global_load_short_d16_hi v69, v0, s[12:13] offset:2048
	s_add_u32 s12, s12, 0x3a00
	s_addc_u32 s13, s13, 0
	global_load_short_d16_hi v36, v0, s[12:13]
	global_load_short_d16_hi v70, v0, s[12:13] offset:2048
	s_add_u32 s12, s12, 0x3a00
	s_addc_u32 s13, s13, 0
	global_load_short_d16_hi v37, v0, s[12:13]
	global_load_short_d16_hi v71, v0, s[12:13] offset:2048
	s_add_u32 s12, s12, 0x3a00
	s_addc_u32 s13, s13, 0
	global_load_short_d16_hi v38, v0, s[12:13]
	global_load_short_d16_hi v72, v0, s[12:13] offset:2048
	s_add_u32 s12, s12, 0x3a00
	s_addc_u32 s13, s13, 0
	global_load_short_d16_hi v39, v0, s[12:13]
	global_load_short_d16_hi v73, v0, s[12:13] offset:2048
	s_add_u32 s12, s12, 0x3a00
	s_addc_u32 s13, s13, 0
	global_load_short_d16_hi v40, v0, s[12:13]
	global_load_short_d16_hi v74, v0, s[12:13] offset:2048
	s_add_u32 s12, s12, 0x3a00
	s_addc_u32 s13, s13, 0
	global_load_short_d16_hi v41, v0, s[12:13]
	global_load_short_d16_hi v75, v0, s[12:13] offset:2048
	s_add_u32 s12, s12, 0x3a00
	s_addc_u32 s13, s13, 0
	global_load_short_d16_hi v42, v0, s[12:13]
	global_load_short_d16_hi v76, v0, s[12:13] offset:2048
	s_add_u32 s12, s12, 0x3a00
	s_addc_u32 s13, s13, 0
	global_load_short_d16_hi v43, v0, s[12:13]
	global_load_short_d16_hi v77, v0, s[12:13] offset:2048
	s_add_u32 s12, s12, 0x3a00
	s_addc_u32 s13, s13, 0
	global_load_short_d16_hi v44, v0, s[12:13]
	global_load_short_d16_hi v78, v0, s[12:13] offset:2048
	s_add_u32 s12, s12, 0x3a00
	s_addc_u32 s13, s13, 0
	global_load_short_d16_hi v45, v0, s[12:13]
	global_load_short_d16_hi v79, v0, s[12:13] offset:2048
	s_add_u32 s12, s12, 0x3a00
	s_addc_u32 s13, s13, 0
	global_load_short_d16_hi v46, v0, s[12:13]
	global_load_short_d16_hi v80, v0, s[12:13] offset:2048
	s_add_u32 s12, s12, 0x3a00
	s_addc_u32 s13, s13, 0
	global_load_short_d16_hi v47, v0, s[12:13]
	global_load_short_d16_hi v81, v0, s[12:13] offset:2048
	s_add_u32 s12, s12, 0x3a00
	s_addc_u32 s13, s13, 0
	global_load_short_d16_hi v48, v0, s[12:13]
	global_load_short_d16_hi v82, v0, s[12:13] offset:2048
	s_add_u32 s12, s12, 0x3a00
	s_addc_u32 s13, s13, 0
	global_load_short_d16_hi v49, v0, s[12:13]
	global_load_short_d16_hi v83, v0, s[12:13] offset:2048
	s_add_u32 s12, s12, 0x3a00
	s_addc_u32 s13, s13, 0
	global_load_short_d16_hi v50, v0, s[12:13]
	global_load_short_d16_hi v84, v0, s[12:13] offset:2048
	s_add_u32 s12, s12, 0x3a00
	s_addc_u32 s13, s13, 0
	global_load_short_d16_hi v51, v0, s[12:13]
	global_load_short_d16_hi v85, v0, s[12:13] offset:2048
	s_add_u32 s12, s12, 0x3a00
	s_addc_u32 s13, s13, 0
	global_load_short_d16_hi v52, v0, s[12:13]
	global_load_short_d16_hi v86, v0, s[12:13] offset:2048
	s_add_u32 s12, s12, 0x3a00
	s_addc_u32 s13, s13, 0
	global_load_short_d16_hi v53, v0, s[12:13]
	global_load_short_d16_hi v87, v0, s[12:13] offset:2048
	s_add_u32 s12, s12, 0x3a00
	s_addc_u32 s13, s13, 0
	global_load_short_d16_hi v54, v0, s[12:13]
	global_load_short_d16_hi v88, v0, s[12:13] offset:2048
	s_add_u32 s12, s12, 0x3a00
	s_addc_u32 s13, s13, 0
	global_load_short_d16_hi v55, v0, s[12:13]
	global_load_short_d16_hi v89, v0, s[12:13] offset:2048
	s_add_u32 s12, s12, 0x3a00
	s_addc_u32 s13, s13, 0
	global_load_short_d16_hi v56, v0, s[12:13]
	global_load_short_d16_hi v8, v0, s[12:13] offset:2048
	s_add_u32 s12, s12, 0x3a00
	s_addc_u32 s13, s13, 0
	global_load_short_d16_hi v57, v0, s[12:13]
	global_load_short_d16_hi v9, v0, s[12:13] offset:2048
	s_add_u32 s12, s12, 0x3a00
	s_addc_u32 s13, s13, 0
	global_load_short_d16_hi v58, v0, s[12:13]
	global_load_short_d16_hi v10, v0, s[12:13] offset:2048
	s_add_u32 s12, s12, 0x3a00
	s_addc_u32 s13, s13, 0
	s_cmpk_eq_i32 s14, 0xfe0
	s_cbranch_scc1 .Lhz_comp
	global_load_short_d16_hi v59, v0, s[12:13]
	global_load_short_d16_hi v11, v0, s[12:13] offset:2048
; __device__ __forceinline__ float bf2f(bf16_t h) { return __uint_as_float(((unsigned)h) << 16); }
; __device__ __forceinline__ void phase_hyena_z(const Params& p, int l, const int tidx) {
;     ...
; #pragma unroll
;     for (int i = 0; i < 32; i++) {
;       bool has = (t0 + i < SEQ - 1);
;       float vn = has ? bf2f(pv[(size_t)(i + 1) * NP]) : 0.f;
;       float xn = has ? bf2f(pv[(size_t)(i + 1) * NP + 1024]) : 0.f;
;       float v = wv0 * vm + wv1 * vc + wv2 * vn + bv;
;       float x1 = wx0 * xm + wx1 * xc + wx2 * xn + bx;
;       unsigned zb = f2bf(v * x1);
;       if (i & 1) pk[i >> 1] |= zb << 16; else pk[i >> 1] = zb;
;       vm = vc; vc = vn; xm = xc; xc = xn;
;     }
.Lhz_comp:
	s_waitcnt vmcnt(0)
	v_mul_f32_e32 v12, v16, v27
	v_mul_f32_e32 v13, v17, v61
	v_fmac_f32_e32 v12, v2, v26
	v_fmac_f32_e32 v13, v3, v60
	v_fmac_f32_e32 v12, v18, v28
	v_fmac_f32_e32 v13, v19, v62
	v_add_f32_e32 v12, v20, v12
	v_add_f32_e32 v13, v21, v13
	v_mul_f32_e32 v12, v12, v13
	v_mul_f32_e32 v14, v16, v28
	v_mul_f32_e32 v15, v17, v62
	v_fmac_f32_e32 v14, v2, v27
	v_fmac_f32_e32 v15, v3, v61
	v_fmac_f32_e32 v14, v18, v29
	v_fmac_f32_e32 v15, v19, v63
	v_add_f32_e32 v14, v20, v14
	v_add_f32_e32 v15, v21, v15
	v_mul_f32_e32 v14, v14, v15
	v_cvt_pk_bf16_f32 v60, v12, v14
	v_mul_f32_e32 v12, v16, v29
	v_mul_f32_e32 v13, v17, v63
	v_fmac_f32_e32 v12, v2, v28
	v_fmac_f32_e32 v13, v3, v62
	v_fmac_f32_e32 v12, v18, v30
	v_fmac_f32_e32 v13, v19, v64
	v_add_f32_e32 v12, v20, v12
	v_add_f32_e32 v13, v21, v13
	v_mul_f32_e32 v12, v12, v13
	v_mul_f32_e32 v14, v16, v30
	v_mul_f32_e32 v15, v17, v64
	v_fmac_f32_e32 v14, v2, v29
	v_fmac_f32_e32 v15, v3, v63
	v_fmac_f32_e32 v14, v18, v31
	v_fmac_f32_e32 v15, v19, v65
	v_add_f32_e32 v14, v20, v14
	v_add_f32_e32 v15, v21, v15
	v_mul_f32_e32 v14, v14, v15
	v_cvt_pk_bf16_f32 v61, v12, v14
	v_mul_f32_e32 v12, v16, v31
	v_mul_f32_e32 v13, v17, v65
	v_fmac_f32_e32 v12, v2, v30
	v_fmac_f32_e32 v13, v3, v64
	v_fmac_f32_e32 v12, v18, v32
	v_fmac_f32_e32 v13, v19, v66
	v_add_f32_e32 v12, v20, v12
	v_add_f32_e32 v13, v21, v13
	v_mul_f32_e32 v12, v12, v13
	v_mul_f32_e32 v14, v16, v32
	v_mul_f32_e32 v15, v17, v66
	v_fmac_f32_e32 v14, v2, v31
	v_fmac_f32_e32 v15, v3, v65
	v_fmac_f32_e32 v14, v18, v33
	v_fmac_f32_e32 v15, v19, v67
	v_add_f32_e32 v14, v20, v14
	v_add_f32_e32 v15, v21, v15
	v_mul_f32_e32 v14, v14, v15
	v_cvt_pk_bf16_f32 v62, v12, v14
	v_mul_f32_e32 v12, v16, v33
	v_mul_f32_e32 v13, v17, v67
	v_fmac_f32_e32 v12, v2, v32
	v_fmac_f32_e32 v13, v3, v66
	v_fmac_f32_e32 v12, v18, v34
	v_fmac_f32_e32 v13, v19, v68
	v_add_f32_e32 v12, v20, v12
	v_add_f32_e32 v13, v21, v13
	v_mul_f32_e32 v12, v12, v13
	v_mul_f32_e32 v14, v16, v34
	v_mul_f32_e32 v15, v17, v68
	v_fmac_f32_e32 v14, v2, v33
	v_fmac_f32_e32 v15, v3, v67
	v_fmac_f32_e32 v14, v18, v35
	v_fmac_f32_e32 v15, v19, v69
	v_add_f32_e32 v14, v20, v14
	v_add_f32_e32 v15, v21, v15
	v_mul_f32_e32 v14, v14, v15
	v_cvt_pk_bf16_f32 v63, v12, v14
	v_mul_f32_e32 v12, v16, v35
	v_mul_f32_e32 v13, v17, v69
	v_fmac_f32_e32 v12, v2, v34
	v_fmac_f32_e32 v13, v3, v68
	v_fmac_f32_e32 v12, v18, v36
	v_fmac_f32_e32 v13, v19, v70
	v_add_f32_e32 v12, v20, v12
	v_add_f32_e32 v13, v21, v13
	v_mul_f32_e32 v12, v12, v13
	v_mul_f32_e32 v14, v16, v36
	v_mul_f32_e32 v15, v17, v70
	v_fmac_f32_e32 v14, v2, v35
	v_fmac_f32_e32 v15, v3, v69
	v_fmac_f32_e32 v14, v18, v37
	v_fmac_f32_e32 v15, v19, v71
	v_add_f32_e32 v14, v20, v14
	v_add_f32_e32 v15, v21, v15
	v_mul_f32_e32 v14, v14, v15
	v_cvt_pk_bf16_f32 v64, v12, v14
	v_mul_f32_e32 v12, v16, v37
	v_mul_f32_e32 v13, v17, v71
	v_fmac_f32_e32 v12, v2, v36
	v_fmac_f32_e32 v13, v3, v70
	v_fmac_f32_e32 v12, v18, v38
	v_fmac_f32_e32 v13, v19, v72
	v_add_f32_e32 v12, v20, v12
	v_add_f32_e32 v13, v21, v13
	v_mul_f32_e32 v12, v12, v13
	v_mul_f32_e32 v14, v16, v38
	v_mul_f32_e32 v15, v17, v72
	v_fmac_f32_e32 v14, v2, v37
	v_fmac_f32_e32 v15, v3, v71
	v_fmac_f32_e32 v14, v18, v39
	v_fmac_f32_e32 v15, v19, v73
	v_add_f32_e32 v14, v20, v14
	v_add_f32_e32 v15, v21, v15
	v_mul_f32_e32 v14, v14, v15
	v_cvt_pk_bf16_f32 v65, v12, v14
	v_mul_f32_e32 v12, v16, v39
	v_mul_f32_e32 v13, v17, v73
	v_fmac_f32_e32 v12, v2, v38
	v_fmac_f32_e32 v13, v3, v72
	v_fmac_f32_e32 v12, v18, v40
	v_fmac_f32_e32 v13, v19, v74
	v_add_f32_e32 v12, v20, v12
	v_add_f32_e32 v13, v21, v13
	v_mul_f32_e32 v12, v12, v13
	v_mul_f32_e32 v14, v16, v40
	v_mul_f32_e32 v15, v17, v74
	v_fmac_f32_e32 v14, v2, v39
	v_fmac_f32_e32 v15, v3, v73
	v_fmac_f32_e32 v14, v18, v41
	v_fmac_f32_e32 v15, v19, v75
	v_add_f32_e32 v14, v20, v14
	v_add_f32_e32 v15, v21, v15
	v_mul_f32_e32 v14, v14, v15
	v_cvt_pk_bf16_f32 v66, v12, v14
	v_mul_f32_e32 v12, v16, v41
	v_mul_f32_e32 v13, v17, v75
	v_fmac_f32_e32 v12, v2, v40
	v_fmac_f32_e32 v13, v3, v74
	v_fmac_f32_e32 v12, v18, v42
	v_fmac_f32_e32 v13, v19, v76
	v_add_f32_e32 v12, v20, v12
	v_add_f32_e32 v13, v21, v13
	v_mul_f32_e32 v12, v12, v13
	v_mul_f32_e32 v14, v16, v42
	v_mul_f32_e32 v15, v17, v76
	v_fmac_f32_e32 v14, v2, v41
	v_fmac_f32_e32 v15, v3, v75
	v_fmac_f32_e32 v14, v18, v43
	v_fmac_f32_e32 v15, v19, v77
	v_add_f32_e32 v14, v20, v14
	v_add_f32_e32 v15, v21, v15
	v_mul_f32_e32 v14, v14, v15
	v_cvt_pk_bf16_f32 v67, v12, v14
	v_mul_f32_e32 v12, v16, v43
	v_mul_f32_e32 v13, v17, v77
	v_fmac_f32_e32 v12, v2, v42
	v_fmac_f32_e32 v13, v3, v76
	v_fmac_f32_e32 v12, v18, v44
	v_fmac_f32_e32 v13, v19, v78
	v_add_f32_e32 v12, v20, v12
; __device__ __forceinline__ void phase_hyena_z(const Params& p, int l, const int tidx) {
;     ...
;       float v = wv0 * vm + wv1 * vc + wv2 * vn + bv;
;       float x1 = wx0 * xm + wx1 * xc + wx2 * xn + bx;
;       unsigned zb = f2bf(v * x1);
;       if (i & 1) pk[i >> 1] |= zb << 16; else pk[i >> 1] = zb;
;       vm = vc; vc = vn; xm = xc; xc = xn;
;     }
;     u32x4* dst = (u32x4*)(ZT + (size_t)c * T + row0);
; #pragma unroll
;     for (int q = 0; q < 4; q++) dst[q] = u32x4{pk[q * 4], pk[q * 4 + 1], pk[q * 4 + 2], pk[q * 4 + 3]};
	v_add_f32_e32 v13, v21, v13
	v_mul_f32_e32 v12, v12, v13
	v_mul_f32_e32 v14, v16, v44
	v_mul_f32_e32 v15, v17, v78
	v_fmac_f32_e32 v14, v2, v43
	v_fmac_f32_e32 v15, v3, v77
	v_fmac_f32_e32 v14, v18, v45
	v_fmac_f32_e32 v15, v19, v79
	v_add_f32_e32 v14, v20, v14
	v_add_f32_e32 v15, v21, v15
	v_mul_f32_e32 v14, v14, v15
	v_cvt_pk_bf16_f32 v68, v12, v14
	v_mul_f32_e32 v12, v16, v45
	v_mul_f32_e32 v13, v17, v79
	v_fmac_f32_e32 v12, v2, v44
	v_fmac_f32_e32 v13, v3, v78
	v_fmac_f32_e32 v12, v18, v46
	v_fmac_f32_e32 v13, v19, v80
	v_add_f32_e32 v12, v20, v12
	v_add_f32_e32 v13, v21, v13
	v_mul_f32_e32 v12, v12, v13
	v_mul_f32_e32 v14, v16, v46
	v_mul_f32_e32 v15, v17, v80
	v_fmac_f32_e32 v14, v2, v45
	v_fmac_f32_e32 v15, v3, v79
	v_fmac_f32_e32 v14, v18, v47
	v_fmac_f32_e32 v15, v19, v81
	v_add_f32_e32 v14, v20, v14
	v_add_f32_e32 v15, v21, v15
	v_mul_f32_e32 v14, v14, v15
	v_cvt_pk_bf16_f32 v69, v12, v14
	v_mul_f32_e32 v12, v16, v47
	v_mul_f32_e32 v13, v17, v81
	v_fmac_f32_e32 v12, v2, v46
	v_fmac_f32_e32 v13, v3, v80
	v_fmac_f32_e32 v12, v18, v48
	v_fmac_f32_e32 v13, v19, v82
	v_add_f32_e32 v12, v20, v12
	v_add_f32_e32 v13, v21, v13
	v_mul_f32_e32 v12, v12, v13
	v_mul_f32_e32 v14, v16, v48
	v_mul_f32_e32 v15, v17, v82
	v_fmac_f32_e32 v14, v2, v47
	v_fmac_f32_e32 v15, v3, v81
	v_fmac_f32_e32 v14, v18, v49
	v_fmac_f32_e32 v15, v19, v83
	v_add_f32_e32 v14, v20, v14
	v_add_f32_e32 v15, v21, v15
	v_mul_f32_e32 v14, v14, v15
	v_cvt_pk_bf16_f32 v70, v12, v14
	v_mul_f32_e32 v12, v16, v49
	v_mul_f32_e32 v13, v17, v83
	v_fmac_f32_e32 v12, v2, v48
	v_fmac_f32_e32 v13, v3, v82
	v_fmac_f32_e32 v12, v18, v50
	v_fmac_f32_e32 v13, v19, v84
	v_add_f32_e32 v12, v20, v12
	v_add_f32_e32 v13, v21, v13
	v_mul_f32_e32 v12, v12, v13
	v_mul_f32_e32 v14, v16, v50
	v_mul_f32_e32 v15, v17, v84
	v_fmac_f32_e32 v14, v2, v49
	v_fmac_f32_e32 v15, v3, v83
	v_fmac_f32_e32 v14, v18, v51
	v_fmac_f32_e32 v15, v19, v85
	v_add_f32_e32 v14, v20, v14
	v_add_f32_e32 v15, v21, v15
	v_mul_f32_e32 v14, v14, v15
	v_cvt_pk_bf16_f32 v71, v12, v14
	v_mul_f32_e32 v12, v16, v51
	v_mul_f32_e32 v13, v17, v85
	v_fmac_f32_e32 v12, v2, v50
	v_fmac_f32_e32 v13, v3, v84
	v_fmac_f32_e32 v12, v18, v52
	v_fmac_f32_e32 v13, v19, v86
	v_add_f32_e32 v12, v20, v12
	v_add_f32_e32 v13, v21, v13
	v_mul_f32_e32 v12, v12, v13
	v_mul_f32_e32 v14, v16, v52
	v_mul_f32_e32 v15, v17, v86
	v_fmac_f32_e32 v14, v2, v51
	v_fmac_f32_e32 v15, v3, v85
	v_fmac_f32_e32 v14, v18, v53
	v_fmac_f32_e32 v15, v19, v87
	v_add_f32_e32 v14, v20, v14
	v_add_f32_e32 v15, v21, v15
	v_mul_f32_e32 v14, v14, v15
	v_cvt_pk_bf16_f32 v72, v12, v14
	v_mul_f32_e32 v12, v16, v53
	v_mul_f32_e32 v13, v17, v87
	v_fmac_f32_e32 v12, v2, v52
	v_fmac_f32_e32 v13, v3, v86
	v_fmac_f32_e32 v12, v18, v54
	v_fmac_f32_e32 v13, v19, v88
	v_add_f32_e32 v12, v20, v12
	v_add_f32_e32 v13, v21, v13
	v_mul_f32_e32 v12, v12, v13
	v_mul_f32_e32 v14, v16, v54
	v_mul_f32_e32 v15, v17, v88
	v_fmac_f32_e32 v14, v2, v53
	v_fmac_f32_e32 v15, v3, v87
	v_fmac_f32_e32 v14, v18, v55
	v_fmac_f32_e32 v15, v19, v89
	v_add_f32_e32 v14, v20, v14
	v_add_f32_e32 v15, v21, v15
	v_mul_f32_e32 v14, v14, v15
	v_cvt_pk_bf16_f32 v73, v12, v14
	v_mul_f32_e32 v12, v16, v55
	v_mul_f32_e32 v13, v17, v89
	v_fmac_f32_e32 v12, v2, v54
	v_fmac_f32_e32 v13, v3, v88
	v_fmac_f32_e32 v12, v18, v56
	v_fmac_f32_e32 v13, v19, v8
	v_add_f32_e32 v12, v20, v12
	v_add_f32_e32 v13, v21, v13
	v_mul_f32_e32 v12, v12, v13
	v_mul_f32_e32 v14, v16, v56
	v_mul_f32_e32 v15, v17, v8
	v_fmac_f32_e32 v14, v2, v55
	v_fmac_f32_e32 v15, v3, v89
	v_fmac_f32_e32 v14, v18, v57
	v_fmac_f32_e32 v15, v19, v9
	v_add_f32_e32 v14, v20, v14
	v_add_f32_e32 v15, v21, v15
	v_mul_f32_e32 v14, v14, v15
	v_cvt_pk_bf16_f32 v74, v12, v14
	v_mul_f32_e32 v12, v16, v57
	v_mul_f32_e32 v13, v17, v9
	v_fmac_f32_e32 v12, v2, v56
	v_fmac_f32_e32 v13, v3, v8
	v_fmac_f32_e32 v12, v18, v58
	v_fmac_f32_e32 v13, v19, v10
	v_add_f32_e32 v12, v20, v12
	v_add_f32_e32 v13, v21, v13
	v_mul_f32_e32 v12, v12, v13
	v_mul_f32_e32 v14, v16, v58
	v_mul_f32_e32 v15, v17, v10
	v_fmac_f32_e32 v14, v2, v57
	v_fmac_f32_e32 v15, v3, v9
	v_fmac_f32_e32 v14, v18, v59
	v_fmac_f32_e32 v15, v19, v11
	v_add_f32_e32 v14, v20, v14
	v_add_f32_e32 v15, v21, v15
	v_mul_f32_e32 v14, v14, v15
	v_cvt_pk_bf16_f32 v75, v12, v14
	s_mov_b32 s11, 0
	v_lshl_add_u64 v[12:13], s[10:11], 1, v[22:23]
	global_store_dwordx4 v[12:13], v[60:63], off
	global_store_dwordx4 v[12:13], v[64:67], off offset:16
	global_store_dwordx4 v[12:13], v[68:71], off offset:32
	global_store_dwordx4 v[12:13], v[72:75], off offset:48
	v_readlane_b32 s5, v251, 1
	s_add_i32 s0, s0, s5
	v_readlane_b32 s5, v253, 21
	s_add_i32 s10, s10, s5
	s_cmpk_lt_i32 s0, 0x400
	s_cbranch_scc1 .Lhz_loop

; __device__ __forceinline__ void phase_mlstm_gates(const Params& p, int l, const int tidx) {
;     ...
;     for (int kk = 0; kk < 32; kk++) {
;       const int k = kk * 32 + quad * 8;
;       bf16x8 bfr = *(const bf16x8*)(GTt + (size_t)l15 * 1024 + k);
;       const int col = (k < 512) ? (OFF_XC + k) : (OFF_AX + k - 512);
; #pragma unroll
;       for (int mi = 0; mi < 4; mi++) {
;         bf16x8 afr = *(const bf16x8*)(P + (tok0 + mi * 16 + l15) * NP + col);
;         acc[mi] = __builtin_amdgcn_mfma_f32_16x16x32_bf16(afr, bfr, acc[mi], 0, 0, 0);
;       }
;     }
; #pragma unroll
;     for (int mi = 0; mi < 4; mi++)
; #pragma unroll
;       for (int r = 0; r < 4; r++) sg[(mi * 16 + quad * 4 + r) * 17 + l15] = acc[mi][r] + gbias;
.LBB0_395:
	s_cmp_lt_u32 s28, 16
	s_cselect_b64 vcc, -1, 0
	v_add_u32_e32 v0, s0, v39
	v_add_u32_e32 v29, 3072, v0
	v_add_u32_e32 v47, 0xfffffe00, v0
	v_cndmask_b32_e32 v48, v47, v29, vcc
	v_ashrrev_i32_e32 v49, 31, v48
	v_lshl_add_u64 v[52:53], v[48:49], 1, v[32:33]
	global_load_dwordx4 v[56:59], v[34:35], off offset:-192
	global_load_dwordx4 v[72:75], v[52:53], off
	v_add_co_u32_e64 v50, s[22:23], s33, v52
	s_nop 1
	v_addc_co_u32_e64 v51, s[22:23], 0, v53, s[22:23]
	global_load_dwordx4 v[76:79], v[50:51], off
	v_add_co_u32_e64 v50, s[22:23], s68, v52
	s_nop 1
	v_addc_co_u32_e64 v51, s[22:23], 0, v53, s[22:23]
	global_load_dwordx4 v[80:83], v[50:51], off
	v_add_co_u32_e64 v50, s[22:23], s4, v52
	s_nop 1
	v_addc_co_u32_e64 v51, s[22:23], 0, v53, s[22:23]
	global_load_dwordx4 v[84:87], v[50:51], off
	v_add_u32_e32 v29, 3104, v0
	v_add_u32_e32 v47, 0xfffffe20, v0
	v_cndmask_b32_e32 v48, v47, v29, vcc
	v_ashrrev_i32_e32 v49, 31, v48
	v_lshl_add_u64 v[52:53], v[48:49], 1, v[32:33]
	global_load_dwordx4 v[60:63], v[34:35], off offset:-128
	global_load_dwordx4 v[88:91], v[52:53], off
	v_add_co_u32_e64 v50, s[22:23], s33, v52
	s_nop 1
	v_addc_co_u32_e64 v51, s[22:23], 0, v53, s[22:23]
	global_load_dwordx4 v[92:95], v[50:51], off
	v_add_co_u32_e64 v50, s[22:23], s68, v52
	s_nop 1
	v_addc_co_u32_e64 v51, s[22:23], 0, v53, s[22:23]
	global_load_dwordx4 v[96:99], v[50:51], off
	v_add_co_u32_e64 v50, s[22:23], s4, v52
	s_nop 1
	v_addc_co_u32_e64 v51, s[22:23], 0, v53, s[22:23]
	global_load_dwordx4 v[100:103], v[50:51], off
	v_add_u32_e32 v29, 3136, v0
	v_add_u32_e32 v47, 0xfffffe40, v0
	v_cndmask_b32_e32 v48, v47, v29, vcc
	v_ashrrev_i32_e32 v49, 31, v48
	v_lshl_add_u64 v[52:53], v[48:49], 1, v[32:33]
	global_load_dwordx4 v[64:67], v[34:35], off offset:-64
	global_load_dwordx4 v[104:107], v[52:53], off
	v_add_co_u32_e64 v50, s[22:23], s33, v52
	s_nop 1
	v_addc_co_u32_e64 v51, s[22:23], 0, v53, s[22:23]
	global_load_dwordx4 v[108:111], v[50:51], off
	v_add_co_u32_e64 v50, s[22:23], s68, v52
	s_nop 1
	v_addc_co_u32_e64 v51, s[22:23], 0, v53, s[22:23]
	global_load_dwordx4 v[112:115], v[50:51], off
	v_add_co_u32_e64 v50, s[22:23], s4, v52
	s_nop 1
	v_addc_co_u32_e64 v51, s[22:23], 0, v53, s[22:23]
	global_load_dwordx4 v[116:119], v[50:51], off
	v_add_u32_e32 v29, 3168, v0
	v_add_u32_e32 v47, 0xfffffe60, v0
	v_cndmask_b32_e32 v48, v47, v29, vcc
	v_ashrrev_i32_e32 v49, 31, v48
	v_lshl_add_u64 v[52:53], v[48:49], 1, v[32:33]
	global_load_dwordx4 v[68:71], v[34:35], off
	global_load_dwordx4 v[120:123], v[52:53], off
	v_add_co_u32_e64 v50, s[22:23], s33, v52
	s_nop 1
	v_addc_co_u32_e64 v51, s[22:23], 0, v53, s[22:23]
	global_load_dwordx4 v[124:127], v[50:51], off
	v_add_co_u32_e64 v50, s[22:23], s68, v52
	s_nop 1
	v_addc_co_u32_e64 v51, s[22:23], 0, v53, s[22:23]
	global_load_dwordx4 v[128:131], v[50:51], off
	v_add_co_u32_e64 v50, s[22:23], s4, v52
	s_nop 1
	v_addc_co_u32_e64 v51, s[22:23], 0, v53, s[22:23]
	global_load_dwordx4 v[132:135], v[50:51], off
	s_waitcnt vmcnt(18)
	v_mfma_f32_16x16x32_bf16 v[20:23], v[72:75], v[56:59], v[20:23]
	s_waitcnt vmcnt(17)
	v_mfma_f32_16x16x32_bf16 v[24:27], v[76:79], v[56:59], v[24:27]
	s_waitcnt vmcnt(16)
	v_mfma_f32_16x16x32_bf16 v[16:19], v[80:83], v[56:59], v[16:19]
	s_waitcnt vmcnt(15)
	v_mfma_f32_16x16x32_bf16 v[8:11], v[84:87], v[56:59], v[8:11]
	s_waitcnt vmcnt(13)
	v_mfma_f32_16x16x32_bf16 v[20:23], v[88:91], v[60:63], v[20:23]
	s_waitcnt vmcnt(12)
	v_mfma_f32_16x16x32_bf16 v[24:27], v[92:95], v[60:63], v[24:27]
	s_waitcnt vmcnt(11)
	v_mfma_f32_16x16x32_bf16 v[16:19], v[96:99], v[60:63], v[16:19]
	s_waitcnt vmcnt(10)
	v_mfma_f32_16x16x32_bf16 v[8:11], v[100:103], v[60:63], v[8:11]
	s_waitcnt vmcnt(8)
	v_mfma_f32_16x16x32_bf16 v[20:23], v[104:107], v[64:67], v[20:23]
	s_waitcnt vmcnt(7)
	v_mfma_f32_16x16x32_bf16 v[24:27], v[108:111], v[64:67], v[24:27]
	s_waitcnt vmcnt(6)
	v_mfma_f32_16x16x32_bf16 v[16:19], v[112:115], v[64:67], v[16:19]
	s_waitcnt vmcnt(5)
	v_mfma_f32_16x16x32_bf16 v[8:11], v[116:119], v[64:67], v[8:11]
	s_waitcnt vmcnt(3)
	v_mfma_f32_16x16x32_bf16 v[20:23], v[120:123], v[68:71], v[20:23]
	s_waitcnt vmcnt(2)
	v_mfma_f32_16x16x32_bf16 v[24:27], v[124:127], v[68:71], v[24:27]
	s_waitcnt vmcnt(1)
	v_mfma_f32_16x16x32_bf16 v[16:19], v[128:131], v[68:71], v[16:19]
	s_waitcnt vmcnt(0)
	v_mfma_f32_16x16x32_bf16 v[8:11], v[132:135], v[68:71], v[8:11]
	v_lshl_add_u64 v[34:35], v[34:35], 0, s[70:71]
	s_add_i32 s28, s28, 4
	s_addk_i32 s0, 0x80
	s_cmpk_eq_i32 s0, 0x400
	s_cbranch_scc0 .LBB0_395
	v_add_f32_e32 v0, v36, v20
	v_add_f32_e32 v12, v36, v21
	v_add_u32_e32 v13, 0xe000, v46
	ds_write2_b32 v13, v0, v12 offset1:17
	v_add_f32_e32 v0, v36, v22
	v_add_f32_e32 v12, v36, v23
	ds_write2_b32 v13, v0, v12 offset0:34 offset1:51
	v_add_f32_e32 v0, v36, v24
	v_add_f32_e32 v12, v36, v25
	v_add_u32_e32 v13, 0xe400, v46
	ds_write2_b32 v13, v0, v12 offset0:16 offset1:33
	v_add_f32_e32 v0, v36, v26
	v_add_f32_e32 v12, v36, v27
	ds_write2_b32 v13, v0, v12 offset0:50 offset1:67
	v_add_f32_e32 v0, v36, v16
	v_add_f32_e32 v12, v36, v17
	v_add_u32_e32 v13, 0xe800, v46
	ds_write2_b32 v13, v0, v12 offset0:32 offset1:49
	v_add_f32_e32 v0, v36, v18
	v_add_f32_e32 v12, v36, v19
	ds_write2_b32 v13, v0, v12 offset0:66 offset1:83
	v_add_f32_e32 v0, v36, v8
	v_add_f32_e32 v8, v36, v9
	v_add_u32_e32 v9, 0xec00, v46
	ds_write2_b32 v9, v0, v8 offset0:48 offset1:65
	v_add_f32_e32 v0, v36, v10
	v_add_f32_e32 v8, v36, v11
	ds_write2_b32 v9, v0, v8 offset0:82 offset1:99
	v_lshlrev_b32_e32 v0, 6, v28
	s_movk_i32 s0, 0xfc0
	v_and_b32_e32 v10, 0xfc0, v0
	v_bitop3_b32 v11, v0, s0, v0 bitop3:0xc
	v_ashrrev_i32_e32 v0, 4, v28
	v_and_b32_e32 v12, -4, v0
	s_mov_b32 s0, 0

; __device__ __forceinline__ void phase_rwkv_scan(const Params& p, int l, const int tidx) {
;     ...
;         {
;           f32x4 acc[8];
; #pragma unroll
;           for (int nt = 0; nt < 8; nt++) acc[nt] = f32x4{0.f, 0.f, 0.f, 0.f};
; #pragma unroll
;           for (int k2 = 0; k2 < 2; k2++) {
;             bf16x8 af = *(const bf16x8*)(myA + l15 * LSTR + k2 * 32 + quad * 8);
; #pragma unroll
;             for (int nt = 0; nt < 8; nt++) {
;               bf16x8 bfv = *(const bf16x8*)(sBT + (nt * 16 + l15) * LSTR + k2 * 32 + quad * 8);
;               acc[nt] = __builtin_amdgcn_mfma_f32_16x16x32_bf16(af, bfv, acc[nt], 0, 0, 0);
;             }
;           }
;           if (quad < 2) {
; #pragma unroll
;             for (int nt = 0; nt < 4; nt++)
; #pragma unroll
;               for (int r = 0; r < 4; r++) myT[(quad * 4 + r) * 68 + nt * 16 + l15] = acc[nt][r];
;           } else {
; #pragma unroll
;             for (int nt = 0; nt < 4; nt++)
; #pragma unroll
;               for (int r = 0; r < 4; r++) myT[(quad * 4 + r) * 68 + nt * 16 + l15] = acc[4 + nt][r];
;           }
;         }
;         __builtin_amdgcn_wave_barrier();
; #pragma unroll
;         for (int q = 0; q < TPW; q++) {
;           const int s = pw * TPW + q;
;           float wl = w0j + myT[q * 68 + j];
;           float al = a0j + myT[(TPW + q) * 68 + j];
;           float dec = __expf(-0.6065306597126334f * sigmoidf_(wl));
;           float av = sigmoidf_(al);
;           float kkr = uk[q] * kks;
;           float ss = wave_sum(kkr * kkr);
;           float kk = kkr * __builtin_amdgcn_rcpf(fmaxf(sqrtf(ss), 1e-12f));
;           float kd = uk[q] * (1.f + (av - 1.f) * kap);
;           float bt = wave_sum(ur[q] * kd * rkj);
;           float c1 = wave_sum(kk * av * ur[q]);
;           float c2 = wave_sum(kd * ur[q]);
;           nbw[s * 64 + j] = dec;
;           nbw[1 * VSZ + s * 64 + j] = kk * av;
;           nbw[2 * VSZ + s * 64 + j] = kd;
;           ((bf16_t*)(nbw + 3 * VSZ))[s * 128 + j] = f2bf(kk);
;           ((bf16_t*)(nbw + 3 * VSZ))[s * 128 + 64 + j] = f2bf(dec * ur[q]);
;           nbw[4 * VSZ + s * 64 + j] = uv[q];
;           if (lane == 1) *(float2*)(nbw + 6 * VSZ + 2 * s) = float2{c1, c2};
;           if (lane == 0) {
;             int tau = pc * RTC + s;
;             int t = dir ? (4095 - tau) : tau;
;             beta[(size_t)(b * SEQ + t) * 16 + h] = bt;
;           }
;         }
.Lrp_noload:
	s_waitcnt lgkmcnt(0)
	ds_read_b128 v[152:155], v65
	ds_read_b128 v[156:159], v65 offset:64
	s_waitcnt lgkmcnt(1)
	v_mfma_f32_16x16x32_bf16 v[2:5], v[152:155], v[170:173], 0
	v_mfma_f32_16x16x32_bf16 v[6:9], v[152:155], v[178:181], 0
	v_mfma_f32_16x16x32_bf16 v[10:13], v[152:155], v[186:189], 0
	v_mfma_f32_16x16x32_bf16 v[14:17], v[152:155], v[194:197], 0
	v_mfma_f32_16x16x32_bf16 v[18:21], v[152:155], v[202:205], 0
	v_mfma_f32_16x16x32_bf16 v[22:25], v[152:155], v[210:213], 0
	v_mfma_f32_16x16x32_bf16 v[26:29], v[152:155], v[218:221], 0
	v_mfma_f32_16x16x32_bf16 v[30:33], v[152:155], v[226:229], 0
	s_waitcnt lgkmcnt(0)
	v_mfma_f32_16x16x32_bf16 v[2:5], v[156:159], v[174:177], v[2:5]
	v_mfma_f32_16x16x32_bf16 v[6:9], v[156:159], v[182:185], v[6:9]
	v_mfma_f32_16x16x32_bf16 v[10:13], v[156:159], v[190:193], v[10:13]
	v_mfma_f32_16x16x32_bf16 v[14:17], v[156:159], v[198:201], v[14:17]
	v_mfma_f32_16x16x32_bf16 v[18:21], v[156:159], v[206:209], v[18:21]
	v_mfma_f32_16x16x32_bf16 v[22:25], v[156:159], v[214:217], v[22:25]
	v_mfma_f32_16x16x32_bf16 v[26:29], v[156:159], v[222:225], v[26:29]
	v_mfma_f32_16x16x32_bf16 v[30:33], v[156:159], v[230:233], v[30:33]
	s_nop 4
	v_cndmask_b32_e64 v2, v18, v2, s[30:31]
	v_cndmask_b32_e64 v3, v19, v3, s[30:31]
	v_cndmask_b32_e64 v4, v20, v4, s[30:31]
	v_cndmask_b32_e64 v5, v21, v5, s[30:31]
	v_cndmask_b32_e64 v6, v22, v6, s[30:31]
	v_cndmask_b32_e64 v7, v23, v7, s[30:31]
	v_cndmask_b32_e64 v8, v24, v8, s[30:31]
	v_cndmask_b32_e64 v9, v25, v9, s[30:31]
	v_cndmask_b32_e64 v10, v26, v10, s[30:31]
	v_cndmask_b32_e64 v11, v27, v11, s[30:31]
	v_cndmask_b32_e64 v12, v28, v12, s[30:31]
	v_cndmask_b32_e64 v13, v29, v13, s[30:31]
	v_cndmask_b32_e64 v14, v30, v14, s[30:31]
	v_cndmask_b32_e64 v15, v31, v15, s[30:31]
	v_cndmask_b32_e64 v16, v32, v16, s[30:31]
	v_cndmask_b32_e64 v17, v33, v17, s[30:31]
	ds_write2_b32 v66, v2, v3 offset0:0 offset1:68
	ds_write2_b32 v66, v4, v5 offset0:136 offset1:204
	ds_write2_b32 v66, v6, v7 offset0:16 offset1:84
	ds_write2_b32 v66, v8, v9 offset0:152 offset1:220
	ds_write2_b32 v66, v10, v11 offset0:32 offset1:100
	ds_write2_b32 v66, v12, v13 offset0:168 offset1:236
	ds_write2_b32 v66, v14, v15 offset0:48 offset1:116
	ds_write2_b32 v66, v16, v17 offset0:184 offset1:252
	s_waitcnt lgkmcnt(0)
	v_mov_b32_e32 v152, 1.0
	ds_read_b32 v2, v68 offset:0
	ds_read_b32 v3, v68 offset:272
	ds_read_b32 v4, v68 offset:2176
	ds_read_b32 v5, v68 offset:2448
	v_pk_mul_f32 v[12:13], v[128:129], v[48:49] op_sel_hi:[1,0]
	v_pk_mul_f32 v[18:19], v[12:13], v[12:13]
	s_waitcnt lgkmcnt(0)
	v_pk_add_f32 v[2:3], v[2:3], v[54:55] op_sel_hi:[1,0]
	v_pk_add_f32 v[4:5], v[4:5], v[56:57] op_sel_hi:[1,0]
	v_pk_mul_f32 v[6:7], v[2:3], v[34:35] op_sel_hi:[1,0]
	v_pk_mul_f32 v[10:11], v[4:5], v[34:35] op_sel_hi:[1,0]
	v_exp_f32_e32 v6, v6
	v_exp_f32_e32 v7, v7
	v_exp_f32_e32 v10, v10
	v_exp_f32_e32 v11, v11
	v_pk_add_f32 v[6:7], v[6:7], v[50:51] op_sel:[0,1] op_sel_hi:[1,1]
	v_pk_add_f32 v[10:11], v[10:11], v[50:51] op_sel:[0,1] op_sel_hi:[1,1]
	v_rcp_f32_e32 v6, v6
	v_rcp_f32_e32 v7, v7
	v_rcp_f32_e32 v10, v10
	v_rcp_f32_e32 v11, v11
	v_pk_mul_f32 v[8:9], v[6:7], v[144:145] op_sel_hi:[1,0]
	v_exp_f32_e32 v8, v8
	v_exp_f32_e32 v9, v9
	v_mul_f32_e32 v153, v152, v8
	v_mov_b32_e32 v154, v153
	v_mul_f32_e32 v155, v153, v9
	v_rcp_f32_e32 v156, v154
	v_rcp_f32_e32 v157, v155
	v_pk_add_f32 v[14:15], v[10:11], v[146:147] op_sel_hi:[1,0]
	v_pk_fma_f32 v[14:15], v[14:15], v[50:51], v[50:51] op_sel:[0,0,1] op_sel_hi:[1,0,1]
	v_pk_mul_f32 v[16:17], v[128:129], v[14:15]
	v_pk_mul_f32 v[20:21], v[120:121], v[16:17]
	v_pk_mul_f32 v[22:23], v[20:21], v[52:53] op_sel_hi:[1,0]
	v_pk_mul_f32 v[24:25], v[12:13], v[10:11]
	v_pk_mul_f32 v[24:25], v[24:25], v[120:121]
	v_add_f32_dpp v18, v18, v18 quad_perm:[1,0,3,2] row_mask:0xf bank_mask:0xf
	v_add_f32_dpp v19, v19, v19 quad_perm:[1,0,3,2] row_mask:0xf bank_mask:0xf
	v_add_f32_dpp v22, v22, v22 quad_perm:[1,0,3,2] row_mask:0xf bank_mask:0xf
	v_add_f32_dpp v23, v23, v23 quad_perm:[1,0,3,2] row_mask:0xf bank_mask:0xf
	v_add_f32_dpp v24, v24, v24 quad_perm:[1,0,3,2] row_mask:0xf bank_mask:0xf
	v_add_f32_dpp v25, v25, v25 quad_perm:[1,0,3,2] row_mask:0xf bank_mask:0xf
	v_add_f32_dpp v20, v20, v20 quad_perm:[1,0,3,2] row_mask:0xf bank_mask:0xf
	v_add_f32_dpp v21, v21, v21 quad_perm:[1,0,3,2] row_mask:0xf bank_mask:0xf
	v_cndmask_b32_e64 v26, v18, v19, s[24:25]
	v_cndmask_b32_e64 v27, v22, v23, s[24:25]
	v_cndmask_b32_e64 v28, v24, v25, s[24:25]
	v_cndmask_b32_e64 v29, v20, v21, s[24:25]
	v_add_f32_dpp v26, v26, v26 quad_perm:[2,3,0,1] row_mask:0xf bank_mask:0xf
	v_add_f32_dpp v27, v27, v27 quad_perm:[2,3,0,1] row_mask:0xf bank_mask:0xf
	v_add_f32_dpp v28, v28, v28 quad_perm:[2,3,0,1] row_mask:0xf bank_mask:0xf
	v_add_f32_dpp v29, v29, v29 quad_perm:[2,3,0,1] row_mask:0xf bank_mask:0xf
	v_cndmask_b32_e64 v30, v26, v27, s[26:27]
	v_cndmask_b32_e64 v31, v28, v29, s[26:27]
	s_nop 0
	v_add_f32_dpp v30, v30, v30 row_ror:4 row_mask:0xf bank_mask:0xf
	v_add_f32_dpp v31, v31, v31 row_ror:4 row_mask:0xf bank_mask:0xf
	v_cndmask_b32_e64 v32, v30, v31, s[28:29]
	s_nop 1
	v_add_f32_dpp v32, v32, v32 row_ror:8 row_mask:0xf bank_mask:0xf
	v_mov_b32_e32 v33, v32
	s_nop 1
	v_permlane16_swap_b32 v33, v32
	v_add_f32_e32 v32, v33, v32
	v_mov_b32_e32 v33, v32
	s_nop 1
	v_permlane32_swap_b32 v33, v32
	v_add_f32_e32 v32, v33, v32
	s_nop 1
	v_mov_b32_dpp v246, v32 row_newbcast:0 row_mask:0xf bank_mask:0xf
	v_mov_b32_dpp v247, v32 row_newbcast:1 row_mask:0xf bank_mask:0xf
	v_max_f32_e32 v246, 0x179abe15, v246
	v_max_f32_e32 v247, 0x179abe15, v247
	v_rsq_f32_e32 v238, v246
	v_rsq_f32_e32 v239, v247
	s_nop 0
; __device__ __forceinline__ float sigmoidf_(float x) { return __builtin_amdgcn_rcpf(1.f + __expf(-x)); }
; __device__ __forceinline__ void phase_rwkv_scan(const Params& p, int l, const int tidx) {
;     ...
; #pragma unroll
;         for (int q = 0; q < TPW; q++) {
;           const int s = pw * TPW + q;
;           float wl = w0j + myT[q * 68 + j];
;           float al = a0j + myT[(TPW + q) * 68 + j];
;           float dec = __expf(-0.6065306597126334f * sigmoidf_(wl));
;           float av = sigmoidf_(al);
;           float kkr = uk[q] * kks;
;           float ss = wave_sum(kkr * kkr);
;           float kk = kkr * __builtin_amdgcn_rcpf(fmaxf(sqrtf(ss), 1e-12f));
;           float kd = uk[q] * (1.f + (av - 1.f) * kap);
;           float bt = wave_sum(ur[q] * kd * rkj);
;           float c1 = wave_sum(kk * av * ur[q]);
;           float c2 = wave_sum(kd * ur[q]);
;           nbw[s * 64 + j] = dec;
;           nbw[1 * VSZ + s * 64 + j] = kk * av;
;           nbw[2 * VSZ + s * 64 + j] = kd;
;           ((bf16_t*)(nbw + 3 * VSZ))[s * 128 + j] = f2bf(kk);
;           ((bf16_t*)(nbw + 3 * VSZ))[s * 128 + 64 + j] = f2bf(dec * ur[q]);
;           nbw[4 * VSZ + s * 64 + j] = uv[q];
;           if (lane == 1) *(float2*)(nbw + 6 * VSZ + 2 * s) = float2{c1, c2};
;           if (lane == 0) {
;             int tau = pc * RTC + s;
;             int t = dir ? (4095 - tau) : tau;
;             beta[(size_t)(b * SEQ + t) * 16 + h] = bt;
;           }
;         }
	v_pk_mul_f32 v[242:243], v[12:13], v[238:239]
	v_mul_f32_dpp v244, v32, v238 row_newbcast:4 row_mask:0xf bank_mask:0xf
	v_mul_f32_dpp v245, v32, v239 row_newbcast:5 row_mask:0xf bank_mask:0xf
	v_pk_mul_f32 v[6:7], v[242:243], v[10:11]
	v_pk_mul_f32 v[14:15], v[154:155], v[120:121]
	v_pk_mul_f32 v[242:243], v[242:243], v[152:153]
	v_pk_mul_f32 v[6:7], v[6:7], v[156:157] neg_lo:[0,1] neg_hi:[0,1]
	v_pk_mul_f32 v[16:17], v[16:17], v[156:157]
	v_cvt_pk_bf16_f32 v248, v242, v243
	v_cvt_pk_bf16_f32 v249, v14, v15
	v_mov_b32_e32 v152, v155
	ds_write_b32 v234, v6 offset:8192
	ds_write_b32 v234, v16 offset:16384
	ds_write_b32 v234, v136 offset:32768
	ds_write_b32 v234, v7 offset:8448
	ds_write_b32 v234, v17 offset:16640
	ds_write_b32 v234, v137 offset:33024
	ds_write_b16 v235, v248 offset:0
	ds_write_b16_d16_hi v235, v248 offset:256
	ds_write_b16 v235, v249 offset:128
	ds_write_b16_d16_hi v235, v249 offset:384
	s_lshl_b32 s12, s0, 5
	s_lshl_b32 s13, s17, 3
	s_add_i32 s12, s12, s13
	s_add_i32 s12, s12, 0
	s_sub_i32 s67, 0xfff, s12
	s_cmp_eq_u32 s16, 0
	s_cselect_b32 s13, s12, s67
	s_add_i32 s13, s13, s5
	s_lshl_b32 s13, s13, 6
	s_add_u32 s72, s22, s13
	s_addc_u32 s73, s23, 0
	s_add_i32 s12, s12, 1
	s_sub_i32 s67, 0xfff, s12
	s_cmp_eq_u32 s16, 0
	s_cselect_b32 s13, s12, s67
	s_add_i32 s13, s13, s5
	s_lshl_b32 s13, s13, 6
	s_add_u32 s74, s22, s13
	s_addc_u32 s75, s23, 0
	s_mov_b64 exec, 1
	ds_write_b32 v236, v244 offset:49152
	ds_write_b32 v236, v245 offset:49160
	s_mov_b64 exec, 0x40
	ds_write_b32 v236, v32 offset:49156
	s_mov_b64 exec, 0x80
	ds_write_b32 v236, v32 offset:49164
	s_mov_b64 exec, 4
	global_store_dword v1, v32, s[72:73]
	s_mov_b64 exec, 8
	global_store_dword v1, v32, s[74:75]
	s_mov_b64 exec, -1
	ds_read_b32 v2, v68 offset:544
	ds_read_b32 v3, v68 offset:816
	ds_read_b32 v4, v68 offset:2720
	ds_read_b32 v5, v68 offset:2992
	v_pk_mul_f32 v[12:13], v[130:131], v[48:49] op_sel_hi:[1,0]
	v_pk_mul_f32 v[18:19], v[12:13], v[12:13]
	s_waitcnt lgkmcnt(0)
	v_pk_add_f32 v[2:3], v[2:3], v[54:55] op_sel_hi:[1,0]
	v_pk_add_f32 v[4:5], v[4:5], v[56:57] op_sel_hi:[1,0]
	v_pk_mul_f32 v[6:7], v[2:3], v[34:35] op_sel_hi:[1,0]
	v_pk_mul_f32 v[10:11], v[4:5], v[34:35] op_sel_hi:[1,0]
	v_exp_f32_e32 v6, v6
	v_exp_f32_e32 v7, v7
	v_exp_f32_e32 v10, v10
	v_exp_f32_e32 v11, v11
	v_pk_add_f32 v[6:7], v[6:7], v[50:51] op_sel:[0,1] op_sel_hi:[1,1]
	v_pk_add_f32 v[10:11], v[10:11], v[50:51] op_sel:[0,1] op_sel_hi:[1,1]
	v_rcp_f32_e32 v6, v6
	v_rcp_f32_e32 v7, v7
	v_rcp_f32_e32 v10, v10
	v_rcp_f32_e32 v11, v11
	v_pk_mul_f32 v[8:9], v[6:7], v[144:145] op_sel_hi:[1,0]
	v_exp_f32_e32 v8, v8
	v_exp_f32_e32 v9, v9
	v_mul_f32_e32 v153, v152, v8
	v_mov_b32_e32 v154, v153
	v_mul_f32_e32 v155, v153, v9
	v_rcp_f32_e32 v156, v154
	v_rcp_f32_e32 v157, v155
	v_pk_add_f32 v[14:15], v[10:11], v[146:147] op_sel_hi:[1,0]
	v_pk_fma_f32 v[14:15], v[14:15], v[50:51], v[50:51] op_sel:[0,0,1] op_sel_hi:[1,0,1]
	v_pk_mul_f32 v[16:17], v[130:131], v[14:15]
	v_pk_mul_f32 v[20:21], v[122:123], v[16:17]
	v_pk_mul_f32 v[22:23], v[20:21], v[52:53] op_sel_hi:[1,0]
	v_pk_mul_f32 v[24:25], v[12:13], v[10:11]
	v_pk_mul_f32 v[24:25], v[24:25], v[122:123]
	v_add_f32_dpp v18, v18, v18 quad_perm:[1,0,3,2] row_mask:0xf bank_mask:0xf
	v_add_f32_dpp v19, v19, v19 quad_perm:[1,0,3,2] row_mask:0xf bank_mask:0xf
	v_add_f32_dpp v22, v22, v22 quad_perm:[1,0,3,2] row_mask:0xf bank_mask:0xf
	v_add_f32_dpp v23, v23, v23 quad_perm:[1,0,3,2] row_mask:0xf bank_mask:0xf
	v_add_f32_dpp v24, v24, v24 quad_perm:[1,0,3,2] row_mask:0xf bank_mask:0xf
	v_add_f32_dpp v25, v25, v25 quad_perm:[1,0,3,2] row_mask:0xf bank_mask:0xf
	v_add_f32_dpp v20, v20, v20 quad_perm:[1,0,3,2] row_mask:0xf bank_mask:0xf
	v_add_f32_dpp v21, v21, v21 quad_perm:[1,0,3,2] row_mask:0xf bank_mask:0xf
	v_cndmask_b32_e64 v26, v18, v19, s[24:25]
	v_cndmask_b32_e64 v27, v22, v23, s[24:25]
	v_cndmask_b32_e64 v28, v24, v25, s[24:25]
	v_cndmask_b32_e64 v29, v20, v21, s[24:25]
	v_add_f32_dpp v26, v26, v26 quad_perm:[2,3,0,1] row_mask:0xf bank_mask:0xf
	v_add_f32_dpp v27, v27, v27 quad_perm:[2,3,0,1] row_mask:0xf bank_mask:0xf
	v_add_f32_dpp v28, v28, v28 quad_perm:[2,3,0,1] row_mask:0xf bank_mask:0xf
	v_add_f32_dpp v29, v29, v29 quad_perm:[2,3,0,1] row_mask:0xf bank_mask:0xf
	v_cndmask_b32_e64 v30, v26, v27, s[26:27]
	v_cndmask_b32_e64 v31, v28, v29, s[26:27]
	s_nop 0
	v_add_f32_dpp v30, v30, v30 row_ror:4 row_mask:0xf bank_mask:0xf
	v_add_f32_dpp v31, v31, v31 row_ror:4 row_mask:0xf bank_mask:0xf
	v_cndmask_b32_e64 v32, v30, v31, s[28:29]
	s_nop 1
	v_add_f32_dpp v32, v32, v32 row_ror:8 row_mask:0xf bank_mask:0xf
	v_mov_b32_e32 v33, v32
	s_nop 1
	v_permlane16_swap_b32 v33, v32
	v_add_f32_e32 v32, v33, v32
	v_mov_b32_e32 v33, v32
	s_nop 1
	v_permlane32_swap_b32 v33, v32
	v_add_f32_e32 v32, v33, v32
	s_nop 1
	v_mov_b32_dpp v246, v32 row_newbcast:0 row_mask:0xf bank_mask:0xf
	v_mov_b32_dpp v247, v32 row_newbcast:1 row_mask:0xf bank_mask:0xf
	v_max_f32_e32 v246, 0x179abe15, v246
	v_max_f32_e32 v247, 0x179abe15, v247
	v_rsq_f32_e32 v238, v246
	v_rsq_f32_e32 v239, v247
	s_nop 0
	v_pk_mul_f32 v[242:243], v[12:13], v[238:239]
	v_mul_f32_dpp v244, v32, v238 row_newbcast:4 row_mask:0xf bank_mask:0xf
	v_mul_f32_dpp v245, v32, v239 row_newbcast:5 row_mask:0xf bank_mask:0xf
	v_pk_mul_f32 v[6:7], v[242:243], v[10:11]
	v_pk_mul_f32 v[14:15], v[154:155], v[122:123]
	v_pk_mul_f32 v[242:243], v[242:243], v[152:153]
	v_pk_mul_f32 v[6:7], v[6:7], v[156:157] neg_lo:[0,1] neg_hi:[0,1]
	v_pk_mul_f32 v[16:17], v[16:17], v[156:157]
	v_cvt_pk_bf16_f32 v248, v242, v243
	v_cvt_pk_bf16_f32 v249, v14, v15
	v_mov_b32_e32 v152, v155
	ds_write_b32 v234, v6 offset:8704
	ds_write_b32 v234, v16 offset:16896
	ds_write_b32 v234, v138 offset:33280
	ds_write_b32 v234, v7 offset:8960
	ds_write_b32 v234, v17 offset:17152
	ds_write_b32 v234, v139 offset:33536
	ds_write_b16 v235, v248 offset:512
	ds_write_b16_d16_hi v235, v248 offset:768
	ds_write_b16 v235, v249 offset:640
	ds_write_b16_d16_hi v235, v249 offset:896
	s_lshl_b32 s12, s0, 5
	s_lshl_b32 s13, s17, 3
	s_add_i32 s12, s12, s13
	s_add_i32 s12, s12, 2
	s_sub_i32 s67, 0xfff, s12
	s_cmp_eq_u32 s16, 0
	s_cselect_b32 s13, s12, s67
	s_add_i32 s13, s13, s5
	s_lshl_b32 s13, s13, 6
	s_add_u32 s72, s22, s13
	s_addc_u32 s73, s23, 0
	s_add_i32 s12, s12, 1
	s_sub_i32 s67, 0xfff, s12
	s_cmp_eq_u32 s16, 0
	s_cselect_b32 s13, s12, s67
	s_add_i32 s13, s13, s5
	s_lshl_b32 s13, s13, 6
	s_add_u32 s74, s22, s13
	s_addc_u32 s75, s23, 0
	s_mov_b64 exec, 1
	ds_write_b32 v236, v244 offset:49168
	ds_write_b32 v236, v245 offset:49176
	s_mov_b64 exec, 0x40
	ds_write_b32 v236, v32 offset:49172
	s_mov_b64 exec, 0x80
	ds_write_b32 v236, v32 offset:49180
	s_mov_b64 exec, 4
	global_store_dword v1, v32, s[72:73]
	s_mov_b64 exec, 8
	global_store_dword v1, v32, s[74:75]
	s_mov_b64 exec, -1
	ds_read_b32 v2, v68 offset:1088
	ds_read_b32 v3, v68 offset:1360
	ds_read_b32 v4, v68 offset:3264
	ds_read_b32 v5, v68 offset:3536
	v_pk_mul_f32 v[12:13], v[132:133], v[48:49] op_sel_hi:[1,0]
	v_pk_mul_f32 v[18:19], v[12:13], v[12:13]
	s_waitcnt lgkmcnt(0)
; __device__ __forceinline__ float sigmoidf_(float x) { return __builtin_amdgcn_rcpf(1.f + __expf(-x)); }
; __device__ __forceinline__ void phase_rwkv_scan(const Params& p, int l, const int tidx) {
;     ...
; #pragma unroll
;         for (int q = 0; q < TPW; q++) {
;           const int s = pw * TPW + q;
;           float wl = w0j + myT[q * 68 + j];
;           float al = a0j + myT[(TPW + q) * 68 + j];
;           float dec = __expf(-0.6065306597126334f * sigmoidf_(wl));
;           float av = sigmoidf_(al);
;           float kkr = uk[q] * kks;
;           float ss = wave_sum(kkr * kkr);
;           float kk = kkr * __builtin_amdgcn_rcpf(fmaxf(sqrtf(ss), 1e-12f));
;           float kd = uk[q] * (1.f + (av - 1.f) * kap);
;           float bt = wave_sum(ur[q] * kd * rkj);
;           float c1 = wave_sum(kk * av * ur[q]);
;           float c2 = wave_sum(kd * ur[q]);
;           nbw[s * 64 + j] = dec;
;           nbw[1 * VSZ + s * 64 + j] = kk * av;
;           nbw[2 * VSZ + s * 64 + j] = kd;
;           ((bf16_t*)(nbw + 3 * VSZ))[s * 128 + j] = f2bf(kk);
;           ((bf16_t*)(nbw + 3 * VSZ))[s * 128 + 64 + j] = f2bf(dec * ur[q]);
;           nbw[4 * VSZ + s * 64 + j] = uv[q];
;           if (lane == 1) *(float2*)(nbw + 6 * VSZ + 2 * s) = float2{c1, c2};
;           if (lane == 0) {
;             int tau = pc * RTC + s;
;             int t = dir ? (4095 - tau) : tau;
;             beta[(size_t)(b * SEQ + t) * 16 + h] = bt;
;           }
;         }
	v_pk_add_f32 v[2:3], v[2:3], v[54:55] op_sel_hi:[1,0]
	v_pk_add_f32 v[4:5], v[4:5], v[56:57] op_sel_hi:[1,0]
	v_pk_mul_f32 v[6:7], v[2:3], v[34:35] op_sel_hi:[1,0]
	v_pk_mul_f32 v[10:11], v[4:5], v[34:35] op_sel_hi:[1,0]
	v_exp_f32_e32 v6, v6
	v_exp_f32_e32 v7, v7
	v_exp_f32_e32 v10, v10
	v_exp_f32_e32 v11, v11
	v_pk_add_f32 v[6:7], v[6:7], v[50:51] op_sel:[0,1] op_sel_hi:[1,1]
	v_pk_add_f32 v[10:11], v[10:11], v[50:51] op_sel:[0,1] op_sel_hi:[1,1]
	v_rcp_f32_e32 v6, v6
	v_rcp_f32_e32 v7, v7
	v_rcp_f32_e32 v10, v10
	v_rcp_f32_e32 v11, v11
	v_pk_mul_f32 v[8:9], v[6:7], v[144:145] op_sel_hi:[1,0]
	v_exp_f32_e32 v8, v8
	v_exp_f32_e32 v9, v9
	v_mul_f32_e32 v153, v152, v8
	v_mov_b32_e32 v154, v153
	v_mul_f32_e32 v155, v153, v9
	v_rcp_f32_e32 v156, v154
	v_rcp_f32_e32 v157, v155
	v_pk_add_f32 v[14:15], v[10:11], v[146:147] op_sel_hi:[1,0]
	v_pk_fma_f32 v[14:15], v[14:15], v[50:51], v[50:51] op_sel:[0,0,1] op_sel_hi:[1,0,1]
	v_pk_mul_f32 v[16:17], v[132:133], v[14:15]
	v_pk_mul_f32 v[20:21], v[124:125], v[16:17]
	v_pk_mul_f32 v[22:23], v[20:21], v[52:53] op_sel_hi:[1,0]
	v_pk_mul_f32 v[24:25], v[12:13], v[10:11]
	v_pk_mul_f32 v[24:25], v[24:25], v[124:125]
	v_add_f32_dpp v18, v18, v18 quad_perm:[1,0,3,2] row_mask:0xf bank_mask:0xf
	v_add_f32_dpp v19, v19, v19 quad_perm:[1,0,3,2] row_mask:0xf bank_mask:0xf
	v_add_f32_dpp v22, v22, v22 quad_perm:[1,0,3,2] row_mask:0xf bank_mask:0xf
	v_add_f32_dpp v23, v23, v23 quad_perm:[1,0,3,2] row_mask:0xf bank_mask:0xf
	v_add_f32_dpp v24, v24, v24 quad_perm:[1,0,3,2] row_mask:0xf bank_mask:0xf
	v_add_f32_dpp v25, v25, v25 quad_perm:[1,0,3,2] row_mask:0xf bank_mask:0xf
	v_add_f32_dpp v20, v20, v20 quad_perm:[1,0,3,2] row_mask:0xf bank_mask:0xf
	v_add_f32_dpp v21, v21, v21 quad_perm:[1,0,3,2] row_mask:0xf bank_mask:0xf
	v_cndmask_b32_e64 v26, v18, v19, s[24:25]
	v_cndmask_b32_e64 v27, v22, v23, s[24:25]
	v_cndmask_b32_e64 v28, v24, v25, s[24:25]
	v_cndmask_b32_e64 v29, v20, v21, s[24:25]
	v_add_f32_dpp v26, v26, v26 quad_perm:[2,3,0,1] row_mask:0xf bank_mask:0xf
	v_add_f32_dpp v27, v27, v27 quad_perm:[2,3,0,1] row_mask:0xf bank_mask:0xf
	v_add_f32_dpp v28, v28, v28 quad_perm:[2,3,0,1] row_mask:0xf bank_mask:0xf
	v_add_f32_dpp v29, v29, v29 quad_perm:[2,3,0,1] row_mask:0xf bank_mask:0xf
	v_cndmask_b32_e64 v30, v26, v27, s[26:27]
	v_cndmask_b32_e64 v31, v28, v29, s[26:27]
	s_nop 0
	v_add_f32_dpp v30, v30, v30 row_ror:4 row_mask:0xf bank_mask:0xf
	v_add_f32_dpp v31, v31, v31 row_ror:4 row_mask:0xf bank_mask:0xf
	v_cndmask_b32_e64 v32, v30, v31, s[28:29]
	s_nop 1
	v_add_f32_dpp v32, v32, v32 row_ror:8 row_mask:0xf bank_mask:0xf
	v_mov_b32_e32 v33, v32
	s_nop 1
	v_permlane16_swap_b32 v33, v32
	v_add_f32_e32 v32, v33, v32
	v_mov_b32_e32 v33, v32
	s_nop 1
	v_permlane32_swap_b32 v33, v32
	v_add_f32_e32 v32, v33, v32
	s_nop 1
	v_mov_b32_dpp v246, v32 row_newbcast:0 row_mask:0xf bank_mask:0xf
	v_mov_b32_dpp v247, v32 row_newbcast:1 row_mask:0xf bank_mask:0xf
	v_max_f32_e32 v246, 0x179abe15, v246
	v_max_f32_e32 v247, 0x179abe15, v247
	v_rsq_f32_e32 v238, v246
	v_rsq_f32_e32 v239, v247
	s_nop 0
	v_pk_mul_f32 v[242:243], v[12:13], v[238:239]
	v_mul_f32_dpp v244, v32, v238 row_newbcast:4 row_mask:0xf bank_mask:0xf
	v_mul_f32_dpp v245, v32, v239 row_newbcast:5 row_mask:0xf bank_mask:0xf
	v_pk_mul_f32 v[6:7], v[242:243], v[10:11]
	v_pk_mul_f32 v[14:15], v[154:155], v[124:125]
	v_pk_mul_f32 v[242:243], v[242:243], v[152:153]
	v_pk_mul_f32 v[6:7], v[6:7], v[156:157] neg_lo:[0,1] neg_hi:[0,1]
	v_pk_mul_f32 v[16:17], v[16:17], v[156:157]
	v_cvt_pk_bf16_f32 v248, v242, v243
	v_cvt_pk_bf16_f32 v249, v14, v15
	v_mov_b32_e32 v152, v155
	ds_write_b32 v234, v6 offset:9216
	ds_write_b32 v234, v16 offset:17408
	ds_write_b32 v234, v140 offset:33792
	ds_write_b32 v234, v7 offset:9472
	ds_write_b32 v234, v17 offset:17664
	ds_write_b32 v234, v141 offset:34048
	ds_write_b16 v235, v248 offset:1024
	ds_write_b16_d16_hi v235, v248 offset:1280
	ds_write_b16 v235, v249 offset:1152
	ds_write_b16_d16_hi v235, v249 offset:1408
	s_lshl_b32 s12, s0, 5
	s_lshl_b32 s13, s17, 3
	s_add_i32 s12, s12, s13
	s_add_i32 s12, s12, 4
	s_sub_i32 s67, 0xfff, s12
	s_cmp_eq_u32 s16, 0
	s_cselect_b32 s13, s12, s67
	s_add_i32 s13, s13, s5
	s_lshl_b32 s13, s13, 6
	s_add_u32 s72, s22, s13
	s_addc_u32 s73, s23, 0
	s_add_i32 s12, s12, 1
	s_sub_i32 s67, 0xfff, s12
	s_cmp_eq_u32 s16, 0
	s_cselect_b32 s13, s12, s67
	s_add_i32 s13, s13, s5
	s_lshl_b32 s13, s13, 6
	s_add_u32 s74, s22, s13
	s_addc_u32 s75, s23, 0
	s_mov_b64 exec, 1
	ds_write_b32 v236, v244 offset:49184
	ds_write_b32 v236, v245 offset:49192
	s_mov_b64 exec, 0x40
	ds_write_b32 v236, v32 offset:49188
	s_mov_b64 exec, 0x80
	ds_write_b32 v236, v32 offset:49196
	s_mov_b64 exec, 4
	global_store_dword v1, v32, s[72:73]
	s_mov_b64 exec, 8
	global_store_dword v1, v32, s[74:75]
	s_mov_b64 exec, -1
	ds_read_b32 v2, v68 offset:1632
	ds_read_b32 v3, v68 offset:1904
	ds_read_b32 v4, v68 offset:3808
	ds_read_b32 v5, v68 offset:4080
	v_pk_mul_f32 v[12:13], v[134:135], v[48:49] op_sel_hi:[1,0]
	v_pk_mul_f32 v[18:19], v[12:13], v[12:13]
	s_waitcnt lgkmcnt(0)
; __device__ __forceinline__ float sigmoidf_(float x) { return __builtin_amdgcn_rcpf(1.f + __expf(-x)); }
; __device__ __forceinline__ void phase_rwkv_scan(const Params& p, int l, const int tidx) {
;     ...
; #pragma unroll
;         for (int q = 0; q < TPW; q++) {
;           const int s = pw * TPW + q;
;           float wl = w0j + myT[q * 68 + j];
;           float al = a0j + myT[(TPW + q) * 68 + j];
;           float dec = __expf(-0.6065306597126334f * sigmoidf_(wl));
;           float av = sigmoidf_(al);
;           float kkr = uk[q] * kks;
;           float ss = wave_sum(kkr * kkr);
;           float kk = kkr * __builtin_amdgcn_rcpf(fmaxf(sqrtf(ss), 1e-12f));
;           float kd = uk[q] * (1.f + (av - 1.f) * kap);
;           float bt = wave_sum(ur[q] * kd * rkj);
;           float c1 = wave_sum(kk * av * ur[q]);
;           float c2 = wave_sum(kd * ur[q]);
;           nbw[s * 64 + j] = dec;
;           nbw[1 * VSZ + s * 64 + j] = kk * av;
;           nbw[2 * VSZ + s * 64 + j] = kd;
;           ((bf16_t*)(nbw + 3 * VSZ))[s * 128 + j] = f2bf(kk);
;           ((bf16_t*)(nbw + 3 * VSZ))[s * 128 + 64 + j] = f2bf(dec * ur[q]);
;           nbw[4 * VSZ + s * 64 + j] = uv[q];
;           if (lane == 1) *(float2*)(nbw + 6 * VSZ + 2 * s) = float2{c1, c2};
;           if (lane == 0) {
;             int tau = pc * RTC + s;
;             int t = dir ? (4095 - tau) : tau;
;             beta[(size_t)(b * SEQ + t) * 16 + h] = bt;
;           }
;         }
	v_pk_add_f32 v[2:3], v[2:3], v[54:55] op_sel_hi:[1,0]
	v_pk_add_f32 v[4:5], v[4:5], v[56:57] op_sel_hi:[1,0]
	v_pk_mul_f32 v[6:7], v[2:3], v[34:35] op_sel_hi:[1,0]
	v_pk_mul_f32 v[10:11], v[4:5], v[34:35] op_sel_hi:[1,0]
	v_exp_f32_e32 v6, v6
	v_exp_f32_e32 v7, v7
	v_exp_f32_e32 v10, v10
	v_exp_f32_e32 v11, v11
	v_pk_add_f32 v[6:7], v[6:7], v[50:51] op_sel:[0,1] op_sel_hi:[1,1]
	v_pk_add_f32 v[10:11], v[10:11], v[50:51] op_sel:[0,1] op_sel_hi:[1,1]
	v_rcp_f32_e32 v6, v6
	v_rcp_f32_e32 v7, v7
	v_rcp_f32_e32 v10, v10
	v_rcp_f32_e32 v11, v11
	v_pk_mul_f32 v[8:9], v[6:7], v[144:145] op_sel_hi:[1,0]
	v_exp_f32_e32 v8, v8
	v_exp_f32_e32 v9, v9
	v_mul_f32_e32 v153, v152, v8
	v_mov_b32_e32 v154, v153
	v_mul_f32_e32 v155, v153, v9
	v_rcp_f32_e32 v156, v154
	v_rcp_f32_e32 v157, v155
	v_pk_add_f32 v[14:15], v[10:11], v[146:147] op_sel_hi:[1,0]
	v_pk_fma_f32 v[14:15], v[14:15], v[50:51], v[50:51] op_sel:[0,0,1] op_sel_hi:[1,0,1]
	v_pk_mul_f32 v[16:17], v[134:135], v[14:15]
	v_pk_mul_f32 v[20:21], v[126:127], v[16:17]
	v_pk_mul_f32 v[22:23], v[20:21], v[52:53] op_sel_hi:[1,0]
	v_pk_mul_f32 v[24:25], v[12:13], v[10:11]
	v_pk_mul_f32 v[24:25], v[24:25], v[126:127]
	v_add_f32_dpp v18, v18, v18 quad_perm:[1,0,3,2] row_mask:0xf bank_mask:0xf
	v_add_f32_dpp v19, v19, v19 quad_perm:[1,0,3,2] row_mask:0xf bank_mask:0xf
	v_add_f32_dpp v22, v22, v22 quad_perm:[1,0,3,2] row_mask:0xf bank_mask:0xf
	v_add_f32_dpp v23, v23, v23 quad_perm:[1,0,3,2] row_mask:0xf bank_mask:0xf
	v_add_f32_dpp v24, v24, v24 quad_perm:[1,0,3,2] row_mask:0xf bank_mask:0xf
	v_add_f32_dpp v25, v25, v25 quad_perm:[1,0,3,2] row_mask:0xf bank_mask:0xf
	v_add_f32_dpp v20, v20, v20 quad_perm:[1,0,3,2] row_mask:0xf bank_mask:0xf
	v_add_f32_dpp v21, v21, v21 quad_perm:[1,0,3,2] row_mask:0xf bank_mask:0xf
	v_cndmask_b32_e64 v26, v18, v19, s[24:25]
	v_cndmask_b32_e64 v27, v22, v23, s[24:25]
	v_cndmask_b32_e64 v28, v24, v25, s[24:25]
	v_cndmask_b32_e64 v29, v20, v21, s[24:25]
	v_add_f32_dpp v26, v26, v26 quad_perm:[2,3,0,1] row_mask:0xf bank_mask:0xf
	v_add_f32_dpp v27, v27, v27 quad_perm:[2,3,0,1] row_mask:0xf bank_mask:0xf
	v_add_f32_dpp v28, v28, v28 quad_perm:[2,3,0,1] row_mask:0xf bank_mask:0xf
	v_add_f32_dpp v29, v29, v29 quad_perm:[2,3,0,1] row_mask:0xf bank_mask:0xf
	v_cndmask_b32_e64 v30, v26, v27, s[26:27]
	v_cndmask_b32_e64 v31, v28, v29, s[26:27]
	s_nop 0
	v_add_f32_dpp v30, v30, v30 row_ror:4 row_mask:0xf bank_mask:0xf
	v_add_f32_dpp v31, v31, v31 row_ror:4 row_mask:0xf bank_mask:0xf
	v_cndmask_b32_e64 v32, v30, v31, s[28:29]
	s_nop 1
	v_add_f32_dpp v32, v32, v32 row_ror:8 row_mask:0xf bank_mask:0xf
	v_mov_b32_e32 v33, v32
	s_nop 1
	v_permlane16_swap_b32 v33, v32
	v_add_f32_e32 v32, v33, v32
	v_mov_b32_e32 v33, v32
	s_nop 1
	v_permlane32_swap_b32 v33, v32
	v_add_f32_e32 v32, v33, v32
	s_nop 1
	v_mov_b32_dpp v246, v32 row_newbcast:0 row_mask:0xf bank_mask:0xf
	v_mov_b32_dpp v247, v32 row_newbcast:1 row_mask:0xf bank_mask:0xf
	v_max_f32_e32 v246, 0x179abe15, v246
	v_max_f32_e32 v247, 0x179abe15, v247
	v_rsq_f32_e32 v238, v246
	v_rsq_f32_e32 v239, v247
	s_nop 0
	v_pk_mul_f32 v[242:243], v[12:13], v[238:239]
	v_mul_f32_dpp v244, v32, v238 row_newbcast:4 row_mask:0xf bank_mask:0xf
	v_mul_f32_dpp v245, v32, v239 row_newbcast:5 row_mask:0xf bank_mask:0xf
	v_pk_mul_f32 v[6:7], v[242:243], v[10:11]
	v_pk_mul_f32 v[14:15], v[154:155], v[126:127]
	v_pk_mul_f32 v[242:243], v[242:243], v[152:153]
	v_pk_mul_f32 v[6:7], v[6:7], v[156:157] neg_lo:[0,1] neg_hi:[0,1]
	v_pk_mul_f32 v[16:17], v[16:17], v[156:157]
	v_cvt_pk_bf16_f32 v248, v242, v243
	v_cvt_pk_bf16_f32 v249, v14, v15
	ds_write_b32 v234, v155 offset:1792
	v_mov_b32_e32 v152, v155
	ds_write_b32 v234, v6 offset:9728
	ds_write_b32 v234, v16 offset:17920
	ds_write_b32 v234, v142 offset:34304
	ds_write_b32 v234, v7 offset:9984
	ds_write_b32 v234, v17 offset:18176
	ds_write_b32 v234, v143 offset:34560
	ds_write_b16 v235, v248 offset:1536
	ds_write_b16_d16_hi v235, v248 offset:1792
	ds_write_b16 v235, v249 offset:1664
	ds_write_b16_d16_hi v235, v249 offset:1920
	s_lshl_b32 s12, s0, 5
	s_lshl_b32 s13, s17, 3
	s_add_i32 s12, s12, s13
	s_add_i32 s12, s12, 6
	s_sub_i32 s67, 0xfff, s12
	s_cmp_eq_u32 s16, 0
	s_cselect_b32 s13, s12, s67
	s_add_i32 s13, s13, s5
	s_lshl_b32 s13, s13, 6
	s_add_u32 s72, s22, s13
	s_addc_u32 s73, s23, 0
	s_add_i32 s12, s12, 1
	s_sub_i32 s67, 0xfff, s12
	s_cmp_eq_u32 s16, 0
	s_cselect_b32 s13, s12, s67
	s_add_i32 s13, s13, s5
	s_lshl_b32 s13, s13, 6
	s_add_u32 s74, s22, s13
	s_addc_u32 s75, s23, 0
	s_mov_b64 exec, 1
	ds_write_b32 v236, v244 offset:49200
	ds_write_b32 v236, v245 offset:49208
	s_mov_b64 exec, 0x40
	ds_write_b32 v236, v32 offset:49204
	s_mov_b64 exec, 0x80
	ds_write_b32 v236, v32 offset:49212
	s_mov_b64 exec, 4
	global_store_dword v1, v32, s[72:73]
	s_mov_b64 exec, 8
	global_store_dword v1, v32, s[74:75]
	s_mov_b64 exec, -1

; __device__ __forceinline__ void phase_rwkv_scan(const Params& p, int l, const int tidx) {
;     ...
;       for (int s = 0; s < RTC; s++) {
;         const bf16x8 A0 = nA0, A1 = nA1;
;         const float wA[8] = {nw0.x, nw0.y, nw0.z, nw0.w, nw1.x, nw1.y, nw1.z, nw1.w};
;         const float wB[8] = {nw2.x, nw2.y, nw2.z, nw2.w, nw3.x, nw3.y, nw3.z, nw3.w};
;         const float kaA[8] = {nka0.x, nka0.y, nka0.z, nka0.w, nka1.x, nka1.y, nka1.z, nka1.w};
;         const float kaB[8] = {nka2.x, nka2.y, nka2.z, nka2.w, nka3.x, nka3.y, nka3.z, nka3.w};
;         const float kdA[8] = {nkd0.x, nkd0.y, nkd0.z, nkd0.w, nkd1.x, nkd1.y, nkd1.z, nkd1.w};
;         const float kdB[8] = {nkd2.x, nkd2.y, nkd2.z, nkd2.w, nkd3.x, nkd3.y, nkd3.z, nkd3.w};
;         const float v = nv;
;         float c1 = nc.x, c2 = nc.y;
;         asm volatile("" : "+v"(c1), "+v"(c2));
;         if (s + 1 < RTC) RW_LD(s + 1);
;         u32x4 pa = {pack2(Sa[0], Sa[1]), pack2(Sa[2], Sa[3]), pack2(Sa[4], Sa[5]), pack2(Sa[6], Sa[7])};
;         u32x4 pb = {pack2(Sb[0], Sb[1]), pack2(Sb[2], Sb[3]), pack2(Sb[4], Sb[5]), pack2(Sb[6], Sb[7])};
;         f32x4 acc = {0.f, 0.f, 0.f, 0.f};
;         acc = __builtin_amdgcn_mfma_f32_16x16x32_bf16(A0, __builtin_bit_cast(bf16x8, pa), acc, 0, 0, 0);
;         acc = __builtin_amdgcn_mfma_f32_16x16x32_bf16(A1, __builtin_bit_cast(bf16x8, pb), acc, 0, 0, 0);
;         float tA[8], tB[8];
; #pragma unroll
;         for (int c = 0; c < 8; c++) { tA[c] = Sa[c] * wA[c] + v * kdA[c]; tB[c] = Sb[c] * wB[c] + v * kdB[c]; }
;         const float sa = -acc[0];
;         const float yq = acc[1];
; #pragma unroll
;         for (int c = 0; c < 8; c++) { Sa[c] = tA[c] + sa * kaA[c]; Sb[c] = tB[c] + sa * kaB[c]; }
;         const float y = yq + sa * c1 + v * c2;
;         if (quad == 0) by[s * 64 + row] = y;
;       }
.Lrw_chunk:
	s_bitcmp1_b32 s0, 0
	s_cselect_b32 s10, 0xc100, 0
	v_add_u32_e32 v104, s10, v100
	v_add_u32_e32 v105, s10, v101
	v_add_u32_e32 v106, s10, v102
	v_add_u32_e32 v107, s10, v103
	v_mov_b32_e32 v108, s10
	ds_read_b128 v[40:43], v104 offset:0
	ds_read_b128 v[44:47], v104 offset:16
	ds_read_b32 v65, v105 offset:16384
	ds_read_b32 v66, v107 offset:0
	ds_read_b32 v48, v105 offset:8192
	ds_read_b64 v[68:69], v108 offset:49152
	v_cvt_pk_bf16_f32 v24, v8, v9
	v_cvt_pk_bf16_f32 v25, v10, v11
	v_cvt_pk_bf16_f32 v26, v12, v13
	v_cvt_pk_bf16_f32 v27, v14, v15
	v_cvt_pk_bf16_f32 v28, v16, v17
	v_cvt_pk_bf16_f32 v29, v18, v19
	s_waitcnt lgkmcnt(2)
	v_mfma_f32_16x16x32_bf16 v[32:35], v[40:43], v[24:27], 0
	v_cvt_pk_bf16_f32 v30, v20, v21
	v_cvt_pk_bf16_f32 v31, v22, v23
	v_fmac_f32_dpp v8, v65, v66 row_newbcast:0 row_mask:0xf bank_mask:0xf
	v_fmac_f32_dpp v9, v65, v66 row_newbcast:1 row_mask:0xf bank_mask:0xf
	v_mfma_f32_16x16x32_bf16 v[32:35], v[44:47], v[28:31], v[32:35]
	v_fmac_f32_dpp v10, v65, v66 row_newbcast:2 row_mask:0xf bank_mask:0xf
	v_fmac_f32_dpp v11, v65, v66 row_newbcast:3 row_mask:0xf bank_mask:0xf
	ds_read_b128 v[70:73], v104 offset:256
	v_fmac_f32_dpp v12, v65, v66 row_newbcast:4 row_mask:0xf bank_mask:0xf
	v_fmac_f32_dpp v13, v65, v66 row_newbcast:5 row_mask:0xf bank_mask:0xf
	ds_read_b128 v[74:77], v104 offset:272
	v_fmac_f32_dpp v14, v65, v66 row_newbcast:6 row_mask:0xf bank_mask:0xf
	v_fmac_f32_dpp v15, v65, v66 row_newbcast:7 row_mask:0xf bank_mask:0xf
	ds_read_b32 v95, v105 offset:16640
	v_fmac_f32_dpp v16, v65, v66 row_newbcast:8 row_mask:0xf bank_mask:0xf
	v_fmac_f32_dpp v17, v65, v66 row_newbcast:9 row_mask:0xf bank_mask:0xf
	ds_read_b32 v96, v107 offset:256
	v_fmac_f32_dpp v18, v65, v66 row_newbcast:10 row_mask:0xf bank_mask:0xf
	v_fmac_f32_dpp v19, v65, v66 row_newbcast:11 row_mask:0xf bank_mask:0xf
	ds_read_b32 v78, v105 offset:8448
	v_fmac_f32_dpp v20, v65, v66 row_newbcast:12 row_mask:0xf bank_mask:0xf
	v_fmac_f32_dpp v21, v65, v66 row_newbcast:13 row_mask:0xf bank_mask:0xf
	ds_read_b64 v[98:99], v108 offset:49160
	v_fmac_f32_dpp v22, v65, v66 row_newbcast:14 row_mask:0xf bank_mask:0xf
	v_fmac_f32_dpp v23, v65, v66 row_newbcast:15 row_mask:0xf bank_mask:0xf
	s_waitcnt lgkmcnt(6)
	v_fmac_f32_dpp v8, v48, v32 row_newbcast:0 row_mask:0xf bank_mask:0xf
	v_fmac_f32_dpp v9, v48, v32 row_newbcast:1 row_mask:0xf bank_mask:0xf
	v_fmac_f32_dpp v10, v48, v32 row_newbcast:2 row_mask:0xf bank_mask:0xf
	v_fmac_f32_dpp v11, v48, v32 row_newbcast:3 row_mask:0xf bank_mask:0xf
	v_fmac_f32_dpp v12, v48, v32 row_newbcast:4 row_mask:0xf bank_mask:0xf
	v_fmac_f32_dpp v13, v48, v32 row_newbcast:5 row_mask:0xf bank_mask:0xf
	v_fmac_f32_dpp v14, v48, v32 row_newbcast:6 row_mask:0xf bank_mask:0xf
	v_fmac_f32_dpp v15, v48, v32 row_newbcast:7 row_mask:0xf bank_mask:0xf
	v_fmac_f32_dpp v16, v48, v32 row_newbcast:8 row_mask:0xf bank_mask:0xf
	v_fmac_f32_dpp v17, v48, v32 row_newbcast:9 row_mask:0xf bank_mask:0xf
	v_fmac_f32_dpp v18, v48, v32 row_newbcast:10 row_mask:0xf bank_mask:0xf
	v_fmac_f32_dpp v19, v48, v32 row_newbcast:11 row_mask:0xf bank_mask:0xf
	v_fmac_f32_dpp v20, v48, v32 row_newbcast:12 row_mask:0xf bank_mask:0xf
	v_fmac_f32_dpp v21, v48, v32 row_newbcast:13 row_mask:0xf bank_mask:0xf
	v_fmac_f32_dpp v22, v48, v32 row_newbcast:14 row_mask:0xf bank_mask:0xf
	v_fmac_f32_dpp v23, v48, v32 row_newbcast:15 row_mask:0xf bank_mask:0xf
	v_fma_f32 v109, -v32, v68, v33
	v_fma_f32 v109, v66, v69, v109
	ds_write_b32 v107, v109 offset:8192
	v_cvt_pk_bf16_f32 v24, v8, v9
	v_cvt_pk_bf16_f32 v25, v10, v11
	v_cvt_pk_bf16_f32 v26, v12, v13
	v_cvt_pk_bf16_f32 v27, v14, v15
	v_cvt_pk_bf16_f32 v28, v16, v17
	v_cvt_pk_bf16_f32 v29, v18, v19
	s_waitcnt lgkmcnt(3)
	v_mfma_f32_16x16x32_bf16 v[32:35], v[70:73], v[24:27], 0
	v_cvt_pk_bf16_f32 v30, v20, v21
	v_cvt_pk_bf16_f32 v31, v22, v23
	v_fmac_f32_dpp v8, v95, v96 row_newbcast:0 row_mask:0xf bank_mask:0xf
	v_fmac_f32_dpp v9, v95, v96 row_newbcast:1 row_mask:0xf bank_mask:0xf
	v_mfma_f32_16x16x32_bf16 v[32:35], v[74:77], v[28:31], v[32:35]
	v_fmac_f32_dpp v10, v95, v96 row_newbcast:2 row_mask:0xf bank_mask:0xf
	v_fmac_f32_dpp v11, v95, v96 row_newbcast:3 row_mask:0xf bank_mask:0xf
	ds_read_b128 v[40:43], v104 offset:512
	v_fmac_f32_dpp v12, v95, v96 row_newbcast:4 row_mask:0xf bank_mask:0xf
	v_fmac_f32_dpp v13, v95, v96 row_newbcast:5 row_mask:0xf bank_mask:0xf
	ds_read_b128 v[44:47], v104 offset:528
	v_fmac_f32_dpp v14, v95, v96 row_newbcast:6 row_mask:0xf bank_mask:0xf
	v_fmac_f32_dpp v15, v95, v96 row_newbcast:7 row_mask:0xf bank_mask:0xf
	ds_read_b32 v65, v105 offset:16896
	v_fmac_f32_dpp v16, v95, v96 row_newbcast:8 row_mask:0xf bank_mask:0xf
	v_fmac_f32_dpp v17, v95, v96 row_newbcast:9 row_mask:0xf bank_mask:0xf
	ds_read_b32 v66, v107 offset:512
	v_fmac_f32_dpp v18, v95, v96 row_newbcast:10 row_mask:0xf bank_mask:0xf
	v_fmac_f32_dpp v19, v95, v96 row_newbcast:11 row_mask:0xf bank_mask:0xf
	ds_read_b32 v48, v105 offset:8704
	v_fmac_f32_dpp v20, v95, v96 row_newbcast:12 row_mask:0xf bank_mask:0xf
	v_fmac_f32_dpp v21, v95, v96 row_newbcast:13 row_mask:0xf bank_mask:0xf
	ds_read_b64 v[68:69], v108 offset:49168
	v_fmac_f32_dpp v22, v95, v96 row_newbcast:14 row_mask:0xf bank_mask:0xf
	v_fmac_f32_dpp v23, v95, v96 row_newbcast:15 row_mask:0xf bank_mask:0xf
	s_waitcnt lgkmcnt(7)
; __device__ __forceinline__ void phase_rwkv_scan(const Params& p, int l, const int tidx) {
;     ...
;       for (int s = 0; s < RTC; s++) {
;         const bf16x8 A0 = nA0, A1 = nA1;
;         const float wA[8] = {nw0.x, nw0.y, nw0.z, nw0.w, nw1.x, nw1.y, nw1.z, nw1.w};
;         const float wB[8] = {nw2.x, nw2.y, nw2.z, nw2.w, nw3.x, nw3.y, nw3.z, nw3.w};
;         const float kaA[8] = {nka0.x, nka0.y, nka0.z, nka0.w, nka1.x, nka1.y, nka1.z, nka1.w};
;         const float kaB[8] = {nka2.x, nka2.y, nka2.z, nka2.w, nka3.x, nka3.y, nka3.z, nka3.w};
;         const float kdA[8] = {nkd0.x, nkd0.y, nkd0.z, nkd0.w, nkd1.x, nkd1.y, nkd1.z, nkd1.w};
;         const float kdB[8] = {nkd2.x, nkd2.y, nkd2.z, nkd2.w, nkd3.x, nkd3.y, nkd3.z, nkd3.w};
;         const float v = nv;
;         float c1 = nc.x, c2 = nc.y;
;         asm volatile("" : "+v"(c1), "+v"(c2));
;         if (s + 1 < RTC) RW_LD(s + 1);
;         u32x4 pa = {pack2(Sa[0], Sa[1]), pack2(Sa[2], Sa[3]), pack2(Sa[4], Sa[5]), pack2(Sa[6], Sa[7])};
;         u32x4 pb = {pack2(Sb[0], Sb[1]), pack2(Sb[2], Sb[3]), pack2(Sb[4], Sb[5]), pack2(Sb[6], Sb[7])};
;         f32x4 acc = {0.f, 0.f, 0.f, 0.f};
;         acc = __builtin_amdgcn_mfma_f32_16x16x32_bf16(A0, __builtin_bit_cast(bf16x8, pa), acc, 0, 0, 0);
;         acc = __builtin_amdgcn_mfma_f32_16x16x32_bf16(A1, __builtin_bit_cast(bf16x8, pb), acc, 0, 0, 0);
;         float tA[8], tB[8];
; #pragma unroll
;         for (int c = 0; c < 8; c++) { tA[c] = Sa[c] * wA[c] + v * kdA[c]; tB[c] = Sb[c] * wB[c] + v * kdB[c]; }
;         const float sa = -acc[0];
;         const float yq = acc[1];
; #pragma unroll
;         for (int c = 0; c < 8; c++) { Sa[c] = tA[c] + sa * kaA[c]; Sb[c] = tB[c] + sa * kaB[c]; }
;         const float y = yq + sa * c1 + v * c2;
;         if (quad == 0) by[s * 64 + row] = y;
;       }
	v_fmac_f32_dpp v8, v78, v32 row_newbcast:0 row_mask:0xf bank_mask:0xf
	v_fmac_f32_dpp v9, v78, v32 row_newbcast:1 row_mask:0xf bank_mask:0xf
	v_fmac_f32_dpp v10, v78, v32 row_newbcast:2 row_mask:0xf bank_mask:0xf
	v_fmac_f32_dpp v11, v78, v32 row_newbcast:3 row_mask:0xf bank_mask:0xf
	v_fmac_f32_dpp v12, v78, v32 row_newbcast:4 row_mask:0xf bank_mask:0xf
	v_fmac_f32_dpp v13, v78, v32 row_newbcast:5 row_mask:0xf bank_mask:0xf
	v_fmac_f32_dpp v14, v78, v32 row_newbcast:6 row_mask:0xf bank_mask:0xf
	v_fmac_f32_dpp v15, v78, v32 row_newbcast:7 row_mask:0xf bank_mask:0xf
	v_fmac_f32_dpp v16, v78, v32 row_newbcast:8 row_mask:0xf bank_mask:0xf
	v_fmac_f32_dpp v17, v78, v32 row_newbcast:9 row_mask:0xf bank_mask:0xf
	v_fmac_f32_dpp v18, v78, v32 row_newbcast:10 row_mask:0xf bank_mask:0xf
	v_fmac_f32_dpp v19, v78, v32 row_newbcast:11 row_mask:0xf bank_mask:0xf
	v_fmac_f32_dpp v20, v78, v32 row_newbcast:12 row_mask:0xf bank_mask:0xf
	v_fmac_f32_dpp v21, v78, v32 row_newbcast:13 row_mask:0xf bank_mask:0xf
	v_fmac_f32_dpp v22, v78, v32 row_newbcast:14 row_mask:0xf bank_mask:0xf
	v_fmac_f32_dpp v23, v78, v32 row_newbcast:15 row_mask:0xf bank_mask:0xf
	v_fma_f32 v109, -v32, v98, v33
	v_fma_f32 v109, v96, v99, v109
	ds_write_b32 v107, v109 offset:8448
	v_cvt_pk_bf16_f32 v24, v8, v9
	v_cvt_pk_bf16_f32 v25, v10, v11
	v_cvt_pk_bf16_f32 v26, v12, v13
	v_cvt_pk_bf16_f32 v27, v14, v15
	v_cvt_pk_bf16_f32 v28, v16, v17
	v_cvt_pk_bf16_f32 v29, v18, v19
	s_waitcnt lgkmcnt(3)
	v_mfma_f32_16x16x32_bf16 v[32:35], v[40:43], v[24:27], 0
	v_cvt_pk_bf16_f32 v30, v20, v21
	v_cvt_pk_bf16_f32 v31, v22, v23
	v_fmac_f32_dpp v8, v65, v66 row_newbcast:0 row_mask:0xf bank_mask:0xf
	v_fmac_f32_dpp v9, v65, v66 row_newbcast:1 row_mask:0xf bank_mask:0xf
	v_mfma_f32_16x16x32_bf16 v[32:35], v[44:47], v[28:31], v[32:35]
	v_fmac_f32_dpp v10, v65, v66 row_newbcast:2 row_mask:0xf bank_mask:0xf
	v_fmac_f32_dpp v11, v65, v66 row_newbcast:3 row_mask:0xf bank_mask:0xf
	ds_read_b128 v[70:73], v104 offset:768
	v_fmac_f32_dpp v12, v65, v66 row_newbcast:4 row_mask:0xf bank_mask:0xf
	v_fmac_f32_dpp v13, v65, v66 row_newbcast:5 row_mask:0xf bank_mask:0xf
	ds_read_b128 v[74:77], v104 offset:784
	v_fmac_f32_dpp v14, v65, v66 row_newbcast:6 row_mask:0xf bank_mask:0xf
	v_fmac_f32_dpp v15, v65, v66 row_newbcast:7 row_mask:0xf bank_mask:0xf
	ds_read_b32 v95, v105 offset:17152
	v_fmac_f32_dpp v16, v65, v66 row_newbcast:8 row_mask:0xf bank_mask:0xf
	v_fmac_f32_dpp v17, v65, v66 row_newbcast:9 row_mask:0xf bank_mask:0xf
	ds_read_b32 v96, v107 offset:768
	v_fmac_f32_dpp v18, v65, v66 row_newbcast:10 row_mask:0xf bank_mask:0xf
	v_fmac_f32_dpp v19, v65, v66 row_newbcast:11 row_mask:0xf bank_mask:0xf
	ds_read_b32 v78, v105 offset:8960
	v_fmac_f32_dpp v20, v65, v66 row_newbcast:12 row_mask:0xf bank_mask:0xf
	v_fmac_f32_dpp v21, v65, v66 row_newbcast:13 row_mask:0xf bank_mask:0xf
	ds_read_b64 v[98:99], v108 offset:49176
	v_fmac_f32_dpp v22, v65, v66 row_newbcast:14 row_mask:0xf bank_mask:0xf
	v_fmac_f32_dpp v23, v65, v66 row_newbcast:15 row_mask:0xf bank_mask:0xf
	s_waitcnt lgkmcnt(7)
	v_fmac_f32_dpp v8, v48, v32 row_newbcast:0 row_mask:0xf bank_mask:0xf
	v_fmac_f32_dpp v9, v48, v32 row_newbcast:1 row_mask:0xf bank_mask:0xf
	v_fmac_f32_dpp v10, v48, v32 row_newbcast:2 row_mask:0xf bank_mask:0xf
	v_fmac_f32_dpp v11, v48, v32 row_newbcast:3 row_mask:0xf bank_mask:0xf
	v_fmac_f32_dpp v12, v48, v32 row_newbcast:4 row_mask:0xf bank_mask:0xf
	v_fmac_f32_dpp v13, v48, v32 row_newbcast:5 row_mask:0xf bank_mask:0xf
	v_fmac_f32_dpp v14, v48, v32 row_newbcast:6 row_mask:0xf bank_mask:0xf
	v_fmac_f32_dpp v15, v48, v32 row_newbcast:7 row_mask:0xf bank_mask:0xf
	v_fmac_f32_dpp v16, v48, v32 row_newbcast:8 row_mask:0xf bank_mask:0xf
	v_fmac_f32_dpp v17, v48, v32 row_newbcast:9 row_mask:0xf bank_mask:0xf
	v_fmac_f32_dpp v18, v48, v32 row_newbcast:10 row_mask:0xf bank_mask:0xf
	v_fmac_f32_dpp v19, v48, v32 row_newbcast:11 row_mask:0xf bank_mask:0xf
	v_fmac_f32_dpp v20, v48, v32 row_newbcast:12 row_mask:0xf bank_mask:0xf
	v_fmac_f32_dpp v21, v48, v32 row_newbcast:13 row_mask:0xf bank_mask:0xf
	v_fmac_f32_dpp v22, v48, v32 row_newbcast:14 row_mask:0xf bank_mask:0xf
	v_fmac_f32_dpp v23, v48, v32 row_newbcast:15 row_mask:0xf bank_mask:0xf
	v_fma_f32 v109, -v32, v68, v33
	v_fma_f32 v109, v66, v69, v109
	ds_write_b32 v107, v109 offset:8704
	v_cvt_pk_bf16_f32 v24, v8, v9
	v_cvt_pk_bf16_f32 v25, v10, v11
	v_cvt_pk_bf16_f32 v26, v12, v13
	v_cvt_pk_bf16_f32 v27, v14, v15
	v_cvt_pk_bf16_f32 v28, v16, v17
	v_cvt_pk_bf16_f32 v29, v18, v19
	s_waitcnt lgkmcnt(3)
	v_mfma_f32_16x16x32_bf16 v[32:35], v[70:73], v[24:27], 0
	v_cvt_pk_bf16_f32 v30, v20, v21
	v_cvt_pk_bf16_f32 v31, v22, v23
	v_fmac_f32_dpp v8, v95, v96 row_newbcast:0 row_mask:0xf bank_mask:0xf
	v_fmac_f32_dpp v9, v95, v96 row_newbcast:1 row_mask:0xf bank_mask:0xf
	v_mfma_f32_16x16x32_bf16 v[32:35], v[74:77], v[28:31], v[32:35]
	v_fmac_f32_dpp v10, v95, v96 row_newbcast:2 row_mask:0xf bank_mask:0xf
	v_fmac_f32_dpp v11, v95, v96 row_newbcast:3 row_mask:0xf bank_mask:0xf
	ds_read_b128 v[40:43], v104 offset:1024
	v_fmac_f32_dpp v12, v95, v96 row_newbcast:4 row_mask:0xf bank_mask:0xf
	v_fmac_f32_dpp v13, v95, v96 row_newbcast:5 row_mask:0xf bank_mask:0xf
	ds_read_b128 v[44:47], v104 offset:1040
	v_fmac_f32_dpp v14, v95, v96 row_newbcast:6 row_mask:0xf bank_mask:0xf
	v_fmac_f32_dpp v15, v95, v96 row_newbcast:7 row_mask:0xf bank_mask:0xf
	ds_read_b32 v65, v105 offset:17408
	v_fmac_f32_dpp v16, v95, v96 row_newbcast:8 row_mask:0xf bank_mask:0xf
	v_fmac_f32_dpp v17, v95, v96 row_newbcast:9 row_mask:0xf bank_mask:0xf
	ds_read_b32 v66, v107 offset:1024
	v_fmac_f32_dpp v18, v95, v96 row_newbcast:10 row_mask:0xf bank_mask:0xf
	v_fmac_f32_dpp v19, v95, v96 row_newbcast:11 row_mask:0xf bank_mask:0xf
	ds_read_b32 v48, v105 offset:9216
	v_fmac_f32_dpp v20, v95, v96 row_newbcast:12 row_mask:0xf bank_mask:0xf
	v_fmac_f32_dpp v21, v95, v96 row_newbcast:13 row_mask:0xf bank_mask:0xf
	ds_read_b64 v[68:69], v108 offset:49184
	v_fmac_f32_dpp v22, v95, v96 row_newbcast:14 row_mask:0xf bank_mask:0xf
	v_fmac_f32_dpp v23, v95, v96 row_newbcast:15 row_mask:0xf bank_mask:0xf
	s_waitcnt lgkmcnt(7)
; __device__ __forceinline__ void phase_rwkv_scan(const Params& p, int l, const int tidx) {
;     ...
;       for (int s = 0; s < RTC; s++) {
;         const bf16x8 A0 = nA0, A1 = nA1;
;         const float wA[8] = {nw0.x, nw0.y, nw0.z, nw0.w, nw1.x, nw1.y, nw1.z, nw1.w};
;         const float wB[8] = {nw2.x, nw2.y, nw2.z, nw2.w, nw3.x, nw3.y, nw3.z, nw3.w};
;         const float kaA[8] = {nka0.x, nka0.y, nka0.z, nka0.w, nka1.x, nka1.y, nka1.z, nka1.w};
;         const float kaB[8] = {nka2.x, nka2.y, nka2.z, nka2.w, nka3.x, nka3.y, nka3.z, nka3.w};
;         const float kdA[8] = {nkd0.x, nkd0.y, nkd0.z, nkd0.w, nkd1.x, nkd1.y, nkd1.z, nkd1.w};
;         const float kdB[8] = {nkd2.x, nkd2.y, nkd2.z, nkd2.w, nkd3.x, nkd3.y, nkd3.z, nkd3.w};
;         const float v = nv;
;         float c1 = nc.x, c2 = nc.y;
;         asm volatile("" : "+v"(c1), "+v"(c2));
;         if (s + 1 < RTC) RW_LD(s + 1);
;         u32x4 pa = {pack2(Sa[0], Sa[1]), pack2(Sa[2], Sa[3]), pack2(Sa[4], Sa[5]), pack2(Sa[6], Sa[7])};
;         u32x4 pb = {pack2(Sb[0], Sb[1]), pack2(Sb[2], Sb[3]), pack2(Sb[4], Sb[5]), pack2(Sb[6], Sb[7])};
;         f32x4 acc = {0.f, 0.f, 0.f, 0.f};
;         acc = __builtin_amdgcn_mfma_f32_16x16x32_bf16(A0, __builtin_bit_cast(bf16x8, pa), acc, 0, 0, 0);
;         acc = __builtin_amdgcn_mfma_f32_16x16x32_bf16(A1, __builtin_bit_cast(bf16x8, pb), acc, 0, 0, 0);
;         float tA[8], tB[8];
; #pragma unroll
;         for (int c = 0; c < 8; c++) { tA[c] = Sa[c] * wA[c] + v * kdA[c]; tB[c] = Sb[c] * wB[c] + v * kdB[c]; }
;         const float sa = -acc[0];
;         const float yq = acc[1];
; #pragma unroll
;         for (int c = 0; c < 8; c++) { Sa[c] = tA[c] + sa * kaA[c]; Sb[c] = tB[c] + sa * kaB[c]; }
;         const float y = yq + sa * c1 + v * c2;
;         if (quad == 0) by[s * 64 + row] = y;
;       }
	v_fmac_f32_dpp v8, v78, v32 row_newbcast:0 row_mask:0xf bank_mask:0xf
	v_fmac_f32_dpp v9, v78, v32 row_newbcast:1 row_mask:0xf bank_mask:0xf
	v_fmac_f32_dpp v10, v78, v32 row_newbcast:2 row_mask:0xf bank_mask:0xf
	v_fmac_f32_dpp v11, v78, v32 row_newbcast:3 row_mask:0xf bank_mask:0xf
	v_fmac_f32_dpp v12, v78, v32 row_newbcast:4 row_mask:0xf bank_mask:0xf
	v_fmac_f32_dpp v13, v78, v32 row_newbcast:5 row_mask:0xf bank_mask:0xf
	v_fmac_f32_dpp v14, v78, v32 row_newbcast:6 row_mask:0xf bank_mask:0xf
	v_fmac_f32_dpp v15, v78, v32 row_newbcast:7 row_mask:0xf bank_mask:0xf
	v_fmac_f32_dpp v16, v78, v32 row_newbcast:8 row_mask:0xf bank_mask:0xf
	v_fmac_f32_dpp v17, v78, v32 row_newbcast:9 row_mask:0xf bank_mask:0xf
	v_fmac_f32_dpp v18, v78, v32 row_newbcast:10 row_mask:0xf bank_mask:0xf
	v_fmac_f32_dpp v19, v78, v32 row_newbcast:11 row_mask:0xf bank_mask:0xf
	v_fmac_f32_dpp v20, v78, v32 row_newbcast:12 row_mask:0xf bank_mask:0xf
	v_fmac_f32_dpp v21, v78, v32 row_newbcast:13 row_mask:0xf bank_mask:0xf
	v_fmac_f32_dpp v22, v78, v32 row_newbcast:14 row_mask:0xf bank_mask:0xf
	v_fmac_f32_dpp v23, v78, v32 row_newbcast:15 row_mask:0xf bank_mask:0xf
	v_fma_f32 v109, -v32, v98, v33
	v_fma_f32 v109, v96, v99, v109
	ds_write_b32 v107, v109 offset:8960
	v_cvt_pk_bf16_f32 v24, v8, v9
	v_cvt_pk_bf16_f32 v25, v10, v11
	v_cvt_pk_bf16_f32 v26, v12, v13
	v_cvt_pk_bf16_f32 v27, v14, v15
	v_cvt_pk_bf16_f32 v28, v16, v17
	v_cvt_pk_bf16_f32 v29, v18, v19
	s_waitcnt lgkmcnt(3)
	v_mfma_f32_16x16x32_bf16 v[32:35], v[40:43], v[24:27], 0
	v_cvt_pk_bf16_f32 v30, v20, v21
	v_cvt_pk_bf16_f32 v31, v22, v23
	v_fmac_f32_dpp v8, v65, v66 row_newbcast:0 row_mask:0xf bank_mask:0xf
	v_fmac_f32_dpp v9, v65, v66 row_newbcast:1 row_mask:0xf bank_mask:0xf
	v_mfma_f32_16x16x32_bf16 v[32:35], v[44:47], v[28:31], v[32:35]
	v_fmac_f32_dpp v10, v65, v66 row_newbcast:2 row_mask:0xf bank_mask:0xf
	v_fmac_f32_dpp v11, v65, v66 row_newbcast:3 row_mask:0xf bank_mask:0xf
	ds_read_b128 v[70:73], v104 offset:1280
	v_fmac_f32_dpp v12, v65, v66 row_newbcast:4 row_mask:0xf bank_mask:0xf
	v_fmac_f32_dpp v13, v65, v66 row_newbcast:5 row_mask:0xf bank_mask:0xf
	ds_read_b128 v[74:77], v104 offset:1296
	v_fmac_f32_dpp v14, v65, v66 row_newbcast:6 row_mask:0xf bank_mask:0xf
	v_fmac_f32_dpp v15, v65, v66 row_newbcast:7 row_mask:0xf bank_mask:0xf
	ds_read_b32 v95, v105 offset:17664
	v_fmac_f32_dpp v16, v65, v66 row_newbcast:8 row_mask:0xf bank_mask:0xf
	v_fmac_f32_dpp v17, v65, v66 row_newbcast:9 row_mask:0xf bank_mask:0xf
	ds_read_b32 v96, v107 offset:1280
	v_fmac_f32_dpp v18, v65, v66 row_newbcast:10 row_mask:0xf bank_mask:0xf
	v_fmac_f32_dpp v19, v65, v66 row_newbcast:11 row_mask:0xf bank_mask:0xf
	ds_read_b32 v78, v105 offset:9472
	v_fmac_f32_dpp v20, v65, v66 row_newbcast:12 row_mask:0xf bank_mask:0xf
	v_fmac_f32_dpp v21, v65, v66 row_newbcast:13 row_mask:0xf bank_mask:0xf
	ds_read_b64 v[98:99], v108 offset:49192
	v_fmac_f32_dpp v22, v65, v66 row_newbcast:14 row_mask:0xf bank_mask:0xf
	v_fmac_f32_dpp v23, v65, v66 row_newbcast:15 row_mask:0xf bank_mask:0xf
	s_waitcnt lgkmcnt(7)
	v_fmac_f32_dpp v8, v48, v32 row_newbcast:0 row_mask:0xf bank_mask:0xf
	v_fmac_f32_dpp v9, v48, v32 row_newbcast:1 row_mask:0xf bank_mask:0xf
	v_fmac_f32_dpp v10, v48, v32 row_newbcast:2 row_mask:0xf bank_mask:0xf
	v_fmac_f32_dpp v11, v48, v32 row_newbcast:3 row_mask:0xf bank_mask:0xf
	v_fmac_f32_dpp v12, v48, v32 row_newbcast:4 row_mask:0xf bank_mask:0xf
	v_fmac_f32_dpp v13, v48, v32 row_newbcast:5 row_mask:0xf bank_mask:0xf
	v_fmac_f32_dpp v14, v48, v32 row_newbcast:6 row_mask:0xf bank_mask:0xf
	v_fmac_f32_dpp v15, v48, v32 row_newbcast:7 row_mask:0xf bank_mask:0xf
	v_fmac_f32_dpp v16, v48, v32 row_newbcast:8 row_mask:0xf bank_mask:0xf
	v_fmac_f32_dpp v17, v48, v32 row_newbcast:9 row_mask:0xf bank_mask:0xf
	v_fmac_f32_dpp v18, v48, v32 row_newbcast:10 row_mask:0xf bank_mask:0xf
	v_fmac_f32_dpp v19, v48, v32 row_newbcast:11 row_mask:0xf bank_mask:0xf
	v_fmac_f32_dpp v20, v48, v32 row_newbcast:12 row_mask:0xf bank_mask:0xf
	v_fmac_f32_dpp v21, v48, v32 row_newbcast:13 row_mask:0xf bank_mask:0xf
	v_fmac_f32_dpp v22, v48, v32 row_newbcast:14 row_mask:0xf bank_mask:0xf
	v_fmac_f32_dpp v23, v48, v32 row_newbcast:15 row_mask:0xf bank_mask:0xf
	v_fma_f32 v109, -v32, v68, v33
	v_fma_f32 v109, v66, v69, v109
	ds_write_b32 v107, v109 offset:9216
	v_cvt_pk_bf16_f32 v24, v8, v9
	v_cvt_pk_bf16_f32 v25, v10, v11
	v_cvt_pk_bf16_f32 v26, v12, v13
	v_cvt_pk_bf16_f32 v27, v14, v15
	v_cvt_pk_bf16_f32 v28, v16, v17
	v_cvt_pk_bf16_f32 v29, v18, v19
	s_waitcnt lgkmcnt(3)
	v_mfma_f32_16x16x32_bf16 v[32:35], v[70:73], v[24:27], 0
	v_cvt_pk_bf16_f32 v30, v20, v21
	v_cvt_pk_bf16_f32 v31, v22, v23
	v_fmac_f32_dpp v8, v95, v96 row_newbcast:0 row_mask:0xf bank_mask:0xf
	v_fmac_f32_dpp v9, v95, v96 row_newbcast:1 row_mask:0xf bank_mask:0xf
	v_mfma_f32_16x16x32_bf16 v[32:35], v[74:77], v[28:31], v[32:35]
	v_fmac_f32_dpp v10, v95, v96 row_newbcast:2 row_mask:0xf bank_mask:0xf
	v_fmac_f32_dpp v11, v95, v96 row_newbcast:3 row_mask:0xf bank_mask:0xf
	ds_read_b128 v[40:43], v104 offset:1536
	v_fmac_f32_dpp v12, v95, v96 row_newbcast:4 row_mask:0xf bank_mask:0xf
	v_fmac_f32_dpp v13, v95, v96 row_newbcast:5 row_mask:0xf bank_mask:0xf
	ds_read_b128 v[44:47], v104 offset:1552
	v_fmac_f32_dpp v14, v95, v96 row_newbcast:6 row_mask:0xf bank_mask:0xf
	v_fmac_f32_dpp v15, v95, v96 row_newbcast:7 row_mask:0xf bank_mask:0xf
	ds_read_b32 v65, v105 offset:17920
	v_fmac_f32_dpp v16, v95, v96 row_newbcast:8 row_mask:0xf bank_mask:0xf
	v_fmac_f32_dpp v17, v95, v96 row_newbcast:9 row_mask:0xf bank_mask:0xf
	ds_read_b32 v66, v107 offset:1536
	v_fmac_f32_dpp v18, v95, v96 row_newbcast:10 row_mask:0xf bank_mask:0xf
	v_fmac_f32_dpp v19, v95, v96 row_newbcast:11 row_mask:0xf bank_mask:0xf
	ds_read_b32 v48, v105 offset:9728
	v_fmac_f32_dpp v20, v95, v96 row_newbcast:12 row_mask:0xf bank_mask:0xf
	v_fmac_f32_dpp v21, v95, v96 row_newbcast:13 row_mask:0xf bank_mask:0xf
	ds_read_b64 v[68:69], v108 offset:49200
	v_fmac_f32_dpp v22, v95, v96 row_newbcast:14 row_mask:0xf bank_mask:0xf
	v_fmac_f32_dpp v23, v95, v96 row_newbcast:15 row_mask:0xf bank_mask:0xf
	s_waitcnt lgkmcnt(7)
; __device__ __forceinline__ void phase_rwkv_scan(const Params& p, int l, const int tidx) {
;     ...
;       for (int s = 0; s < RTC; s++) {
;         const bf16x8 A0 = nA0, A1 = nA1;
;         const float wA[8] = {nw0.x, nw0.y, nw0.z, nw0.w, nw1.x, nw1.y, nw1.z, nw1.w};
;         const float wB[8] = {nw2.x, nw2.y, nw2.z, nw2.w, nw3.x, nw3.y, nw3.z, nw3.w};
;         const float kaA[8] = {nka0.x, nka0.y, nka0.z, nka0.w, nka1.x, nka1.y, nka1.z, nka1.w};
;         const float kaB[8] = {nka2.x, nka2.y, nka2.z, nka2.w, nka3.x, nka3.y, nka3.z, nka3.w};
;         const float kdA[8] = {nkd0.x, nkd0.y, nkd0.z, nkd0.w, nkd1.x, nkd1.y, nkd1.z, nkd1.w};
;         const float kdB[8] = {nkd2.x, nkd2.y, nkd2.z, nkd2.w, nkd3.x, nkd3.y, nkd3.z, nkd3.w};
;         const float v = nv;
;         float c1 = nc.x, c2 = nc.y;
;         asm volatile("" : "+v"(c1), "+v"(c2));
;         if (s + 1 < RTC) RW_LD(s + 1);
;         u32x4 pa = {pack2(Sa[0], Sa[1]), pack2(Sa[2], Sa[3]), pack2(Sa[4], Sa[5]), pack2(Sa[6], Sa[7])};
;         u32x4 pb = {pack2(Sb[0], Sb[1]), pack2(Sb[2], Sb[3]), pack2(Sb[4], Sb[5]), pack2(Sb[6], Sb[7])};
;         f32x4 acc = {0.f, 0.f, 0.f, 0.f};
;         acc = __builtin_amdgcn_mfma_f32_16x16x32_bf16(A0, __builtin_bit_cast(bf16x8, pa), acc, 0, 0, 0);
;         acc = __builtin_amdgcn_mfma_f32_16x16x32_bf16(A1, __builtin_bit_cast(bf16x8, pb), acc, 0, 0, 0);
;         float tA[8], tB[8];
; #pragma unroll
;         for (int c = 0; c < 8; c++) { tA[c] = Sa[c] * wA[c] + v * kdA[c]; tB[c] = Sb[c] * wB[c] + v * kdB[c]; }
;         const float sa = -acc[0];
;         const float yq = acc[1];
; #pragma unroll
;         for (int c = 0; c < 8; c++) { Sa[c] = tA[c] + sa * kaA[c]; Sb[c] = tB[c] + sa * kaB[c]; }
;         const float y = yq + sa * c1 + v * c2;
;         if (quad == 0) by[s * 64 + row] = y;
;       }
	v_fmac_f32_dpp v8, v78, v32 row_newbcast:0 row_mask:0xf bank_mask:0xf
	v_fmac_f32_dpp v9, v78, v32 row_newbcast:1 row_mask:0xf bank_mask:0xf
	v_fmac_f32_dpp v10, v78, v32 row_newbcast:2 row_mask:0xf bank_mask:0xf
	v_fmac_f32_dpp v11, v78, v32 row_newbcast:3 row_mask:0xf bank_mask:0xf
	v_fmac_f32_dpp v12, v78, v32 row_newbcast:4 row_mask:0xf bank_mask:0xf
	v_fmac_f32_dpp v13, v78, v32 row_newbcast:5 row_mask:0xf bank_mask:0xf
	v_fmac_f32_dpp v14, v78, v32 row_newbcast:6 row_mask:0xf bank_mask:0xf
	v_fmac_f32_dpp v15, v78, v32 row_newbcast:7 row_mask:0xf bank_mask:0xf
	v_fmac_f32_dpp v16, v78, v32 row_newbcast:8 row_mask:0xf bank_mask:0xf
	v_fmac_f32_dpp v17, v78, v32 row_newbcast:9 row_mask:0xf bank_mask:0xf
	v_fmac_f32_dpp v18, v78, v32 row_newbcast:10 row_mask:0xf bank_mask:0xf
	v_fmac_f32_dpp v19, v78, v32 row_newbcast:11 row_mask:0xf bank_mask:0xf
	v_fmac_f32_dpp v20, v78, v32 row_newbcast:12 row_mask:0xf bank_mask:0xf
	v_fmac_f32_dpp v21, v78, v32 row_newbcast:13 row_mask:0xf bank_mask:0xf
	v_fmac_f32_dpp v22, v78, v32 row_newbcast:14 row_mask:0xf bank_mask:0xf
	v_fmac_f32_dpp v23, v78, v32 row_newbcast:15 row_mask:0xf bank_mask:0xf
	v_fma_f32 v109, -v32, v98, v33
	v_fma_f32 v109, v96, v99, v109
	ds_write_b32 v107, v109 offset:9472
	v_cvt_pk_bf16_f32 v24, v8, v9
	v_cvt_pk_bf16_f32 v25, v10, v11
	v_cvt_pk_bf16_f32 v26, v12, v13
	v_cvt_pk_bf16_f32 v27, v14, v15
	v_cvt_pk_bf16_f32 v28, v16, v17
	v_cvt_pk_bf16_f32 v29, v18, v19
	s_waitcnt lgkmcnt(3)
	v_mfma_f32_16x16x32_bf16 v[32:35], v[40:43], v[24:27], 0
	v_cvt_pk_bf16_f32 v30, v20, v21
	v_cvt_pk_bf16_f32 v31, v22, v23
	v_fmac_f32_dpp v8, v65, v66 row_newbcast:0 row_mask:0xf bank_mask:0xf
	v_fmac_f32_dpp v9, v65, v66 row_newbcast:1 row_mask:0xf bank_mask:0xf
	v_mfma_f32_16x16x32_bf16 v[32:35], v[44:47], v[28:31], v[32:35]
	v_fmac_f32_dpp v10, v65, v66 row_newbcast:2 row_mask:0xf bank_mask:0xf
	v_fmac_f32_dpp v11, v65, v66 row_newbcast:3 row_mask:0xf bank_mask:0xf
	ds_read_b128 v[70:73], v104 offset:1792
	v_fmac_f32_dpp v12, v65, v66 row_newbcast:4 row_mask:0xf bank_mask:0xf
	v_fmac_f32_dpp v13, v65, v66 row_newbcast:5 row_mask:0xf bank_mask:0xf
	ds_read_b128 v[74:77], v104 offset:1808
	v_fmac_f32_dpp v14, v65, v66 row_newbcast:6 row_mask:0xf bank_mask:0xf
	v_fmac_f32_dpp v15, v65, v66 row_newbcast:7 row_mask:0xf bank_mask:0xf
	ds_read_b32 v95, v105 offset:18176
	v_fmac_f32_dpp v16, v65, v66 row_newbcast:8 row_mask:0xf bank_mask:0xf
	v_fmac_f32_dpp v17, v65, v66 row_newbcast:9 row_mask:0xf bank_mask:0xf
	ds_read_b32 v96, v107 offset:1792
	v_fmac_f32_dpp v18, v65, v66 row_newbcast:10 row_mask:0xf bank_mask:0xf
	v_fmac_f32_dpp v19, v65, v66 row_newbcast:11 row_mask:0xf bank_mask:0xf
	ds_read_b32 v94, v105 offset:1792
	v_fmac_f32_dpp v20, v65, v66 row_newbcast:12 row_mask:0xf bank_mask:0xf
	v_fmac_f32_dpp v21, v65, v66 row_newbcast:13 row_mask:0xf bank_mask:0xf
	ds_read_b32 v78, v105 offset:9984
	v_fmac_f32_dpp v22, v65, v66 row_newbcast:14 row_mask:0xf bank_mask:0xf
	v_fmac_f32_dpp v23, v65, v66 row_newbcast:15 row_mask:0xf bank_mask:0xf
	ds_read_b64 v[98:99], v108 offset:49208
	s_waitcnt lgkmcnt(8)
	v_fmac_f32_dpp v8, v48, v32 row_newbcast:0 row_mask:0xf bank_mask:0xf
	v_fmac_f32_dpp v9, v48, v32 row_newbcast:1 row_mask:0xf bank_mask:0xf
	v_fmac_f32_dpp v10, v48, v32 row_newbcast:2 row_mask:0xf bank_mask:0xf
	v_fmac_f32_dpp v11, v48, v32 row_newbcast:3 row_mask:0xf bank_mask:0xf
	v_fmac_f32_dpp v12, v48, v32 row_newbcast:4 row_mask:0xf bank_mask:0xf
	v_fmac_f32_dpp v13, v48, v32 row_newbcast:5 row_mask:0xf bank_mask:0xf
	v_fmac_f32_dpp v14, v48, v32 row_newbcast:6 row_mask:0xf bank_mask:0xf
	v_fmac_f32_dpp v15, v48, v32 row_newbcast:7 row_mask:0xf bank_mask:0xf
	v_fmac_f32_dpp v16, v48, v32 row_newbcast:8 row_mask:0xf bank_mask:0xf
	v_fmac_f32_dpp v17, v48, v32 row_newbcast:9 row_mask:0xf bank_mask:0xf
	v_fmac_f32_dpp v18, v48, v32 row_newbcast:10 row_mask:0xf bank_mask:0xf
	v_fmac_f32_dpp v19, v48, v32 row_newbcast:11 row_mask:0xf bank_mask:0xf
	v_fmac_f32_dpp v20, v48, v32 row_newbcast:12 row_mask:0xf bank_mask:0xf
	v_fmac_f32_dpp v21, v48, v32 row_newbcast:13 row_mask:0xf bank_mask:0xf
	v_fmac_f32_dpp v22, v48, v32 row_newbcast:14 row_mask:0xf bank_mask:0xf
	v_fmac_f32_dpp v23, v48, v32 row_newbcast:15 row_mask:0xf bank_mask:0xf
	v_fma_f32 v109, -v32, v68, v33
	v_fma_f32 v109, v66, v69, v109
	ds_write_b32 v107, v109 offset:9728
	v_cvt_pk_bf16_f32 v24, v8, v9
	v_cvt_pk_bf16_f32 v25, v10, v11
	v_cvt_pk_bf16_f32 v26, v12, v13
	v_cvt_pk_bf16_f32 v27, v14, v15
	v_cvt_pk_bf16_f32 v28, v16, v17
	v_cvt_pk_bf16_f32 v29, v18, v19
	s_waitcnt lgkmcnt(4)
	v_mfma_f32_16x16x32_bf16 v[32:35], v[70:73], v[24:27], 0
	v_cvt_pk_bf16_f32 v30, v20, v21
	v_cvt_pk_bf16_f32 v31, v22, v23
	v_fmac_f32_dpp v8, v95, v96 row_newbcast:0 row_mask:0xf bank_mask:0xf
	v_fmac_f32_dpp v9, v95, v96 row_newbcast:1 row_mask:0xf bank_mask:0xf
	v_mfma_f32_16x16x32_bf16 v[32:35], v[74:77], v[28:31], v[32:35]
	v_fmac_f32_dpp v10, v95, v96 row_newbcast:2 row_mask:0xf bank_mask:0xf
	v_fmac_f32_dpp v11, v95, v96 row_newbcast:3 row_mask:0xf bank_mask:0xf
	ds_read_b128 v[40:43], v104 offset:2048
	v_fmac_f32_dpp v12, v95, v96 row_newbcast:4 row_mask:0xf bank_mask:0xf
	v_fmac_f32_dpp v13, v95, v96 row_newbcast:5 row_mask:0xf bank_mask:0xf
	ds_read_b128 v[44:47], v104 offset:2064
	v_fmac_f32_dpp v14, v95, v96 row_newbcast:6 row_mask:0xf bank_mask:0xf
	v_fmac_f32_dpp v15, v95, v96 row_newbcast:7 row_mask:0xf bank_mask:0xf
	ds_read_b32 v65, v105 offset:18432
	v_fmac_f32_dpp v16, v95, v96 row_newbcast:8 row_mask:0xf bank_mask:0xf
	v_fmac_f32_dpp v17, v95, v96 row_newbcast:9 row_mask:0xf bank_mask:0xf
	ds_read_b32 v66, v107 offset:2048
	v_fmac_f32_dpp v18, v95, v96 row_newbcast:10 row_mask:0xf bank_mask:0xf
	v_fmac_f32_dpp v19, v95, v96 row_newbcast:11 row_mask:0xf bank_mask:0xf
	ds_read_b32 v48, v105 offset:10240
	v_fmac_f32_dpp v20, v95, v96 row_newbcast:12 row_mask:0xf bank_mask:0xf
	v_fmac_f32_dpp v21, v95, v96 row_newbcast:13 row_mask:0xf bank_mask:0xf
	ds_read_b64 v[68:69], v108 offset:49216
	v_fmac_f32_dpp v22, v95, v96 row_newbcast:14 row_mask:0xf bank_mask:0xf
	v_fmac_f32_dpp v23, v95, v96 row_newbcast:15 row_mask:0xf bank_mask:0xf
	s_waitcnt lgkmcnt(7)
; __device__ __forceinline__ void phase_rwkv_scan(const Params& p, int l, const int tidx) {
;     ...
;       for (int s = 0; s < RTC; s++) {
;         const bf16x8 A0 = nA0, A1 = nA1;
;         const float wA[8] = {nw0.x, nw0.y, nw0.z, nw0.w, nw1.x, nw1.y, nw1.z, nw1.w};
;         const float wB[8] = {nw2.x, nw2.y, nw2.z, nw2.w, nw3.x, nw3.y, nw3.z, nw3.w};
;         const float kaA[8] = {nka0.x, nka0.y, nka0.z, nka0.w, nka1.x, nka1.y, nka1.z, nka1.w};
;         const float kaB[8] = {nka2.x, nka2.y, nka2.z, nka2.w, nka3.x, nka3.y, nka3.z, nka3.w};
;         const float kdA[8] = {nkd0.x, nkd0.y, nkd0.z, nkd0.w, nkd1.x, nkd1.y, nkd1.z, nkd1.w};
;         const float kdB[8] = {nkd2.x, nkd2.y, nkd2.z, nkd2.w, nkd3.x, nkd3.y, nkd3.z, nkd3.w};
;         const float v = nv;
;         float c1 = nc.x, c2 = nc.y;
;         asm volatile("" : "+v"(c1), "+v"(c2));
;         if (s + 1 < RTC) RW_LD(s + 1);
;         u32x4 pa = {pack2(Sa[0], Sa[1]), pack2(Sa[2], Sa[3]), pack2(Sa[4], Sa[5]), pack2(Sa[6], Sa[7])};
;         u32x4 pb = {pack2(Sb[0], Sb[1]), pack2(Sb[2], Sb[3]), pack2(Sb[4], Sb[5]), pack2(Sb[6], Sb[7])};
;         f32x4 acc = {0.f, 0.f, 0.f, 0.f};
;         acc = __builtin_amdgcn_mfma_f32_16x16x32_bf16(A0, __builtin_bit_cast(bf16x8, pa), acc, 0, 0, 0);
;         acc = __builtin_amdgcn_mfma_f32_16x16x32_bf16(A1, __builtin_bit_cast(bf16x8, pb), acc, 0, 0, 0);
;         float tA[8], tB[8];
; #pragma unroll
;         for (int c = 0; c < 8; c++) { tA[c] = Sa[c] * wA[c] + v * kdA[c]; tB[c] = Sb[c] * wB[c] + v * kdB[c]; }
;         const float sa = -acc[0];
;         const float yq = acc[1];
; #pragma unroll
;         for (int c = 0; c < 8; c++) { Sa[c] = tA[c] + sa * kaA[c]; Sb[c] = tB[c] + sa * kaB[c]; }
;         const float y = yq + sa * c1 + v * c2;
;         if (quad == 0) by[s * 64 + row] = y;
;       }
	v_fmac_f32_dpp v8, v78, v32 row_newbcast:0 row_mask:0xf bank_mask:0xf
	v_fmac_f32_dpp v9, v78, v32 row_newbcast:1 row_mask:0xf bank_mask:0xf
	v_fmac_f32_dpp v10, v78, v32 row_newbcast:2 row_mask:0xf bank_mask:0xf
	v_fmac_f32_dpp v11, v78, v32 row_newbcast:3 row_mask:0xf bank_mask:0xf
	v_fmac_f32_dpp v12, v78, v32 row_newbcast:4 row_mask:0xf bank_mask:0xf
	v_fmac_f32_dpp v13, v78, v32 row_newbcast:5 row_mask:0xf bank_mask:0xf
	v_fmac_f32_dpp v14, v78, v32 row_newbcast:6 row_mask:0xf bank_mask:0xf
	v_fmac_f32_dpp v15, v78, v32 row_newbcast:7 row_mask:0xf bank_mask:0xf
	v_fmac_f32_dpp v16, v78, v32 row_newbcast:8 row_mask:0xf bank_mask:0xf
	v_fmac_f32_dpp v17, v78, v32 row_newbcast:9 row_mask:0xf bank_mask:0xf
	v_fmac_f32_dpp v18, v78, v32 row_newbcast:10 row_mask:0xf bank_mask:0xf
	v_fmac_f32_dpp v19, v78, v32 row_newbcast:11 row_mask:0xf bank_mask:0xf
	v_fmac_f32_dpp v20, v78, v32 row_newbcast:12 row_mask:0xf bank_mask:0xf
	v_fmac_f32_dpp v21, v78, v32 row_newbcast:13 row_mask:0xf bank_mask:0xf
	v_fmac_f32_dpp v22, v78, v32 row_newbcast:14 row_mask:0xf bank_mask:0xf
	v_fmac_f32_dpp v23, v78, v32 row_newbcast:15 row_mask:0xf bank_mask:0xf
	v_fma_f32 v109, -v32, v98, v33
	v_fma_f32 v109, v96, v99, v109
	v_mul_f32_dpp v8, v94, v8 row_newbcast:0 row_mask:0xf bank_mask:0xf
	v_mul_f32_dpp v9, v94, v9 row_newbcast:1 row_mask:0xf bank_mask:0xf
	v_mul_f32_dpp v10, v94, v10 row_newbcast:2 row_mask:0xf bank_mask:0xf
	v_mul_f32_dpp v11, v94, v11 row_newbcast:3 row_mask:0xf bank_mask:0xf
	v_mul_f32_dpp v12, v94, v12 row_newbcast:4 row_mask:0xf bank_mask:0xf
	v_mul_f32_dpp v13, v94, v13 row_newbcast:5 row_mask:0xf bank_mask:0xf
	v_mul_f32_dpp v14, v94, v14 row_newbcast:6 row_mask:0xf bank_mask:0xf
	v_mul_f32_dpp v15, v94, v15 row_newbcast:7 row_mask:0xf bank_mask:0xf
	v_mul_f32_dpp v16, v94, v16 row_newbcast:8 row_mask:0xf bank_mask:0xf
	v_mul_f32_dpp v17, v94, v17 row_newbcast:9 row_mask:0xf bank_mask:0xf
	v_mul_f32_dpp v18, v94, v18 row_newbcast:10 row_mask:0xf bank_mask:0xf
	v_mul_f32_dpp v19, v94, v19 row_newbcast:11 row_mask:0xf bank_mask:0xf
	v_mul_f32_dpp v20, v94, v20 row_newbcast:12 row_mask:0xf bank_mask:0xf
	v_mul_f32_dpp v21, v94, v21 row_newbcast:13 row_mask:0xf bank_mask:0xf
	v_mul_f32_dpp v22, v94, v22 row_newbcast:14 row_mask:0xf bank_mask:0xf
	v_mul_f32_dpp v23, v94, v23 row_newbcast:15 row_mask:0xf bank_mask:0xf
	ds_write_b32 v107, v109 offset:9984
	v_cvt_pk_bf16_f32 v24, v8, v9
	v_cvt_pk_bf16_f32 v25, v10, v11
	v_cvt_pk_bf16_f32 v26, v12, v13
	v_cvt_pk_bf16_f32 v27, v14, v15
	v_cvt_pk_bf16_f32 v28, v16, v17
	v_cvt_pk_bf16_f32 v29, v18, v19
	s_waitcnt lgkmcnt(3)
	v_mfma_f32_16x16x32_bf16 v[32:35], v[40:43], v[24:27], 0
	v_cvt_pk_bf16_f32 v30, v20, v21
	v_cvt_pk_bf16_f32 v31, v22, v23
	v_fmac_f32_dpp v8, v65, v66 row_newbcast:0 row_mask:0xf bank_mask:0xf
	v_fmac_f32_dpp v9, v65, v66 row_newbcast:1 row_mask:0xf bank_mask:0xf
	v_mfma_f32_16x16x32_bf16 v[32:35], v[44:47], v[28:31], v[32:35]
	v_fmac_f32_dpp v10, v65, v66 row_newbcast:2 row_mask:0xf bank_mask:0xf
	v_fmac_f32_dpp v11, v65, v66 row_newbcast:3 row_mask:0xf bank_mask:0xf
	ds_read_b128 v[70:73], v104 offset:2304
	v_fmac_f32_dpp v12, v65, v66 row_newbcast:4 row_mask:0xf bank_mask:0xf
	v_fmac_f32_dpp v13, v65, v66 row_newbcast:5 row_mask:0xf bank_mask:0xf
	ds_read_b128 v[74:77], v104 offset:2320
	v_fmac_f32_dpp v14, v65, v66 row_newbcast:6 row_mask:0xf bank_mask:0xf
	v_fmac_f32_dpp v15, v65, v66 row_newbcast:7 row_mask:0xf bank_mask:0xf
	ds_read_b32 v95, v105 offset:18688
	v_fmac_f32_dpp v16, v65, v66 row_newbcast:8 row_mask:0xf bank_mask:0xf
	v_fmac_f32_dpp v17, v65, v66 row_newbcast:9 row_mask:0xf bank_mask:0xf
	ds_read_b32 v96, v107 offset:2304
	v_fmac_f32_dpp v18, v65, v66 row_newbcast:10 row_mask:0xf bank_mask:0xf
	v_fmac_f32_dpp v19, v65, v66 row_newbcast:11 row_mask:0xf bank_mask:0xf
	ds_read_b32 v78, v105 offset:10496
	v_fmac_f32_dpp v20, v65, v66 row_newbcast:12 row_mask:0xf bank_mask:0xf
	v_fmac_f32_dpp v21, v65, v66 row_newbcast:13 row_mask:0xf bank_mask:0xf
	ds_read_b64 v[98:99], v108 offset:49224
	v_fmac_f32_dpp v22, v65, v66 row_newbcast:14 row_mask:0xf bank_mask:0xf
	v_fmac_f32_dpp v23, v65, v66 row_newbcast:15 row_mask:0xf bank_mask:0xf
	s_waitcnt lgkmcnt(7)
	v_fmac_f32_dpp v8, v48, v32 row_newbcast:0 row_mask:0xf bank_mask:0xf
	v_fmac_f32_dpp v9, v48, v32 row_newbcast:1 row_mask:0xf bank_mask:0xf
	v_fmac_f32_dpp v10, v48, v32 row_newbcast:2 row_mask:0xf bank_mask:0xf
	v_fmac_f32_dpp v11, v48, v32 row_newbcast:3 row_mask:0xf bank_mask:0xf
	v_fmac_f32_dpp v12, v48, v32 row_newbcast:4 row_mask:0xf bank_mask:0xf
	v_fmac_f32_dpp v13, v48, v32 row_newbcast:5 row_mask:0xf bank_mask:0xf
	v_fmac_f32_dpp v14, v48, v32 row_newbcast:6 row_mask:0xf bank_mask:0xf
	v_fmac_f32_dpp v15, v48, v32 row_newbcast:7 row_mask:0xf bank_mask:0xf
	v_fmac_f32_dpp v16, v48, v32 row_newbcast:8 row_mask:0xf bank_mask:0xf
	v_fmac_f32_dpp v17, v48, v32 row_newbcast:9 row_mask:0xf bank_mask:0xf
	v_fmac_f32_dpp v18, v48, v32 row_newbcast:10 row_mask:0xf bank_mask:0xf
	v_fmac_f32_dpp v19, v48, v32 row_newbcast:11 row_mask:0xf bank_mask:0xf
	v_fmac_f32_dpp v20, v48, v32 row_newbcast:12 row_mask:0xf bank_mask:0xf
	v_fmac_f32_dpp v21, v48, v32 row_newbcast:13 row_mask:0xf bank_mask:0xf
	v_fmac_f32_dpp v22, v48, v32 row_newbcast:14 row_mask:0xf bank_mask:0xf
	v_fmac_f32_dpp v23, v48, v32 row_newbcast:15 row_mask:0xf bank_mask:0xf
	v_fma_f32 v109, -v32, v68, v33
	v_fma_f32 v109, v66, v69, v109
	ds_write_b32 v107, v109 offset:10240
	v_cvt_pk_bf16_f32 v24, v8, v9
	v_cvt_pk_bf16_f32 v25, v10, v11
	v_cvt_pk_bf16_f32 v26, v12, v13
	v_cvt_pk_bf16_f32 v27, v14, v15
	v_cvt_pk_bf16_f32 v28, v16, v17
	v_cvt_pk_bf16_f32 v29, v18, v19
	s_waitcnt lgkmcnt(3)
; __device__ __forceinline__ void phase_rwkv_scan(const Params& p, int l, const int tidx) {
;     ...
;       for (int s = 0; s < RTC; s++) {
;         const bf16x8 A0 = nA0, A1 = nA1;
;         const float wA[8] = {nw0.x, nw0.y, nw0.z, nw0.w, nw1.x, nw1.y, nw1.z, nw1.w};
;         const float wB[8] = {nw2.x, nw2.y, nw2.z, nw2.w, nw3.x, nw3.y, nw3.z, nw3.w};
;         const float kaA[8] = {nka0.x, nka0.y, nka0.z, nka0.w, nka1.x, nka1.y, nka1.z, nka1.w};
;         const float kaB[8] = {nka2.x, nka2.y, nka2.z, nka2.w, nka3.x, nka3.y, nka3.z, nka3.w};
;         const float kdA[8] = {nkd0.x, nkd0.y, nkd0.z, nkd0.w, nkd1.x, nkd1.y, nkd1.z, nkd1.w};
;         const float kdB[8] = {nkd2.x, nkd2.y, nkd2.z, nkd2.w, nkd3.x, nkd3.y, nkd3.z, nkd3.w};
;         const float v = nv;
;         float c1 = nc.x, c2 = nc.y;
;         asm volatile("" : "+v"(c1), "+v"(c2));
;         if (s + 1 < RTC) RW_LD(s + 1);
;         u32x4 pa = {pack2(Sa[0], Sa[1]), pack2(Sa[2], Sa[3]), pack2(Sa[4], Sa[5]), pack2(Sa[6], Sa[7])};
;         u32x4 pb = {pack2(Sb[0], Sb[1]), pack2(Sb[2], Sb[3]), pack2(Sb[4], Sb[5]), pack2(Sb[6], Sb[7])};
;         f32x4 acc = {0.f, 0.f, 0.f, 0.f};
;         acc = __builtin_amdgcn_mfma_f32_16x16x32_bf16(A0, __builtin_bit_cast(bf16x8, pa), acc, 0, 0, 0);
;         acc = __builtin_amdgcn_mfma_f32_16x16x32_bf16(A1, __builtin_bit_cast(bf16x8, pb), acc, 0, 0, 0);
;         float tA[8], tB[8];
; #pragma unroll
;         for (int c = 0; c < 8; c++) { tA[c] = Sa[c] * wA[c] + v * kdA[c]; tB[c] = Sb[c] * wB[c] + v * kdB[c]; }
;         const float sa = -acc[0];
;         const float yq = acc[1];
; #pragma unroll
;         for (int c = 0; c < 8; c++) { Sa[c] = tA[c] + sa * kaA[c]; Sb[c] = tB[c] + sa * kaB[c]; }
;         const float y = yq + sa * c1 + v * c2;
;         if (quad == 0) by[s * 64 + row] = y;
;       }
	v_mfma_f32_16x16x32_bf16 v[32:35], v[70:73], v[24:27], 0
	v_cvt_pk_bf16_f32 v30, v20, v21
	v_cvt_pk_bf16_f32 v31, v22, v23
	v_fmac_f32_dpp v8, v95, v96 row_newbcast:0 row_mask:0xf bank_mask:0xf
	v_fmac_f32_dpp v9, v95, v96 row_newbcast:1 row_mask:0xf bank_mask:0xf
	v_mfma_f32_16x16x32_bf16 v[32:35], v[74:77], v[28:31], v[32:35]
	v_fmac_f32_dpp v10, v95, v96 row_newbcast:2 row_mask:0xf bank_mask:0xf
	v_fmac_f32_dpp v11, v95, v96 row_newbcast:3 row_mask:0xf bank_mask:0xf
	ds_read_b128 v[40:43], v104 offset:2560
	v_fmac_f32_dpp v12, v95, v96 row_newbcast:4 row_mask:0xf bank_mask:0xf
	v_fmac_f32_dpp v13, v95, v96 row_newbcast:5 row_mask:0xf bank_mask:0xf
	ds_read_b128 v[44:47], v104 offset:2576
	v_fmac_f32_dpp v14, v95, v96 row_newbcast:6 row_mask:0xf bank_mask:0xf
	v_fmac_f32_dpp v15, v95, v96 row_newbcast:7 row_mask:0xf bank_mask:0xf
	ds_read_b32 v65, v105 offset:18944
	v_fmac_f32_dpp v16, v95, v96 row_newbcast:8 row_mask:0xf bank_mask:0xf
	v_fmac_f32_dpp v17, v95, v96 row_newbcast:9 row_mask:0xf bank_mask:0xf
	ds_read_b32 v66, v107 offset:2560
	v_fmac_f32_dpp v18, v95, v96 row_newbcast:10 row_mask:0xf bank_mask:0xf
	v_fmac_f32_dpp v19, v95, v96 row_newbcast:11 row_mask:0xf bank_mask:0xf
	ds_read_b32 v48, v105 offset:10752
	v_fmac_f32_dpp v20, v95, v96 row_newbcast:12 row_mask:0xf bank_mask:0xf
	v_fmac_f32_dpp v21, v95, v96 row_newbcast:13 row_mask:0xf bank_mask:0xf
	ds_read_b64 v[68:69], v108 offset:49232
	v_fmac_f32_dpp v22, v95, v96 row_newbcast:14 row_mask:0xf bank_mask:0xf
	v_fmac_f32_dpp v23, v95, v96 row_newbcast:15 row_mask:0xf bank_mask:0xf
	s_waitcnt lgkmcnt(7)
	v_fmac_f32_dpp v8, v78, v32 row_newbcast:0 row_mask:0xf bank_mask:0xf
	v_fmac_f32_dpp v9, v78, v32 row_newbcast:1 row_mask:0xf bank_mask:0xf
	v_fmac_f32_dpp v10, v78, v32 row_newbcast:2 row_mask:0xf bank_mask:0xf
	v_fmac_f32_dpp v11, v78, v32 row_newbcast:3 row_mask:0xf bank_mask:0xf
	v_fmac_f32_dpp v12, v78, v32 row_newbcast:4 row_mask:0xf bank_mask:0xf
	v_fmac_f32_dpp v13, v78, v32 row_newbcast:5 row_mask:0xf bank_mask:0xf
	v_fmac_f32_dpp v14, v78, v32 row_newbcast:6 row_mask:0xf bank_mask:0xf
	v_fmac_f32_dpp v15, v78, v32 row_newbcast:7 row_mask:0xf bank_mask:0xf
	v_fmac_f32_dpp v16, v78, v32 row_newbcast:8 row_mask:0xf bank_mask:0xf
	v_fmac_f32_dpp v17, v78, v32 row_newbcast:9 row_mask:0xf bank_mask:0xf
	v_fmac_f32_dpp v18, v78, v32 row_newbcast:10 row_mask:0xf bank_mask:0xf
	v_fmac_f32_dpp v19, v78, v32 row_newbcast:11 row_mask:0xf bank_mask:0xf
	v_fmac_f32_dpp v20, v78, v32 row_newbcast:12 row_mask:0xf bank_mask:0xf
	v_fmac_f32_dpp v21, v78, v32 row_newbcast:13 row_mask:0xf bank_mask:0xf
	v_fmac_f32_dpp v22, v78, v32 row_newbcast:14 row_mask:0xf bank_mask:0xf
	v_fmac_f32_dpp v23, v78, v32 row_newbcast:15 row_mask:0xf bank_mask:0xf
	v_fma_f32 v109, -v32, v98, v33
	v_fma_f32 v109, v96, v99, v109
	ds_write_b32 v107, v109 offset:10496
	v_cvt_pk_bf16_f32 v24, v8, v9
	v_cvt_pk_bf16_f32 v25, v10, v11
	v_cvt_pk_bf16_f32 v26, v12, v13
	v_cvt_pk_bf16_f32 v27, v14, v15
	v_cvt_pk_bf16_f32 v28, v16, v17
	v_cvt_pk_bf16_f32 v29, v18, v19
	s_waitcnt lgkmcnt(3)
	v_mfma_f32_16x16x32_bf16 v[32:35], v[40:43], v[24:27], 0
	v_cvt_pk_bf16_f32 v30, v20, v21
	v_cvt_pk_bf16_f32 v31, v22, v23
	v_fmac_f32_dpp v8, v65, v66 row_newbcast:0 row_mask:0xf bank_mask:0xf
	v_fmac_f32_dpp v9, v65, v66 row_newbcast:1 row_mask:0xf bank_mask:0xf
	v_mfma_f32_16x16x32_bf16 v[32:35], v[44:47], v[28:31], v[32:35]
	v_fmac_f32_dpp v10, v65, v66 row_newbcast:2 row_mask:0xf bank_mask:0xf
	v_fmac_f32_dpp v11, v65, v66 row_newbcast:3 row_mask:0xf bank_mask:0xf
	ds_read_b128 v[70:73], v104 offset:2816
	v_fmac_f32_dpp v12, v65, v66 row_newbcast:4 row_mask:0xf bank_mask:0xf
	v_fmac_f32_dpp v13, v65, v66 row_newbcast:5 row_mask:0xf bank_mask:0xf
	ds_read_b128 v[74:77], v104 offset:2832
	v_fmac_f32_dpp v14, v65, v66 row_newbcast:6 row_mask:0xf bank_mask:0xf
	v_fmac_f32_dpp v15, v65, v66 row_newbcast:7 row_mask:0xf bank_mask:0xf
	ds_read_b32 v95, v105 offset:19200
	v_fmac_f32_dpp v16, v65, v66 row_newbcast:8 row_mask:0xf bank_mask:0xf
	v_fmac_f32_dpp v17, v65, v66 row_newbcast:9 row_mask:0xf bank_mask:0xf
	ds_read_b32 v96, v107 offset:2816
	v_fmac_f32_dpp v18, v65, v66 row_newbcast:10 row_mask:0xf bank_mask:0xf
	v_fmac_f32_dpp v19, v65, v66 row_newbcast:11 row_mask:0xf bank_mask:0xf
	ds_read_b32 v78, v105 offset:11008
	v_fmac_f32_dpp v20, v65, v66 row_newbcast:12 row_mask:0xf bank_mask:0xf
	v_fmac_f32_dpp v21, v65, v66 row_newbcast:13 row_mask:0xf bank_mask:0xf
	ds_read_b64 v[98:99], v108 offset:49240
	v_fmac_f32_dpp v22, v65, v66 row_newbcast:14 row_mask:0xf bank_mask:0xf
	v_fmac_f32_dpp v23, v65, v66 row_newbcast:15 row_mask:0xf bank_mask:0xf
	s_waitcnt lgkmcnt(7)
	v_fmac_f32_dpp v8, v48, v32 row_newbcast:0 row_mask:0xf bank_mask:0xf
	v_fmac_f32_dpp v9, v48, v32 row_newbcast:1 row_mask:0xf bank_mask:0xf
	v_fmac_f32_dpp v10, v48, v32 row_newbcast:2 row_mask:0xf bank_mask:0xf
	v_fmac_f32_dpp v11, v48, v32 row_newbcast:3 row_mask:0xf bank_mask:0xf
	v_fmac_f32_dpp v12, v48, v32 row_newbcast:4 row_mask:0xf bank_mask:0xf
	v_fmac_f32_dpp v13, v48, v32 row_newbcast:5 row_mask:0xf bank_mask:0xf
	v_fmac_f32_dpp v14, v48, v32 row_newbcast:6 row_mask:0xf bank_mask:0xf
	v_fmac_f32_dpp v15, v48, v32 row_newbcast:7 row_mask:0xf bank_mask:0xf
	v_fmac_f32_dpp v16, v48, v32 row_newbcast:8 row_mask:0xf bank_mask:0xf
	v_fmac_f32_dpp v17, v48, v32 row_newbcast:9 row_mask:0xf bank_mask:0xf
	v_fmac_f32_dpp v18, v48, v32 row_newbcast:10 row_mask:0xf bank_mask:0xf
	v_fmac_f32_dpp v19, v48, v32 row_newbcast:11 row_mask:0xf bank_mask:0xf
	v_fmac_f32_dpp v20, v48, v32 row_newbcast:12 row_mask:0xf bank_mask:0xf
	v_fmac_f32_dpp v21, v48, v32 row_newbcast:13 row_mask:0xf bank_mask:0xf
	v_fmac_f32_dpp v22, v48, v32 row_newbcast:14 row_mask:0xf bank_mask:0xf
	v_fmac_f32_dpp v23, v48, v32 row_newbcast:15 row_mask:0xf bank_mask:0xf
	v_fma_f32 v109, -v32, v68, v33
	v_fma_f32 v109, v66, v69, v109
	ds_write_b32 v107, v109 offset:10752
	v_cvt_pk_bf16_f32 v24, v8, v9
	v_cvt_pk_bf16_f32 v25, v10, v11
	v_cvt_pk_bf16_f32 v26, v12, v13
	v_cvt_pk_bf16_f32 v27, v14, v15
	v_cvt_pk_bf16_f32 v28, v16, v17
	v_cvt_pk_bf16_f32 v29, v18, v19
	s_waitcnt lgkmcnt(3)
; __device__ __forceinline__ void phase_rwkv_scan(const Params& p, int l, const int tidx) {
;     ...
;       for (int s = 0; s < RTC; s++) {
;         const bf16x8 A0 = nA0, A1 = nA1;
;         const float wA[8] = {nw0.x, nw0.y, nw0.z, nw0.w, nw1.x, nw1.y, nw1.z, nw1.w};
;         const float wB[8] = {nw2.x, nw2.y, nw2.z, nw2.w, nw3.x, nw3.y, nw3.z, nw3.w};
;         const float kaA[8] = {nka0.x, nka0.y, nka0.z, nka0.w, nka1.x, nka1.y, nka1.z, nka1.w};
;         const float kaB[8] = {nka2.x, nka2.y, nka2.z, nka2.w, nka3.x, nka3.y, nka3.z, nka3.w};
;         const float kdA[8] = {nkd0.x, nkd0.y, nkd0.z, nkd0.w, nkd1.x, nkd1.y, nkd1.z, nkd1.w};
;         const float kdB[8] = {nkd2.x, nkd2.y, nkd2.z, nkd2.w, nkd3.x, nkd3.y, nkd3.z, nkd3.w};
;         const float v = nv;
;         float c1 = nc.x, c2 = nc.y;
;         asm volatile("" : "+v"(c1), "+v"(c2));
;         if (s + 1 < RTC) RW_LD(s + 1);
;         u32x4 pa = {pack2(Sa[0], Sa[1]), pack2(Sa[2], Sa[3]), pack2(Sa[4], Sa[5]), pack2(Sa[6], Sa[7])};
;         u32x4 pb = {pack2(Sb[0], Sb[1]), pack2(Sb[2], Sb[3]), pack2(Sb[4], Sb[5]), pack2(Sb[6], Sb[7])};
;         f32x4 acc = {0.f, 0.f, 0.f, 0.f};
;         acc = __builtin_amdgcn_mfma_f32_16x16x32_bf16(A0, __builtin_bit_cast(bf16x8, pa), acc, 0, 0, 0);
;         acc = __builtin_amdgcn_mfma_f32_16x16x32_bf16(A1, __builtin_bit_cast(bf16x8, pb), acc, 0, 0, 0);
;         float tA[8], tB[8];
; #pragma unroll
;         for (int c = 0; c < 8; c++) { tA[c] = Sa[c] * wA[c] + v * kdA[c]; tB[c] = Sb[c] * wB[c] + v * kdB[c]; }
;         const float sa = -acc[0];
;         const float yq = acc[1];
; #pragma unroll
;         for (int c = 0; c < 8; c++) { Sa[c] = tA[c] + sa * kaA[c]; Sb[c] = tB[c] + sa * kaB[c]; }
;         const float y = yq + sa * c1 + v * c2;
;         if (quad == 0) by[s * 64 + row] = y;
;       }
	v_mfma_f32_16x16x32_bf16 v[32:35], v[70:73], v[24:27], 0
	v_cvt_pk_bf16_f32 v30, v20, v21
	v_cvt_pk_bf16_f32 v31, v22, v23
	v_fmac_f32_dpp v8, v95, v96 row_newbcast:0 row_mask:0xf bank_mask:0xf
	v_fmac_f32_dpp v9, v95, v96 row_newbcast:1 row_mask:0xf bank_mask:0xf
	v_mfma_f32_16x16x32_bf16 v[32:35], v[74:77], v[28:31], v[32:35]
	v_fmac_f32_dpp v10, v95, v96 row_newbcast:2 row_mask:0xf bank_mask:0xf
	v_fmac_f32_dpp v11, v95, v96 row_newbcast:3 row_mask:0xf bank_mask:0xf
	ds_read_b128 v[40:43], v104 offset:3072
	v_fmac_f32_dpp v12, v95, v96 row_newbcast:4 row_mask:0xf bank_mask:0xf
	v_fmac_f32_dpp v13, v95, v96 row_newbcast:5 row_mask:0xf bank_mask:0xf
	ds_read_b128 v[44:47], v104 offset:3088
	v_fmac_f32_dpp v14, v95, v96 row_newbcast:6 row_mask:0xf bank_mask:0xf
	v_fmac_f32_dpp v15, v95, v96 row_newbcast:7 row_mask:0xf bank_mask:0xf
	ds_read_b32 v65, v105 offset:19456
	v_fmac_f32_dpp v16, v95, v96 row_newbcast:8 row_mask:0xf bank_mask:0xf
	v_fmac_f32_dpp v17, v95, v96 row_newbcast:9 row_mask:0xf bank_mask:0xf
	ds_read_b32 v66, v107 offset:3072
	v_fmac_f32_dpp v18, v95, v96 row_newbcast:10 row_mask:0xf bank_mask:0xf
	v_fmac_f32_dpp v19, v95, v96 row_newbcast:11 row_mask:0xf bank_mask:0xf
	ds_read_b32 v48, v105 offset:11264
	v_fmac_f32_dpp v20, v95, v96 row_newbcast:12 row_mask:0xf bank_mask:0xf
	v_fmac_f32_dpp v21, v95, v96 row_newbcast:13 row_mask:0xf bank_mask:0xf
	ds_read_b64 v[68:69], v108 offset:49248
	v_fmac_f32_dpp v22, v95, v96 row_newbcast:14 row_mask:0xf bank_mask:0xf
	v_fmac_f32_dpp v23, v95, v96 row_newbcast:15 row_mask:0xf bank_mask:0xf
	s_waitcnt lgkmcnt(7)
	v_fmac_f32_dpp v8, v78, v32 row_newbcast:0 row_mask:0xf bank_mask:0xf
	v_fmac_f32_dpp v9, v78, v32 row_newbcast:1 row_mask:0xf bank_mask:0xf
	v_fmac_f32_dpp v10, v78, v32 row_newbcast:2 row_mask:0xf bank_mask:0xf
	v_fmac_f32_dpp v11, v78, v32 row_newbcast:3 row_mask:0xf bank_mask:0xf
	v_fmac_f32_dpp v12, v78, v32 row_newbcast:4 row_mask:0xf bank_mask:0xf
	v_fmac_f32_dpp v13, v78, v32 row_newbcast:5 row_mask:0xf bank_mask:0xf
	v_fmac_f32_dpp v14, v78, v32 row_newbcast:6 row_mask:0xf bank_mask:0xf
	v_fmac_f32_dpp v15, v78, v32 row_newbcast:7 row_mask:0xf bank_mask:0xf
	v_fmac_f32_dpp v16, v78, v32 row_newbcast:8 row_mask:0xf bank_mask:0xf
	v_fmac_f32_dpp v17, v78, v32 row_newbcast:9 row_mask:0xf bank_mask:0xf
	v_fmac_f32_dpp v18, v78, v32 row_newbcast:10 row_mask:0xf bank_mask:0xf
	v_fmac_f32_dpp v19, v78, v32 row_newbcast:11 row_mask:0xf bank_mask:0xf
	v_fmac_f32_dpp v20, v78, v32 row_newbcast:12 row_mask:0xf bank_mask:0xf
	v_fmac_f32_dpp v21, v78, v32 row_newbcast:13 row_mask:0xf bank_mask:0xf
	v_fmac_f32_dpp v22, v78, v32 row_newbcast:14 row_mask:0xf bank_mask:0xf
	v_fmac_f32_dpp v23, v78, v32 row_newbcast:15 row_mask:0xf bank_mask:0xf
	v_fma_f32 v109, -v32, v98, v33
	v_fma_f32 v109, v96, v99, v109
	ds_write_b32 v107, v109 offset:11008
	v_cvt_pk_bf16_f32 v24, v8, v9
	v_cvt_pk_bf16_f32 v25, v10, v11
	v_cvt_pk_bf16_f32 v26, v12, v13
	v_cvt_pk_bf16_f32 v27, v14, v15
	v_cvt_pk_bf16_f32 v28, v16, v17
	v_cvt_pk_bf16_f32 v29, v18, v19
	s_waitcnt lgkmcnt(3)
	v_mfma_f32_16x16x32_bf16 v[32:35], v[40:43], v[24:27], 0
	v_cvt_pk_bf16_f32 v30, v20, v21
	v_cvt_pk_bf16_f32 v31, v22, v23
	v_fmac_f32_dpp v8, v65, v66 row_newbcast:0 row_mask:0xf bank_mask:0xf
	v_fmac_f32_dpp v9, v65, v66 row_newbcast:1 row_mask:0xf bank_mask:0xf
	v_mfma_f32_16x16x32_bf16 v[32:35], v[44:47], v[28:31], v[32:35]
	v_fmac_f32_dpp v10, v65, v66 row_newbcast:2 row_mask:0xf bank_mask:0xf
	v_fmac_f32_dpp v11, v65, v66 row_newbcast:3 row_mask:0xf bank_mask:0xf
	ds_read_b128 v[70:73], v104 offset:3328
	v_fmac_f32_dpp v12, v65, v66 row_newbcast:4 row_mask:0xf bank_mask:0xf
	v_fmac_f32_dpp v13, v65, v66 row_newbcast:5 row_mask:0xf bank_mask:0xf
	ds_read_b128 v[74:77], v104 offset:3344
	v_fmac_f32_dpp v14, v65, v66 row_newbcast:6 row_mask:0xf bank_mask:0xf
	v_fmac_f32_dpp v15, v65, v66 row_newbcast:7 row_mask:0xf bank_mask:0xf
	ds_read_b32 v95, v105 offset:19712
	v_fmac_f32_dpp v16, v65, v66 row_newbcast:8 row_mask:0xf bank_mask:0xf
	v_fmac_f32_dpp v17, v65, v66 row_newbcast:9 row_mask:0xf bank_mask:0xf
	ds_read_b32 v96, v107 offset:3328
	v_fmac_f32_dpp v18, v65, v66 row_newbcast:10 row_mask:0xf bank_mask:0xf
	v_fmac_f32_dpp v19, v65, v66 row_newbcast:11 row_mask:0xf bank_mask:0xf
	ds_read_b32 v78, v105 offset:11520
	v_fmac_f32_dpp v20, v65, v66 row_newbcast:12 row_mask:0xf bank_mask:0xf
	v_fmac_f32_dpp v21, v65, v66 row_newbcast:13 row_mask:0xf bank_mask:0xf
	ds_read_b64 v[98:99], v108 offset:49256
	v_fmac_f32_dpp v22, v65, v66 row_newbcast:14 row_mask:0xf bank_mask:0xf
	v_fmac_f32_dpp v23, v65, v66 row_newbcast:15 row_mask:0xf bank_mask:0xf
	s_waitcnt lgkmcnt(7)
	v_fmac_f32_dpp v8, v48, v32 row_newbcast:0 row_mask:0xf bank_mask:0xf
	v_fmac_f32_dpp v9, v48, v32 row_newbcast:1 row_mask:0xf bank_mask:0xf
	v_fmac_f32_dpp v10, v48, v32 row_newbcast:2 row_mask:0xf bank_mask:0xf
	v_fmac_f32_dpp v11, v48, v32 row_newbcast:3 row_mask:0xf bank_mask:0xf
	v_fmac_f32_dpp v12, v48, v32 row_newbcast:4 row_mask:0xf bank_mask:0xf
	v_fmac_f32_dpp v13, v48, v32 row_newbcast:5 row_mask:0xf bank_mask:0xf
	v_fmac_f32_dpp v14, v48, v32 row_newbcast:6 row_mask:0xf bank_mask:0xf
	v_fmac_f32_dpp v15, v48, v32 row_newbcast:7 row_mask:0xf bank_mask:0xf
	v_fmac_f32_dpp v16, v48, v32 row_newbcast:8 row_mask:0xf bank_mask:0xf
	v_fmac_f32_dpp v17, v48, v32 row_newbcast:9 row_mask:0xf bank_mask:0xf
	v_fmac_f32_dpp v18, v48, v32 row_newbcast:10 row_mask:0xf bank_mask:0xf
	v_fmac_f32_dpp v19, v48, v32 row_newbcast:11 row_mask:0xf bank_mask:0xf
	v_fmac_f32_dpp v20, v48, v32 row_newbcast:12 row_mask:0xf bank_mask:0xf
	v_fmac_f32_dpp v21, v48, v32 row_newbcast:13 row_mask:0xf bank_mask:0xf
	v_fmac_f32_dpp v22, v48, v32 row_newbcast:14 row_mask:0xf bank_mask:0xf
	v_fmac_f32_dpp v23, v48, v32 row_newbcast:15 row_mask:0xf bank_mask:0xf
	v_fma_f32 v109, -v32, v68, v33
	v_fma_f32 v109, v66, v69, v109
	ds_write_b32 v107, v109 offset:11264
	v_cvt_pk_bf16_f32 v24, v8, v9
	v_cvt_pk_bf16_f32 v25, v10, v11
	v_cvt_pk_bf16_f32 v26, v12, v13
	v_cvt_pk_bf16_f32 v27, v14, v15
	v_cvt_pk_bf16_f32 v28, v16, v17
	v_cvt_pk_bf16_f32 v29, v18, v19
	s_waitcnt lgkmcnt(3)
; __device__ __forceinline__ void phase_rwkv_scan(const Params& p, int l, const int tidx) {
;     ...
;       for (int s = 0; s < RTC; s++) {
;         const bf16x8 A0 = nA0, A1 = nA1;
;         const float wA[8] = {nw0.x, nw0.y, nw0.z, nw0.w, nw1.x, nw1.y, nw1.z, nw1.w};
;         const float wB[8] = {nw2.x, nw2.y, nw2.z, nw2.w, nw3.x, nw3.y, nw3.z, nw3.w};
;         const float kaA[8] = {nka0.x, nka0.y, nka0.z, nka0.w, nka1.x, nka1.y, nka1.z, nka1.w};
;         const float kaB[8] = {nka2.x, nka2.y, nka2.z, nka2.w, nka3.x, nka3.y, nka3.z, nka3.w};
;         const float kdA[8] = {nkd0.x, nkd0.y, nkd0.z, nkd0.w, nkd1.x, nkd1.y, nkd1.z, nkd1.w};
;         const float kdB[8] = {nkd2.x, nkd2.y, nkd2.z, nkd2.w, nkd3.x, nkd3.y, nkd3.z, nkd3.w};
;         const float v = nv;
;         float c1 = nc.x, c2 = nc.y;
;         asm volatile("" : "+v"(c1), "+v"(c2));
;         if (s + 1 < RTC) RW_LD(s + 1);
;         u32x4 pa = {pack2(Sa[0], Sa[1]), pack2(Sa[2], Sa[3]), pack2(Sa[4], Sa[5]), pack2(Sa[6], Sa[7])};
;         u32x4 pb = {pack2(Sb[0], Sb[1]), pack2(Sb[2], Sb[3]), pack2(Sb[4], Sb[5]), pack2(Sb[6], Sb[7])};
;         f32x4 acc = {0.f, 0.f, 0.f, 0.f};
;         acc = __builtin_amdgcn_mfma_f32_16x16x32_bf16(A0, __builtin_bit_cast(bf16x8, pa), acc, 0, 0, 0);
;         acc = __builtin_amdgcn_mfma_f32_16x16x32_bf16(A1, __builtin_bit_cast(bf16x8, pb), acc, 0, 0, 0);
;         float tA[8], tB[8];
; #pragma unroll
;         for (int c = 0; c < 8; c++) { tA[c] = Sa[c] * wA[c] + v * kdA[c]; tB[c] = Sb[c] * wB[c] + v * kdB[c]; }
;         const float sa = -acc[0];
;         const float yq = acc[1];
; #pragma unroll
;         for (int c = 0; c < 8; c++) { Sa[c] = tA[c] + sa * kaA[c]; Sb[c] = tB[c] + sa * kaB[c]; }
;         const float y = yq + sa * c1 + v * c2;
;         if (quad == 0) by[s * 64 + row] = y;
;       }
	v_mfma_f32_16x16x32_bf16 v[32:35], v[70:73], v[24:27], 0
	v_cvt_pk_bf16_f32 v30, v20, v21
	v_cvt_pk_bf16_f32 v31, v22, v23
	v_fmac_f32_dpp v8, v95, v96 row_newbcast:0 row_mask:0xf bank_mask:0xf
	v_fmac_f32_dpp v9, v95, v96 row_newbcast:1 row_mask:0xf bank_mask:0xf
	v_mfma_f32_16x16x32_bf16 v[32:35], v[74:77], v[28:31], v[32:35]
	v_fmac_f32_dpp v10, v95, v96 row_newbcast:2 row_mask:0xf bank_mask:0xf
	v_fmac_f32_dpp v11, v95, v96 row_newbcast:3 row_mask:0xf bank_mask:0xf
	ds_read_b128 v[40:43], v104 offset:3584
	v_fmac_f32_dpp v12, v95, v96 row_newbcast:4 row_mask:0xf bank_mask:0xf
	v_fmac_f32_dpp v13, v95, v96 row_newbcast:5 row_mask:0xf bank_mask:0xf
	ds_read_b128 v[44:47], v104 offset:3600
	v_fmac_f32_dpp v14, v95, v96 row_newbcast:6 row_mask:0xf bank_mask:0xf
	v_fmac_f32_dpp v15, v95, v96 row_newbcast:7 row_mask:0xf bank_mask:0xf
	ds_read_b32 v65, v105 offset:19968
	v_fmac_f32_dpp v16, v95, v96 row_newbcast:8 row_mask:0xf bank_mask:0xf
	v_fmac_f32_dpp v17, v95, v96 row_newbcast:9 row_mask:0xf bank_mask:0xf
	ds_read_b32 v66, v107 offset:3584
	v_fmac_f32_dpp v18, v95, v96 row_newbcast:10 row_mask:0xf bank_mask:0xf
	v_fmac_f32_dpp v19, v95, v96 row_newbcast:11 row_mask:0xf bank_mask:0xf
	ds_read_b32 v48, v105 offset:11776
	v_fmac_f32_dpp v20, v95, v96 row_newbcast:12 row_mask:0xf bank_mask:0xf
	v_fmac_f32_dpp v21, v95, v96 row_newbcast:13 row_mask:0xf bank_mask:0xf
	ds_read_b64 v[68:69], v108 offset:49264
	v_fmac_f32_dpp v22, v95, v96 row_newbcast:14 row_mask:0xf bank_mask:0xf
	v_fmac_f32_dpp v23, v95, v96 row_newbcast:15 row_mask:0xf bank_mask:0xf
	s_waitcnt lgkmcnt(7)
	v_fmac_f32_dpp v8, v78, v32 row_newbcast:0 row_mask:0xf bank_mask:0xf
	v_fmac_f32_dpp v9, v78, v32 row_newbcast:1 row_mask:0xf bank_mask:0xf
	v_fmac_f32_dpp v10, v78, v32 row_newbcast:2 row_mask:0xf bank_mask:0xf
	v_fmac_f32_dpp v11, v78, v32 row_newbcast:3 row_mask:0xf bank_mask:0xf
	v_fmac_f32_dpp v12, v78, v32 row_newbcast:4 row_mask:0xf bank_mask:0xf
	v_fmac_f32_dpp v13, v78, v32 row_newbcast:5 row_mask:0xf bank_mask:0xf
	v_fmac_f32_dpp v14, v78, v32 row_newbcast:6 row_mask:0xf bank_mask:0xf
	v_fmac_f32_dpp v15, v78, v32 row_newbcast:7 row_mask:0xf bank_mask:0xf
	v_fmac_f32_dpp v16, v78, v32 row_newbcast:8 row_mask:0xf bank_mask:0xf
	v_fmac_f32_dpp v17, v78, v32 row_newbcast:9 row_mask:0xf bank_mask:0xf
	v_fmac_f32_dpp v18, v78, v32 row_newbcast:10 row_mask:0xf bank_mask:0xf
	v_fmac_f32_dpp v19, v78, v32 row_newbcast:11 row_mask:0xf bank_mask:0xf
	v_fmac_f32_dpp v20, v78, v32 row_newbcast:12 row_mask:0xf bank_mask:0xf
	v_fmac_f32_dpp v21, v78, v32 row_newbcast:13 row_mask:0xf bank_mask:0xf
	v_fmac_f32_dpp v22, v78, v32 row_newbcast:14 row_mask:0xf bank_mask:0xf
	v_fmac_f32_dpp v23, v78, v32 row_newbcast:15 row_mask:0xf bank_mask:0xf
	v_fma_f32 v109, -v32, v98, v33
	v_fma_f32 v109, v96, v99, v109
	ds_write_b32 v107, v109 offset:11520
	v_cvt_pk_bf16_f32 v24, v8, v9
	v_cvt_pk_bf16_f32 v25, v10, v11
	v_cvt_pk_bf16_f32 v26, v12, v13
	v_cvt_pk_bf16_f32 v27, v14, v15
	v_cvt_pk_bf16_f32 v28, v16, v17
	v_cvt_pk_bf16_f32 v29, v18, v19
	s_waitcnt lgkmcnt(3)
	v_mfma_f32_16x16x32_bf16 v[32:35], v[40:43], v[24:27], 0
	v_cvt_pk_bf16_f32 v30, v20, v21
	v_cvt_pk_bf16_f32 v31, v22, v23
	v_fmac_f32_dpp v8, v65, v66 row_newbcast:0 row_mask:0xf bank_mask:0xf
	v_fmac_f32_dpp v9, v65, v66 row_newbcast:1 row_mask:0xf bank_mask:0xf
	v_mfma_f32_16x16x32_bf16 v[32:35], v[44:47], v[28:31], v[32:35]
	v_fmac_f32_dpp v10, v65, v66 row_newbcast:2 row_mask:0xf bank_mask:0xf
	v_fmac_f32_dpp v11, v65, v66 row_newbcast:3 row_mask:0xf bank_mask:0xf
	ds_read_b128 v[70:73], v104 offset:3840
	v_fmac_f32_dpp v12, v65, v66 row_newbcast:4 row_mask:0xf bank_mask:0xf
	v_fmac_f32_dpp v13, v65, v66 row_newbcast:5 row_mask:0xf bank_mask:0xf
	ds_read_b128 v[74:77], v104 offset:3856
	v_fmac_f32_dpp v14, v65, v66 row_newbcast:6 row_mask:0xf bank_mask:0xf
	v_fmac_f32_dpp v15, v65, v66 row_newbcast:7 row_mask:0xf bank_mask:0xf
	ds_read_b32 v95, v105 offset:20224
	v_fmac_f32_dpp v16, v65, v66 row_newbcast:8 row_mask:0xf bank_mask:0xf
	v_fmac_f32_dpp v17, v65, v66 row_newbcast:9 row_mask:0xf bank_mask:0xf
	ds_read_b32 v96, v107 offset:3840
	v_fmac_f32_dpp v18, v65, v66 row_newbcast:10 row_mask:0xf bank_mask:0xf
	v_fmac_f32_dpp v19, v65, v66 row_newbcast:11 row_mask:0xf bank_mask:0xf
	ds_read_b32 v94, v105 offset:3840
	v_fmac_f32_dpp v20, v65, v66 row_newbcast:12 row_mask:0xf bank_mask:0xf
	v_fmac_f32_dpp v21, v65, v66 row_newbcast:13 row_mask:0xf bank_mask:0xf
	ds_read_b32 v78, v105 offset:12032
	v_fmac_f32_dpp v22, v65, v66 row_newbcast:14 row_mask:0xf bank_mask:0xf
	v_fmac_f32_dpp v23, v65, v66 row_newbcast:15 row_mask:0xf bank_mask:0xf
	ds_read_b64 v[98:99], v108 offset:49272
	s_waitcnt lgkmcnt(8)
	v_fmac_f32_dpp v8, v48, v32 row_newbcast:0 row_mask:0xf bank_mask:0xf
	v_fmac_f32_dpp v9, v48, v32 row_newbcast:1 row_mask:0xf bank_mask:0xf
	v_fmac_f32_dpp v10, v48, v32 row_newbcast:2 row_mask:0xf bank_mask:0xf
	v_fmac_f32_dpp v11, v48, v32 row_newbcast:3 row_mask:0xf bank_mask:0xf
	v_fmac_f32_dpp v12, v48, v32 row_newbcast:4 row_mask:0xf bank_mask:0xf
	v_fmac_f32_dpp v13, v48, v32 row_newbcast:5 row_mask:0xf bank_mask:0xf
	v_fmac_f32_dpp v14, v48, v32 row_newbcast:6 row_mask:0xf bank_mask:0xf
	v_fmac_f32_dpp v15, v48, v32 row_newbcast:7 row_mask:0xf bank_mask:0xf
	v_fmac_f32_dpp v16, v48, v32 row_newbcast:8 row_mask:0xf bank_mask:0xf
	v_fmac_f32_dpp v17, v48, v32 row_newbcast:9 row_mask:0xf bank_mask:0xf
	v_fmac_f32_dpp v18, v48, v32 row_newbcast:10 row_mask:0xf bank_mask:0xf
	v_fmac_f32_dpp v19, v48, v32 row_newbcast:11 row_mask:0xf bank_mask:0xf
	v_fmac_f32_dpp v20, v48, v32 row_newbcast:12 row_mask:0xf bank_mask:0xf
	v_fmac_f32_dpp v21, v48, v32 row_newbcast:13 row_mask:0xf bank_mask:0xf
	v_fmac_f32_dpp v22, v48, v32 row_newbcast:14 row_mask:0xf bank_mask:0xf
	v_fmac_f32_dpp v23, v48, v32 row_newbcast:15 row_mask:0xf bank_mask:0xf
	v_fma_f32 v109, -v32, v68, v33
	v_fma_f32 v109, v66, v69, v109
	ds_write_b32 v107, v109 offset:11776
	v_cvt_pk_bf16_f32 v24, v8, v9
	v_cvt_pk_bf16_f32 v25, v10, v11
	v_cvt_pk_bf16_f32 v26, v12, v13
	v_cvt_pk_bf16_f32 v27, v14, v15
	v_cvt_pk_bf16_f32 v28, v16, v17
	v_cvt_pk_bf16_f32 v29, v18, v19
	s_waitcnt lgkmcnt(4)
; __device__ __forceinline__ void phase_rwkv_scan(const Params& p, int l, const int tidx) {
;     ...
;       for (int s = 0; s < RTC; s++) {
;         const bf16x8 A0 = nA0, A1 = nA1;
;         const float wA[8] = {nw0.x, nw0.y, nw0.z, nw0.w, nw1.x, nw1.y, nw1.z, nw1.w};
;         const float wB[8] = {nw2.x, nw2.y, nw2.z, nw2.w, nw3.x, nw3.y, nw3.z, nw3.w};
;         const float kaA[8] = {nka0.x, nka0.y, nka0.z, nka0.w, nka1.x, nka1.y, nka1.z, nka1.w};
;         const float kaB[8] = {nka2.x, nka2.y, nka2.z, nka2.w, nka3.x, nka3.y, nka3.z, nka3.w};
;         const float kdA[8] = {nkd0.x, nkd0.y, nkd0.z, nkd0.w, nkd1.x, nkd1.y, nkd1.z, nkd1.w};
;         const float kdB[8] = {nkd2.x, nkd2.y, nkd2.z, nkd2.w, nkd3.x, nkd3.y, nkd3.z, nkd3.w};
;         const float v = nv;
;         float c1 = nc.x, c2 = nc.y;
;         asm volatile("" : "+v"(c1), "+v"(c2));
;         if (s + 1 < RTC) RW_LD(s + 1);
;         u32x4 pa = {pack2(Sa[0], Sa[1]), pack2(Sa[2], Sa[3]), pack2(Sa[4], Sa[5]), pack2(Sa[6], Sa[7])};
;         u32x4 pb = {pack2(Sb[0], Sb[1]), pack2(Sb[2], Sb[3]), pack2(Sb[4], Sb[5]), pack2(Sb[6], Sb[7])};
;         f32x4 acc = {0.f, 0.f, 0.f, 0.f};
;         acc = __builtin_amdgcn_mfma_f32_16x16x32_bf16(A0, __builtin_bit_cast(bf16x8, pa), acc, 0, 0, 0);
;         acc = __builtin_amdgcn_mfma_f32_16x16x32_bf16(A1, __builtin_bit_cast(bf16x8, pb), acc, 0, 0, 0);
;         float tA[8], tB[8];
; #pragma unroll
;         for (int c = 0; c < 8; c++) { tA[c] = Sa[c] * wA[c] + v * kdA[c]; tB[c] = Sb[c] * wB[c] + v * kdB[c]; }
;         const float sa = -acc[0];
;         const float yq = acc[1];
; #pragma unroll
;         for (int c = 0; c < 8; c++) { Sa[c] = tA[c] + sa * kaA[c]; Sb[c] = tB[c] + sa * kaB[c]; }
;         const float y = yq + sa * c1 + v * c2;
;         if (quad == 0) by[s * 64 + row] = y;
;       }
	v_mfma_f32_16x16x32_bf16 v[32:35], v[70:73], v[24:27], 0
	v_cvt_pk_bf16_f32 v30, v20, v21
	v_cvt_pk_bf16_f32 v31, v22, v23
	v_fmac_f32_dpp v8, v95, v96 row_newbcast:0 row_mask:0xf bank_mask:0xf
	v_fmac_f32_dpp v9, v95, v96 row_newbcast:1 row_mask:0xf bank_mask:0xf
	v_mfma_f32_16x16x32_bf16 v[32:35], v[74:77], v[28:31], v[32:35]
	v_fmac_f32_dpp v10, v95, v96 row_newbcast:2 row_mask:0xf bank_mask:0xf
	v_fmac_f32_dpp v11, v95, v96 row_newbcast:3 row_mask:0xf bank_mask:0xf
	ds_read_b128 v[40:43], v104 offset:4096
	v_fmac_f32_dpp v12, v95, v96 row_newbcast:4 row_mask:0xf bank_mask:0xf
	v_fmac_f32_dpp v13, v95, v96 row_newbcast:5 row_mask:0xf bank_mask:0xf
	ds_read_b128 v[44:47], v104 offset:4112
	v_fmac_f32_dpp v14, v95, v96 row_newbcast:6 row_mask:0xf bank_mask:0xf
	v_fmac_f32_dpp v15, v95, v96 row_newbcast:7 row_mask:0xf bank_mask:0xf
	ds_read_b32 v65, v105 offset:20480
	v_fmac_f32_dpp v16, v95, v96 row_newbcast:8 row_mask:0xf bank_mask:0xf
	v_fmac_f32_dpp v17, v95, v96 row_newbcast:9 row_mask:0xf bank_mask:0xf
	ds_read_b32 v66, v107 offset:4096
	v_fmac_f32_dpp v18, v95, v96 row_newbcast:10 row_mask:0xf bank_mask:0xf
	v_fmac_f32_dpp v19, v95, v96 row_newbcast:11 row_mask:0xf bank_mask:0xf
	ds_read_b32 v48, v105 offset:12288
	v_fmac_f32_dpp v20, v95, v96 row_newbcast:12 row_mask:0xf bank_mask:0xf
	v_fmac_f32_dpp v21, v95, v96 row_newbcast:13 row_mask:0xf bank_mask:0xf
	ds_read_b64 v[68:69], v108 offset:49280
	v_fmac_f32_dpp v22, v95, v96 row_newbcast:14 row_mask:0xf bank_mask:0xf
	v_fmac_f32_dpp v23, v95, v96 row_newbcast:15 row_mask:0xf bank_mask:0xf
	s_waitcnt lgkmcnt(7)
	v_fmac_f32_dpp v8, v78, v32 row_newbcast:0 row_mask:0xf bank_mask:0xf
	v_fmac_f32_dpp v9, v78, v32 row_newbcast:1 row_mask:0xf bank_mask:0xf
	v_fmac_f32_dpp v10, v78, v32 row_newbcast:2 row_mask:0xf bank_mask:0xf
	v_fmac_f32_dpp v11, v78, v32 row_newbcast:3 row_mask:0xf bank_mask:0xf
	v_fmac_f32_dpp v12, v78, v32 row_newbcast:4 row_mask:0xf bank_mask:0xf
	v_fmac_f32_dpp v13, v78, v32 row_newbcast:5 row_mask:0xf bank_mask:0xf
	v_fmac_f32_dpp v14, v78, v32 row_newbcast:6 row_mask:0xf bank_mask:0xf
	v_fmac_f32_dpp v15, v78, v32 row_newbcast:7 row_mask:0xf bank_mask:0xf
	v_fmac_f32_dpp v16, v78, v32 row_newbcast:8 row_mask:0xf bank_mask:0xf
	v_fmac_f32_dpp v17, v78, v32 row_newbcast:9 row_mask:0xf bank_mask:0xf
	v_fmac_f32_dpp v18, v78, v32 row_newbcast:10 row_mask:0xf bank_mask:0xf
	v_fmac_f32_dpp v19, v78, v32 row_newbcast:11 row_mask:0xf bank_mask:0xf
	v_fmac_f32_dpp v20, v78, v32 row_newbcast:12 row_mask:0xf bank_mask:0xf
	v_fmac_f32_dpp v21, v78, v32 row_newbcast:13 row_mask:0xf bank_mask:0xf
	v_fmac_f32_dpp v22, v78, v32 row_newbcast:14 row_mask:0xf bank_mask:0xf
	v_fmac_f32_dpp v23, v78, v32 row_newbcast:15 row_mask:0xf bank_mask:0xf
	v_fma_f32 v109, -v32, v98, v33
	v_fma_f32 v109, v96, v99, v109
	v_mul_f32_dpp v8, v94, v8 row_newbcast:0 row_mask:0xf bank_mask:0xf
	v_mul_f32_dpp v9, v94, v9 row_newbcast:1 row_mask:0xf bank_mask:0xf
	v_mul_f32_dpp v10, v94, v10 row_newbcast:2 row_mask:0xf bank_mask:0xf
	v_mul_f32_dpp v11, v94, v11 row_newbcast:3 row_mask:0xf bank_mask:0xf
	v_mul_f32_dpp v12, v94, v12 row_newbcast:4 row_mask:0xf bank_mask:0xf
	v_mul_f32_dpp v13, v94, v13 row_newbcast:5 row_mask:0xf bank_mask:0xf
	v_mul_f32_dpp v14, v94, v14 row_newbcast:6 row_mask:0xf bank_mask:0xf
	v_mul_f32_dpp v15, v94, v15 row_newbcast:7 row_mask:0xf bank_mask:0xf
	v_mul_f32_dpp v16, v94, v16 row_newbcast:8 row_mask:0xf bank_mask:0xf
	v_mul_f32_dpp v17, v94, v17 row_newbcast:9 row_mask:0xf bank_mask:0xf
	v_mul_f32_dpp v18, v94, v18 row_newbcast:10 row_mask:0xf bank_mask:0xf
	v_mul_f32_dpp v19, v94, v19 row_newbcast:11 row_mask:0xf bank_mask:0xf
	v_mul_f32_dpp v20, v94, v20 row_newbcast:12 row_mask:0xf bank_mask:0xf
	v_mul_f32_dpp v21, v94, v21 row_newbcast:13 row_mask:0xf bank_mask:0xf
	v_mul_f32_dpp v22, v94, v22 row_newbcast:14 row_mask:0xf bank_mask:0xf
	v_mul_f32_dpp v23, v94, v23 row_newbcast:15 row_mask:0xf bank_mask:0xf
	ds_write_b32 v107, v109 offset:12032
	v_cvt_pk_bf16_f32 v24, v8, v9
	v_cvt_pk_bf16_f32 v25, v10, v11
	v_cvt_pk_bf16_f32 v26, v12, v13
	v_cvt_pk_bf16_f32 v27, v14, v15
	v_cvt_pk_bf16_f32 v28, v16, v17
	v_cvt_pk_bf16_f32 v29, v18, v19
	s_waitcnt lgkmcnt(3)
	v_mfma_f32_16x16x32_bf16 v[32:35], v[40:43], v[24:27], 0
	v_cvt_pk_bf16_f32 v30, v20, v21
	v_cvt_pk_bf16_f32 v31, v22, v23
	v_fmac_f32_dpp v8, v65, v66 row_newbcast:0 row_mask:0xf bank_mask:0xf
	v_fmac_f32_dpp v9, v65, v66 row_newbcast:1 row_mask:0xf bank_mask:0xf
	v_mfma_f32_16x16x32_bf16 v[32:35], v[44:47], v[28:31], v[32:35]
	v_fmac_f32_dpp v10, v65, v66 row_newbcast:2 row_mask:0xf bank_mask:0xf
	v_fmac_f32_dpp v11, v65, v66 row_newbcast:3 row_mask:0xf bank_mask:0xf
	ds_read_b128 v[70:73], v104 offset:4352
	v_fmac_f32_dpp v12, v65, v66 row_newbcast:4 row_mask:0xf bank_mask:0xf
	v_fmac_f32_dpp v13, v65, v66 row_newbcast:5 row_mask:0xf bank_mask:0xf
	ds_read_b128 v[74:77], v104 offset:4368
	v_fmac_f32_dpp v14, v65, v66 row_newbcast:6 row_mask:0xf bank_mask:0xf
	v_fmac_f32_dpp v15, v65, v66 row_newbcast:7 row_mask:0xf bank_mask:0xf
	ds_read_b32 v95, v105 offset:20736
	v_fmac_f32_dpp v16, v65, v66 row_newbcast:8 row_mask:0xf bank_mask:0xf
	v_fmac_f32_dpp v17, v65, v66 row_newbcast:9 row_mask:0xf bank_mask:0xf
	ds_read_b32 v96, v107 offset:4352
	v_fmac_f32_dpp v18, v65, v66 row_newbcast:10 row_mask:0xf bank_mask:0xf
	v_fmac_f32_dpp v19, v65, v66 row_newbcast:11 row_mask:0xf bank_mask:0xf
	ds_read_b32 v78, v105 offset:12544
	v_fmac_f32_dpp v20, v65, v66 row_newbcast:12 row_mask:0xf bank_mask:0xf
	v_fmac_f32_dpp v21, v65, v66 row_newbcast:13 row_mask:0xf bank_mask:0xf
	ds_read_b64 v[98:99], v108 offset:49288
	v_fmac_f32_dpp v22, v65, v66 row_newbcast:14 row_mask:0xf bank_mask:0xf
	v_fmac_f32_dpp v23, v65, v66 row_newbcast:15 row_mask:0xf bank_mask:0xf
	s_waitcnt lgkmcnt(7)
; __device__ __forceinline__ void phase_rwkv_scan(const Params& p, int l, const int tidx) {
;     ...
;       for (int s = 0; s < RTC; s++) {
;         const bf16x8 A0 = nA0, A1 = nA1;
;         const float wA[8] = {nw0.x, nw0.y, nw0.z, nw0.w, nw1.x, nw1.y, nw1.z, nw1.w};
;         const float wB[8] = {nw2.x, nw2.y, nw2.z, nw2.w, nw3.x, nw3.y, nw3.z, nw3.w};
;         const float kaA[8] = {nka0.x, nka0.y, nka0.z, nka0.w, nka1.x, nka1.y, nka1.z, nka1.w};
;         const float kaB[8] = {nka2.x, nka2.y, nka2.z, nka2.w, nka3.x, nka3.y, nka3.z, nka3.w};
;         const float kdA[8] = {nkd0.x, nkd0.y, nkd0.z, nkd0.w, nkd1.x, nkd1.y, nkd1.z, nkd1.w};
;         const float kdB[8] = {nkd2.x, nkd2.y, nkd2.z, nkd2.w, nkd3.x, nkd3.y, nkd3.z, nkd3.w};
;         const float v = nv;
;         float c1 = nc.x, c2 = nc.y;
;         asm volatile("" : "+v"(c1), "+v"(c2));
;         if (s + 1 < RTC) RW_LD(s + 1);
;         u32x4 pa = {pack2(Sa[0], Sa[1]), pack2(Sa[2], Sa[3]), pack2(Sa[4], Sa[5]), pack2(Sa[6], Sa[7])};
;         u32x4 pb = {pack2(Sb[0], Sb[1]), pack2(Sb[2], Sb[3]), pack2(Sb[4], Sb[5]), pack2(Sb[6], Sb[7])};
;         f32x4 acc = {0.f, 0.f, 0.f, 0.f};
;         acc = __builtin_amdgcn_mfma_f32_16x16x32_bf16(A0, __builtin_bit_cast(bf16x8, pa), acc, 0, 0, 0);
;         acc = __builtin_amdgcn_mfma_f32_16x16x32_bf16(A1, __builtin_bit_cast(bf16x8, pb), acc, 0, 0, 0);
;         float tA[8], tB[8];
; #pragma unroll
;         for (int c = 0; c < 8; c++) { tA[c] = Sa[c] * wA[c] + v * kdA[c]; tB[c] = Sb[c] * wB[c] + v * kdB[c]; }
;         const float sa = -acc[0];
;         const float yq = acc[1];
; #pragma unroll
;         for (int c = 0; c < 8; c++) { Sa[c] = tA[c] + sa * kaA[c]; Sb[c] = tB[c] + sa * kaB[c]; }
;         const float y = yq + sa * c1 + v * c2;
;         if (quad == 0) by[s * 64 + row] = y;
;       }
	v_fmac_f32_dpp v8, v48, v32 row_newbcast:0 row_mask:0xf bank_mask:0xf
	v_fmac_f32_dpp v9, v48, v32 row_newbcast:1 row_mask:0xf bank_mask:0xf
	v_fmac_f32_dpp v10, v48, v32 row_newbcast:2 row_mask:0xf bank_mask:0xf
	v_fmac_f32_dpp v11, v48, v32 row_newbcast:3 row_mask:0xf bank_mask:0xf
	v_fmac_f32_dpp v12, v48, v32 row_newbcast:4 row_mask:0xf bank_mask:0xf
	v_fmac_f32_dpp v13, v48, v32 row_newbcast:5 row_mask:0xf bank_mask:0xf
	v_fmac_f32_dpp v14, v48, v32 row_newbcast:6 row_mask:0xf bank_mask:0xf
	v_fmac_f32_dpp v15, v48, v32 row_newbcast:7 row_mask:0xf bank_mask:0xf
	v_fmac_f32_dpp v16, v48, v32 row_newbcast:8 row_mask:0xf bank_mask:0xf
	v_fmac_f32_dpp v17, v48, v32 row_newbcast:9 row_mask:0xf bank_mask:0xf
	v_fmac_f32_dpp v18, v48, v32 row_newbcast:10 row_mask:0xf bank_mask:0xf
	v_fmac_f32_dpp v19, v48, v32 row_newbcast:11 row_mask:0xf bank_mask:0xf
	v_fmac_f32_dpp v20, v48, v32 row_newbcast:12 row_mask:0xf bank_mask:0xf
	v_fmac_f32_dpp v21, v48, v32 row_newbcast:13 row_mask:0xf bank_mask:0xf
	v_fmac_f32_dpp v22, v48, v32 row_newbcast:14 row_mask:0xf bank_mask:0xf
	v_fmac_f32_dpp v23, v48, v32 row_newbcast:15 row_mask:0xf bank_mask:0xf
	v_fma_f32 v109, -v32, v68, v33
	v_fma_f32 v109, v66, v69, v109
	ds_write_b32 v107, v109 offset:12288
	v_cvt_pk_bf16_f32 v24, v8, v9
	v_cvt_pk_bf16_f32 v25, v10, v11
	v_cvt_pk_bf16_f32 v26, v12, v13
	v_cvt_pk_bf16_f32 v27, v14, v15
	v_cvt_pk_bf16_f32 v28, v16, v17
	v_cvt_pk_bf16_f32 v29, v18, v19
	s_waitcnt lgkmcnt(3)
	v_mfma_f32_16x16x32_bf16 v[32:35], v[70:73], v[24:27], 0
	v_cvt_pk_bf16_f32 v30, v20, v21
	v_cvt_pk_bf16_f32 v31, v22, v23
	v_fmac_f32_dpp v8, v95, v96 row_newbcast:0 row_mask:0xf bank_mask:0xf
	v_fmac_f32_dpp v9, v95, v96 row_newbcast:1 row_mask:0xf bank_mask:0xf
	v_mfma_f32_16x16x32_bf16 v[32:35], v[74:77], v[28:31], v[32:35]
	v_fmac_f32_dpp v10, v95, v96 row_newbcast:2 row_mask:0xf bank_mask:0xf
	v_fmac_f32_dpp v11, v95, v96 row_newbcast:3 row_mask:0xf bank_mask:0xf
	ds_read_b128 v[40:43], v104 offset:4608
	v_fmac_f32_dpp v12, v95, v96 row_newbcast:4 row_mask:0xf bank_mask:0xf
	v_fmac_f32_dpp v13, v95, v96 row_newbcast:5 row_mask:0xf bank_mask:0xf
	ds_read_b128 v[44:47], v104 offset:4624
	v_fmac_f32_dpp v14, v95, v96 row_newbcast:6 row_mask:0xf bank_mask:0xf
	v_fmac_f32_dpp v15, v95, v96 row_newbcast:7 row_mask:0xf bank_mask:0xf
	ds_read_b32 v65, v105 offset:20992
	v_fmac_f32_dpp v16, v95, v96 row_newbcast:8 row_mask:0xf bank_mask:0xf
	v_fmac_f32_dpp v17, v95, v96 row_newbcast:9 row_mask:0xf bank_mask:0xf
	ds_read_b32 v66, v107 offset:4608
	v_fmac_f32_dpp v18, v95, v96 row_newbcast:10 row_mask:0xf bank_mask:0xf
	v_fmac_f32_dpp v19, v95, v96 row_newbcast:11 row_mask:0xf bank_mask:0xf
	ds_read_b32 v48, v105 offset:12800
	v_fmac_f32_dpp v20, v95, v96 row_newbcast:12 row_mask:0xf bank_mask:0xf
	v_fmac_f32_dpp v21, v95, v96 row_newbcast:13 row_mask:0xf bank_mask:0xf
	ds_read_b64 v[68:69], v108 offset:49296
	v_fmac_f32_dpp v22, v95, v96 row_newbcast:14 row_mask:0xf bank_mask:0xf
	v_fmac_f32_dpp v23, v95, v96 row_newbcast:15 row_mask:0xf bank_mask:0xf
	s_waitcnt lgkmcnt(7)
	v_fmac_f32_dpp v8, v78, v32 row_newbcast:0 row_mask:0xf bank_mask:0xf
	v_fmac_f32_dpp v9, v78, v32 row_newbcast:1 row_mask:0xf bank_mask:0xf
	v_fmac_f32_dpp v10, v78, v32 row_newbcast:2 row_mask:0xf bank_mask:0xf
	v_fmac_f32_dpp v11, v78, v32 row_newbcast:3 row_mask:0xf bank_mask:0xf
	v_fmac_f32_dpp v12, v78, v32 row_newbcast:4 row_mask:0xf bank_mask:0xf
	v_fmac_f32_dpp v13, v78, v32 row_newbcast:5 row_mask:0xf bank_mask:0xf
	v_fmac_f32_dpp v14, v78, v32 row_newbcast:6 row_mask:0xf bank_mask:0xf
	v_fmac_f32_dpp v15, v78, v32 row_newbcast:7 row_mask:0xf bank_mask:0xf
	v_fmac_f32_dpp v16, v78, v32 row_newbcast:8 row_mask:0xf bank_mask:0xf
	v_fmac_f32_dpp v17, v78, v32 row_newbcast:9 row_mask:0xf bank_mask:0xf
	v_fmac_f32_dpp v18, v78, v32 row_newbcast:10 row_mask:0xf bank_mask:0xf
	v_fmac_f32_dpp v19, v78, v32 row_newbcast:11 row_mask:0xf bank_mask:0xf
	v_fmac_f32_dpp v20, v78, v32 row_newbcast:12 row_mask:0xf bank_mask:0xf
	v_fmac_f32_dpp v21, v78, v32 row_newbcast:13 row_mask:0xf bank_mask:0xf
	v_fmac_f32_dpp v22, v78, v32 row_newbcast:14 row_mask:0xf bank_mask:0xf
	v_fmac_f32_dpp v23, v78, v32 row_newbcast:15 row_mask:0xf bank_mask:0xf
	v_fma_f32 v109, -v32, v98, v33
	v_fma_f32 v109, v96, v99, v109
	ds_write_b32 v107, v109 offset:12544
	v_cvt_pk_bf16_f32 v24, v8, v9
	v_cvt_pk_bf16_f32 v25, v10, v11
	v_cvt_pk_bf16_f32 v26, v12, v13
	v_cvt_pk_bf16_f32 v27, v14, v15
	v_cvt_pk_bf16_f32 v28, v16, v17
	v_cvt_pk_bf16_f32 v29, v18, v19
	s_waitcnt lgkmcnt(3)
	v_mfma_f32_16x16x32_bf16 v[32:35], v[40:43], v[24:27], 0
	v_cvt_pk_bf16_f32 v30, v20, v21
	v_cvt_pk_bf16_f32 v31, v22, v23
	v_fmac_f32_dpp v8, v65, v66 row_newbcast:0 row_mask:0xf bank_mask:0xf
	v_fmac_f32_dpp v9, v65, v66 row_newbcast:1 row_mask:0xf bank_mask:0xf
	v_mfma_f32_16x16x32_bf16 v[32:35], v[44:47], v[28:31], v[32:35]
	v_fmac_f32_dpp v10, v65, v66 row_newbcast:2 row_mask:0xf bank_mask:0xf
	v_fmac_f32_dpp v11, v65, v66 row_newbcast:3 row_mask:0xf bank_mask:0xf
	ds_read_b128 v[70:73], v104 offset:4864
	v_fmac_f32_dpp v12, v65, v66 row_newbcast:4 row_mask:0xf bank_mask:0xf
	v_fmac_f32_dpp v13, v65, v66 row_newbcast:5 row_mask:0xf bank_mask:0xf
	ds_read_b128 v[74:77], v104 offset:4880
	v_fmac_f32_dpp v14, v65, v66 row_newbcast:6 row_mask:0xf bank_mask:0xf
	v_fmac_f32_dpp v15, v65, v66 row_newbcast:7 row_mask:0xf bank_mask:0xf
	ds_read_b32 v95, v105 offset:21248
	v_fmac_f32_dpp v16, v65, v66 row_newbcast:8 row_mask:0xf bank_mask:0xf
	v_fmac_f32_dpp v17, v65, v66 row_newbcast:9 row_mask:0xf bank_mask:0xf
	ds_read_b32 v96, v107 offset:4864
	v_fmac_f32_dpp v18, v65, v66 row_newbcast:10 row_mask:0xf bank_mask:0xf
	v_fmac_f32_dpp v19, v65, v66 row_newbcast:11 row_mask:0xf bank_mask:0xf
	ds_read_b32 v78, v105 offset:13056
	v_fmac_f32_dpp v20, v65, v66 row_newbcast:12 row_mask:0xf bank_mask:0xf
	v_fmac_f32_dpp v21, v65, v66 row_newbcast:13 row_mask:0xf bank_mask:0xf
	ds_read_b64 v[98:99], v108 offset:49304
	v_fmac_f32_dpp v22, v65, v66 row_newbcast:14 row_mask:0xf bank_mask:0xf
	v_fmac_f32_dpp v23, v65, v66 row_newbcast:15 row_mask:0xf bank_mask:0xf
	s_waitcnt lgkmcnt(7)
; __device__ __forceinline__ void phase_rwkv_scan(const Params& p, int l, const int tidx) {
;     ...
;       for (int s = 0; s < RTC; s++) {
;         const bf16x8 A0 = nA0, A1 = nA1;
;         const float wA[8] = {nw0.x, nw0.y, nw0.z, nw0.w, nw1.x, nw1.y, nw1.z, nw1.w};
;         const float wB[8] = {nw2.x, nw2.y, nw2.z, nw2.w, nw3.x, nw3.y, nw3.z, nw3.w};
;         const float kaA[8] = {nka0.x, nka0.y, nka0.z, nka0.w, nka1.x, nka1.y, nka1.z, nka1.w};
;         const float kaB[8] = {nka2.x, nka2.y, nka2.z, nka2.w, nka3.x, nka3.y, nka3.z, nka3.w};
;         const float kdA[8] = {nkd0.x, nkd0.y, nkd0.z, nkd0.w, nkd1.x, nkd1.y, nkd1.z, nkd1.w};
;         const float kdB[8] = {nkd2.x, nkd2.y, nkd2.z, nkd2.w, nkd3.x, nkd3.y, nkd3.z, nkd3.w};
;         const float v = nv;
;         float c1 = nc.x, c2 = nc.y;
;         asm volatile("" : "+v"(c1), "+v"(c2));
;         if (s + 1 < RTC) RW_LD(s + 1);
;         u32x4 pa = {pack2(Sa[0], Sa[1]), pack2(Sa[2], Sa[3]), pack2(Sa[4], Sa[5]), pack2(Sa[6], Sa[7])};
;         u32x4 pb = {pack2(Sb[0], Sb[1]), pack2(Sb[2], Sb[3]), pack2(Sb[4], Sb[5]), pack2(Sb[6], Sb[7])};
;         f32x4 acc = {0.f, 0.f, 0.f, 0.f};
;         acc = __builtin_amdgcn_mfma_f32_16x16x32_bf16(A0, __builtin_bit_cast(bf16x8, pa), acc, 0, 0, 0);
;         acc = __builtin_amdgcn_mfma_f32_16x16x32_bf16(A1, __builtin_bit_cast(bf16x8, pb), acc, 0, 0, 0);
;         float tA[8], tB[8];
; #pragma unroll
;         for (int c = 0; c < 8; c++) { tA[c] = Sa[c] * wA[c] + v * kdA[c]; tB[c] = Sb[c] * wB[c] + v * kdB[c]; }
;         const float sa = -acc[0];
;         const float yq = acc[1];
; #pragma unroll
;         for (int c = 0; c < 8; c++) { Sa[c] = tA[c] + sa * kaA[c]; Sb[c] = tB[c] + sa * kaB[c]; }
;         const float y = yq + sa * c1 + v * c2;
;         if (quad == 0) by[s * 64 + row] = y;
;       }
	v_fmac_f32_dpp v8, v48, v32 row_newbcast:0 row_mask:0xf bank_mask:0xf
	v_fmac_f32_dpp v9, v48, v32 row_newbcast:1 row_mask:0xf bank_mask:0xf
	v_fmac_f32_dpp v10, v48, v32 row_newbcast:2 row_mask:0xf bank_mask:0xf
	v_fmac_f32_dpp v11, v48, v32 row_newbcast:3 row_mask:0xf bank_mask:0xf
	v_fmac_f32_dpp v12, v48, v32 row_newbcast:4 row_mask:0xf bank_mask:0xf
	v_fmac_f32_dpp v13, v48, v32 row_newbcast:5 row_mask:0xf bank_mask:0xf
	v_fmac_f32_dpp v14, v48, v32 row_newbcast:6 row_mask:0xf bank_mask:0xf
	v_fmac_f32_dpp v15, v48, v32 row_newbcast:7 row_mask:0xf bank_mask:0xf
	v_fmac_f32_dpp v16, v48, v32 row_newbcast:8 row_mask:0xf bank_mask:0xf
	v_fmac_f32_dpp v17, v48, v32 row_newbcast:9 row_mask:0xf bank_mask:0xf
	v_fmac_f32_dpp v18, v48, v32 row_newbcast:10 row_mask:0xf bank_mask:0xf
	v_fmac_f32_dpp v19, v48, v32 row_newbcast:11 row_mask:0xf bank_mask:0xf
	v_fmac_f32_dpp v20, v48, v32 row_newbcast:12 row_mask:0xf bank_mask:0xf
	v_fmac_f32_dpp v21, v48, v32 row_newbcast:13 row_mask:0xf bank_mask:0xf
	v_fmac_f32_dpp v22, v48, v32 row_newbcast:14 row_mask:0xf bank_mask:0xf
	v_fmac_f32_dpp v23, v48, v32 row_newbcast:15 row_mask:0xf bank_mask:0xf
	v_fma_f32 v109, -v32, v68, v33
	v_fma_f32 v109, v66, v69, v109
	ds_write_b32 v107, v109 offset:12800
	v_cvt_pk_bf16_f32 v24, v8, v9
	v_cvt_pk_bf16_f32 v25, v10, v11
	v_cvt_pk_bf16_f32 v26, v12, v13
	v_cvt_pk_bf16_f32 v27, v14, v15
	v_cvt_pk_bf16_f32 v28, v16, v17
	v_cvt_pk_bf16_f32 v29, v18, v19
	s_waitcnt lgkmcnt(3)
	v_mfma_f32_16x16x32_bf16 v[32:35], v[70:73], v[24:27], 0
	v_cvt_pk_bf16_f32 v30, v20, v21
	v_cvt_pk_bf16_f32 v31, v22, v23
	v_fmac_f32_dpp v8, v95, v96 row_newbcast:0 row_mask:0xf bank_mask:0xf
	v_fmac_f32_dpp v9, v95, v96 row_newbcast:1 row_mask:0xf bank_mask:0xf
	v_mfma_f32_16x16x32_bf16 v[32:35], v[74:77], v[28:31], v[32:35]
	v_fmac_f32_dpp v10, v95, v96 row_newbcast:2 row_mask:0xf bank_mask:0xf
	v_fmac_f32_dpp v11, v95, v96 row_newbcast:3 row_mask:0xf bank_mask:0xf
	ds_read_b128 v[40:43], v104 offset:5120
	v_fmac_f32_dpp v12, v95, v96 row_newbcast:4 row_mask:0xf bank_mask:0xf
	v_fmac_f32_dpp v13, v95, v96 row_newbcast:5 row_mask:0xf bank_mask:0xf
	ds_read_b128 v[44:47], v104 offset:5136
	v_fmac_f32_dpp v14, v95, v96 row_newbcast:6 row_mask:0xf bank_mask:0xf
	v_fmac_f32_dpp v15, v95, v96 row_newbcast:7 row_mask:0xf bank_mask:0xf
	ds_read_b32 v65, v105 offset:21504
	v_fmac_f32_dpp v16, v95, v96 row_newbcast:8 row_mask:0xf bank_mask:0xf
	v_fmac_f32_dpp v17, v95, v96 row_newbcast:9 row_mask:0xf bank_mask:0xf
	ds_read_b32 v66, v107 offset:5120
	v_fmac_f32_dpp v18, v95, v96 row_newbcast:10 row_mask:0xf bank_mask:0xf
	v_fmac_f32_dpp v19, v95, v96 row_newbcast:11 row_mask:0xf bank_mask:0xf
	ds_read_b32 v48, v105 offset:13312
	v_fmac_f32_dpp v20, v95, v96 row_newbcast:12 row_mask:0xf bank_mask:0xf
	v_fmac_f32_dpp v21, v95, v96 row_newbcast:13 row_mask:0xf bank_mask:0xf
	ds_read_b64 v[68:69], v108 offset:49312
	v_fmac_f32_dpp v22, v95, v96 row_newbcast:14 row_mask:0xf bank_mask:0xf
	v_fmac_f32_dpp v23, v95, v96 row_newbcast:15 row_mask:0xf bank_mask:0xf
	s_waitcnt lgkmcnt(7)
	v_fmac_f32_dpp v8, v78, v32 row_newbcast:0 row_mask:0xf bank_mask:0xf
	v_fmac_f32_dpp v9, v78, v32 row_newbcast:1 row_mask:0xf bank_mask:0xf
	v_fmac_f32_dpp v10, v78, v32 row_newbcast:2 row_mask:0xf bank_mask:0xf
	v_fmac_f32_dpp v11, v78, v32 row_newbcast:3 row_mask:0xf bank_mask:0xf
	v_fmac_f32_dpp v12, v78, v32 row_newbcast:4 row_mask:0xf bank_mask:0xf
	v_fmac_f32_dpp v13, v78, v32 row_newbcast:5 row_mask:0xf bank_mask:0xf
	v_fmac_f32_dpp v14, v78, v32 row_newbcast:6 row_mask:0xf bank_mask:0xf
	v_fmac_f32_dpp v15, v78, v32 row_newbcast:7 row_mask:0xf bank_mask:0xf
	v_fmac_f32_dpp v16, v78, v32 row_newbcast:8 row_mask:0xf bank_mask:0xf
	v_fmac_f32_dpp v17, v78, v32 row_newbcast:9 row_mask:0xf bank_mask:0xf
	v_fmac_f32_dpp v18, v78, v32 row_newbcast:10 row_mask:0xf bank_mask:0xf
	v_fmac_f32_dpp v19, v78, v32 row_newbcast:11 row_mask:0xf bank_mask:0xf
	v_fmac_f32_dpp v20, v78, v32 row_newbcast:12 row_mask:0xf bank_mask:0xf
	v_fmac_f32_dpp v21, v78, v32 row_newbcast:13 row_mask:0xf bank_mask:0xf
	v_fmac_f32_dpp v22, v78, v32 row_newbcast:14 row_mask:0xf bank_mask:0xf
	v_fmac_f32_dpp v23, v78, v32 row_newbcast:15 row_mask:0xf bank_mask:0xf
	v_fma_f32 v109, -v32, v98, v33
	v_fma_f32 v109, v96, v99, v109
	ds_write_b32 v107, v109 offset:13056
	v_cvt_pk_bf16_f32 v24, v8, v9
	v_cvt_pk_bf16_f32 v25, v10, v11
	v_cvt_pk_bf16_f32 v26, v12, v13
	v_cvt_pk_bf16_f32 v27, v14, v15
	v_cvt_pk_bf16_f32 v28, v16, v17
	v_cvt_pk_bf16_f32 v29, v18, v19
	s_waitcnt lgkmcnt(3)
	v_mfma_f32_16x16x32_bf16 v[32:35], v[40:43], v[24:27], 0
	v_cvt_pk_bf16_f32 v30, v20, v21
	v_cvt_pk_bf16_f32 v31, v22, v23
	v_fmac_f32_dpp v8, v65, v66 row_newbcast:0 row_mask:0xf bank_mask:0xf
	v_fmac_f32_dpp v9, v65, v66 row_newbcast:1 row_mask:0xf bank_mask:0xf
	v_mfma_f32_16x16x32_bf16 v[32:35], v[44:47], v[28:31], v[32:35]
	v_fmac_f32_dpp v10, v65, v66 row_newbcast:2 row_mask:0xf bank_mask:0xf
	v_fmac_f32_dpp v11, v65, v66 row_newbcast:3 row_mask:0xf bank_mask:0xf
	ds_read_b128 v[70:73], v104 offset:5376
	v_fmac_f32_dpp v12, v65, v66 row_newbcast:4 row_mask:0xf bank_mask:0xf
	v_fmac_f32_dpp v13, v65, v66 row_newbcast:5 row_mask:0xf bank_mask:0xf
	ds_read_b128 v[74:77], v104 offset:5392
	v_fmac_f32_dpp v14, v65, v66 row_newbcast:6 row_mask:0xf bank_mask:0xf
	v_fmac_f32_dpp v15, v65, v66 row_newbcast:7 row_mask:0xf bank_mask:0xf
	ds_read_b32 v95, v105 offset:21760
	v_fmac_f32_dpp v16, v65, v66 row_newbcast:8 row_mask:0xf bank_mask:0xf
	v_fmac_f32_dpp v17, v65, v66 row_newbcast:9 row_mask:0xf bank_mask:0xf
	ds_read_b32 v96, v107 offset:5376
	v_fmac_f32_dpp v18, v65, v66 row_newbcast:10 row_mask:0xf bank_mask:0xf
	v_fmac_f32_dpp v19, v65, v66 row_newbcast:11 row_mask:0xf bank_mask:0xf
	ds_read_b32 v78, v105 offset:13568
	v_fmac_f32_dpp v20, v65, v66 row_newbcast:12 row_mask:0xf bank_mask:0xf
	v_fmac_f32_dpp v21, v65, v66 row_newbcast:13 row_mask:0xf bank_mask:0xf
	ds_read_b64 v[98:99], v108 offset:49320
	v_fmac_f32_dpp v22, v65, v66 row_newbcast:14 row_mask:0xf bank_mask:0xf
	v_fmac_f32_dpp v23, v65, v66 row_newbcast:15 row_mask:0xf bank_mask:0xf
	s_waitcnt lgkmcnt(7)
; __device__ __forceinline__ void phase_rwkv_scan(const Params& p, int l, const int tidx) {
;     ...
;       for (int s = 0; s < RTC; s++) {
;         const bf16x8 A0 = nA0, A1 = nA1;
;         const float wA[8] = {nw0.x, nw0.y, nw0.z, nw0.w, nw1.x, nw1.y, nw1.z, nw1.w};
;         const float wB[8] = {nw2.x, nw2.y, nw2.z, nw2.w, nw3.x, nw3.y, nw3.z, nw3.w};
;         const float kaA[8] = {nka0.x, nka0.y, nka0.z, nka0.w, nka1.x, nka1.y, nka1.z, nka1.w};
;         const float kaB[8] = {nka2.x, nka2.y, nka2.z, nka2.w, nka3.x, nka3.y, nka3.z, nka3.w};
;         const float kdA[8] = {nkd0.x, nkd0.y, nkd0.z, nkd0.w, nkd1.x, nkd1.y, nkd1.z, nkd1.w};
;         const float kdB[8] = {nkd2.x, nkd2.y, nkd2.z, nkd2.w, nkd3.x, nkd3.y, nkd3.z, nkd3.w};
;         const float v = nv;
;         float c1 = nc.x, c2 = nc.y;
;         asm volatile("" : "+v"(c1), "+v"(c2));
;         if (s + 1 < RTC) RW_LD(s + 1);
;         u32x4 pa = {pack2(Sa[0], Sa[1]), pack2(Sa[2], Sa[3]), pack2(Sa[4], Sa[5]), pack2(Sa[6], Sa[7])};
;         u32x4 pb = {pack2(Sb[0], Sb[1]), pack2(Sb[2], Sb[3]), pack2(Sb[4], Sb[5]), pack2(Sb[6], Sb[7])};
;         f32x4 acc = {0.f, 0.f, 0.f, 0.f};
;         acc = __builtin_amdgcn_mfma_f32_16x16x32_bf16(A0, __builtin_bit_cast(bf16x8, pa), acc, 0, 0, 0);
;         acc = __builtin_amdgcn_mfma_f32_16x16x32_bf16(A1, __builtin_bit_cast(bf16x8, pb), acc, 0, 0, 0);
;         float tA[8], tB[8];
; #pragma unroll
;         for (int c = 0; c < 8; c++) { tA[c] = Sa[c] * wA[c] + v * kdA[c]; tB[c] = Sb[c] * wB[c] + v * kdB[c]; }
;         const float sa = -acc[0];
;         const float yq = acc[1];
; #pragma unroll
;         for (int c = 0; c < 8; c++) { Sa[c] = tA[c] + sa * kaA[c]; Sb[c] = tB[c] + sa * kaB[c]; }
;         const float y = yq + sa * c1 + v * c2;
;         if (quad == 0) by[s * 64 + row] = y;
;       }
	v_fmac_f32_dpp v8, v48, v32 row_newbcast:0 row_mask:0xf bank_mask:0xf
	v_fmac_f32_dpp v9, v48, v32 row_newbcast:1 row_mask:0xf bank_mask:0xf
	v_fmac_f32_dpp v10, v48, v32 row_newbcast:2 row_mask:0xf bank_mask:0xf
	v_fmac_f32_dpp v11, v48, v32 row_newbcast:3 row_mask:0xf bank_mask:0xf
	v_fmac_f32_dpp v12, v48, v32 row_newbcast:4 row_mask:0xf bank_mask:0xf
	v_fmac_f32_dpp v13, v48, v32 row_newbcast:5 row_mask:0xf bank_mask:0xf
	v_fmac_f32_dpp v14, v48, v32 row_newbcast:6 row_mask:0xf bank_mask:0xf
	v_fmac_f32_dpp v15, v48, v32 row_newbcast:7 row_mask:0xf bank_mask:0xf
	v_fmac_f32_dpp v16, v48, v32 row_newbcast:8 row_mask:0xf bank_mask:0xf
	v_fmac_f32_dpp v17, v48, v32 row_newbcast:9 row_mask:0xf bank_mask:0xf
	v_fmac_f32_dpp v18, v48, v32 row_newbcast:10 row_mask:0xf bank_mask:0xf
	v_fmac_f32_dpp v19, v48, v32 row_newbcast:11 row_mask:0xf bank_mask:0xf
	v_fmac_f32_dpp v20, v48, v32 row_newbcast:12 row_mask:0xf bank_mask:0xf
	v_fmac_f32_dpp v21, v48, v32 row_newbcast:13 row_mask:0xf bank_mask:0xf
	v_fmac_f32_dpp v22, v48, v32 row_newbcast:14 row_mask:0xf bank_mask:0xf
	v_fmac_f32_dpp v23, v48, v32 row_newbcast:15 row_mask:0xf bank_mask:0xf
	v_fma_f32 v109, -v32, v68, v33
	v_fma_f32 v109, v66, v69, v109
	ds_write_b32 v107, v109 offset:13312
	v_cvt_pk_bf16_f32 v24, v8, v9
	v_cvt_pk_bf16_f32 v25, v10, v11
	v_cvt_pk_bf16_f32 v26, v12, v13
	v_cvt_pk_bf16_f32 v27, v14, v15
	v_cvt_pk_bf16_f32 v28, v16, v17
	v_cvt_pk_bf16_f32 v29, v18, v19
	s_waitcnt lgkmcnt(3)
	v_mfma_f32_16x16x32_bf16 v[32:35], v[70:73], v[24:27], 0
	v_cvt_pk_bf16_f32 v30, v20, v21
	v_cvt_pk_bf16_f32 v31, v22, v23
	v_fmac_f32_dpp v8, v95, v96 row_newbcast:0 row_mask:0xf bank_mask:0xf
	v_fmac_f32_dpp v9, v95, v96 row_newbcast:1 row_mask:0xf bank_mask:0xf
	v_mfma_f32_16x16x32_bf16 v[32:35], v[74:77], v[28:31], v[32:35]
	v_fmac_f32_dpp v10, v95, v96 row_newbcast:2 row_mask:0xf bank_mask:0xf
	v_fmac_f32_dpp v11, v95, v96 row_newbcast:3 row_mask:0xf bank_mask:0xf
	ds_read_b128 v[40:43], v104 offset:5632
	v_fmac_f32_dpp v12, v95, v96 row_newbcast:4 row_mask:0xf bank_mask:0xf
	v_fmac_f32_dpp v13, v95, v96 row_newbcast:5 row_mask:0xf bank_mask:0xf
	ds_read_b128 v[44:47], v104 offset:5648
	v_fmac_f32_dpp v14, v95, v96 row_newbcast:6 row_mask:0xf bank_mask:0xf
	v_fmac_f32_dpp v15, v95, v96 row_newbcast:7 row_mask:0xf bank_mask:0xf
	ds_read_b32 v65, v105 offset:22016
	v_fmac_f32_dpp v16, v95, v96 row_newbcast:8 row_mask:0xf bank_mask:0xf
	v_fmac_f32_dpp v17, v95, v96 row_newbcast:9 row_mask:0xf bank_mask:0xf
	ds_read_b32 v66, v107 offset:5632
	v_fmac_f32_dpp v18, v95, v96 row_newbcast:10 row_mask:0xf bank_mask:0xf
	v_fmac_f32_dpp v19, v95, v96 row_newbcast:11 row_mask:0xf bank_mask:0xf
	ds_read_b32 v48, v105 offset:13824
	v_fmac_f32_dpp v20, v95, v96 row_newbcast:12 row_mask:0xf bank_mask:0xf
	v_fmac_f32_dpp v21, v95, v96 row_newbcast:13 row_mask:0xf bank_mask:0xf
	ds_read_b64 v[68:69], v108 offset:49328
	v_fmac_f32_dpp v22, v95, v96 row_newbcast:14 row_mask:0xf bank_mask:0xf
	v_fmac_f32_dpp v23, v95, v96 row_newbcast:15 row_mask:0xf bank_mask:0xf
	s_waitcnt lgkmcnt(7)
	v_fmac_f32_dpp v8, v78, v32 row_newbcast:0 row_mask:0xf bank_mask:0xf
	v_fmac_f32_dpp v9, v78, v32 row_newbcast:1 row_mask:0xf bank_mask:0xf
	v_fmac_f32_dpp v10, v78, v32 row_newbcast:2 row_mask:0xf bank_mask:0xf
	v_fmac_f32_dpp v11, v78, v32 row_newbcast:3 row_mask:0xf bank_mask:0xf
	v_fmac_f32_dpp v12, v78, v32 row_newbcast:4 row_mask:0xf bank_mask:0xf
	v_fmac_f32_dpp v13, v78, v32 row_newbcast:5 row_mask:0xf bank_mask:0xf
	v_fmac_f32_dpp v14, v78, v32 row_newbcast:6 row_mask:0xf bank_mask:0xf
	v_fmac_f32_dpp v15, v78, v32 row_newbcast:7 row_mask:0xf bank_mask:0xf
	v_fmac_f32_dpp v16, v78, v32 row_newbcast:8 row_mask:0xf bank_mask:0xf
	v_fmac_f32_dpp v17, v78, v32 row_newbcast:9 row_mask:0xf bank_mask:0xf
	v_fmac_f32_dpp v18, v78, v32 row_newbcast:10 row_mask:0xf bank_mask:0xf
	v_fmac_f32_dpp v19, v78, v32 row_newbcast:11 row_mask:0xf bank_mask:0xf
	v_fmac_f32_dpp v20, v78, v32 row_newbcast:12 row_mask:0xf bank_mask:0xf
	v_fmac_f32_dpp v21, v78, v32 row_newbcast:13 row_mask:0xf bank_mask:0xf
	v_fmac_f32_dpp v22, v78, v32 row_newbcast:14 row_mask:0xf bank_mask:0xf
	v_fmac_f32_dpp v23, v78, v32 row_newbcast:15 row_mask:0xf bank_mask:0xf
	v_fma_f32 v109, -v32, v98, v33
	v_fma_f32 v109, v96, v99, v109
	ds_write_b32 v107, v109 offset:13568
	v_cvt_pk_bf16_f32 v24, v8, v9
	v_cvt_pk_bf16_f32 v25, v10, v11
	v_cvt_pk_bf16_f32 v26, v12, v13
	v_cvt_pk_bf16_f32 v27, v14, v15
	v_cvt_pk_bf16_f32 v28, v16, v17
	v_cvt_pk_bf16_f32 v29, v18, v19
	s_waitcnt lgkmcnt(3)
	v_mfma_f32_16x16x32_bf16 v[32:35], v[40:43], v[24:27], 0
	v_cvt_pk_bf16_f32 v30, v20, v21
	v_cvt_pk_bf16_f32 v31, v22, v23
	v_fmac_f32_dpp v8, v65, v66 row_newbcast:0 row_mask:0xf bank_mask:0xf
	v_fmac_f32_dpp v9, v65, v66 row_newbcast:1 row_mask:0xf bank_mask:0xf
	v_mfma_f32_16x16x32_bf16 v[32:35], v[44:47], v[28:31], v[32:35]
	v_fmac_f32_dpp v10, v65, v66 row_newbcast:2 row_mask:0xf bank_mask:0xf
	v_fmac_f32_dpp v11, v65, v66 row_newbcast:3 row_mask:0xf bank_mask:0xf
	ds_read_b128 v[70:73], v104 offset:5888
	v_fmac_f32_dpp v12, v65, v66 row_newbcast:4 row_mask:0xf bank_mask:0xf
	v_fmac_f32_dpp v13, v65, v66 row_newbcast:5 row_mask:0xf bank_mask:0xf
	ds_read_b128 v[74:77], v104 offset:5904
	v_fmac_f32_dpp v14, v65, v66 row_newbcast:6 row_mask:0xf bank_mask:0xf
	v_fmac_f32_dpp v15, v65, v66 row_newbcast:7 row_mask:0xf bank_mask:0xf
	ds_read_b32 v95, v105 offset:22272
	v_fmac_f32_dpp v16, v65, v66 row_newbcast:8 row_mask:0xf bank_mask:0xf
	v_fmac_f32_dpp v17, v65, v66 row_newbcast:9 row_mask:0xf bank_mask:0xf
	ds_read_b32 v96, v107 offset:5888
	v_fmac_f32_dpp v18, v65, v66 row_newbcast:10 row_mask:0xf bank_mask:0xf
	v_fmac_f32_dpp v19, v65, v66 row_newbcast:11 row_mask:0xf bank_mask:0xf
	ds_read_b32 v94, v105 offset:5888
	v_fmac_f32_dpp v20, v65, v66 row_newbcast:12 row_mask:0xf bank_mask:0xf
	v_fmac_f32_dpp v21, v65, v66 row_newbcast:13 row_mask:0xf bank_mask:0xf
	ds_read_b32 v78, v105 offset:14080
	v_fmac_f32_dpp v22, v65, v66 row_newbcast:14 row_mask:0xf bank_mask:0xf
	v_fmac_f32_dpp v23, v65, v66 row_newbcast:15 row_mask:0xf bank_mask:0xf
	ds_read_b64 v[98:99], v108 offset:49336
	s_waitcnt lgkmcnt(8)
; __device__ __forceinline__ void phase_rwkv_scan(const Params& p, int l, const int tidx) {
;     ...
;       for (int s = 0; s < RTC; s++) {
;         const bf16x8 A0 = nA0, A1 = nA1;
;         const float wA[8] = {nw0.x, nw0.y, nw0.z, nw0.w, nw1.x, nw1.y, nw1.z, nw1.w};
;         const float wB[8] = {nw2.x, nw2.y, nw2.z, nw2.w, nw3.x, nw3.y, nw3.z, nw3.w};
;         const float kaA[8] = {nka0.x, nka0.y, nka0.z, nka0.w, nka1.x, nka1.y, nka1.z, nka1.w};
;         const float kaB[8] = {nka2.x, nka2.y, nka2.z, nka2.w, nka3.x, nka3.y, nka3.z, nka3.w};
;         const float kdA[8] = {nkd0.x, nkd0.y, nkd0.z, nkd0.w, nkd1.x, nkd1.y, nkd1.z, nkd1.w};
;         const float kdB[8] = {nkd2.x, nkd2.y, nkd2.z, nkd2.w, nkd3.x, nkd3.y, nkd3.z, nkd3.w};
;         const float v = nv;
;         float c1 = nc.x, c2 = nc.y;
;         asm volatile("" : "+v"(c1), "+v"(c2));
;         if (s + 1 < RTC) RW_LD(s + 1);
;         u32x4 pa = {pack2(Sa[0], Sa[1]), pack2(Sa[2], Sa[3]), pack2(Sa[4], Sa[5]), pack2(Sa[6], Sa[7])};
;         u32x4 pb = {pack2(Sb[0], Sb[1]), pack2(Sb[2], Sb[3]), pack2(Sb[4], Sb[5]), pack2(Sb[6], Sb[7])};
;         f32x4 acc = {0.f, 0.f, 0.f, 0.f};
;         acc = __builtin_amdgcn_mfma_f32_16x16x32_bf16(A0, __builtin_bit_cast(bf16x8, pa), acc, 0, 0, 0);
;         acc = __builtin_amdgcn_mfma_f32_16x16x32_bf16(A1, __builtin_bit_cast(bf16x8, pb), acc, 0, 0, 0);
;         float tA[8], tB[8];
; #pragma unroll
;         for (int c = 0; c < 8; c++) { tA[c] = Sa[c] * wA[c] + v * kdA[c]; tB[c] = Sb[c] * wB[c] + v * kdB[c]; }
;         const float sa = -acc[0];
;         const float yq = acc[1];
; #pragma unroll
;         for (int c = 0; c < 8; c++) { Sa[c] = tA[c] + sa * kaA[c]; Sb[c] = tB[c] + sa * kaB[c]; }
;         const float y = yq + sa * c1 + v * c2;
;         if (quad == 0) by[s * 64 + row] = y;
;       }
	v_fmac_f32_dpp v8, v48, v32 row_newbcast:0 row_mask:0xf bank_mask:0xf
	v_fmac_f32_dpp v9, v48, v32 row_newbcast:1 row_mask:0xf bank_mask:0xf
	v_fmac_f32_dpp v10, v48, v32 row_newbcast:2 row_mask:0xf bank_mask:0xf
	v_fmac_f32_dpp v11, v48, v32 row_newbcast:3 row_mask:0xf bank_mask:0xf
	v_fmac_f32_dpp v12, v48, v32 row_newbcast:4 row_mask:0xf bank_mask:0xf
	v_fmac_f32_dpp v13, v48, v32 row_newbcast:5 row_mask:0xf bank_mask:0xf
	v_fmac_f32_dpp v14, v48, v32 row_newbcast:6 row_mask:0xf bank_mask:0xf
	v_fmac_f32_dpp v15, v48, v32 row_newbcast:7 row_mask:0xf bank_mask:0xf
	v_fmac_f32_dpp v16, v48, v32 row_newbcast:8 row_mask:0xf bank_mask:0xf
	v_fmac_f32_dpp v17, v48, v32 row_newbcast:9 row_mask:0xf bank_mask:0xf
	v_fmac_f32_dpp v18, v48, v32 row_newbcast:10 row_mask:0xf bank_mask:0xf
	v_fmac_f32_dpp v19, v48, v32 row_newbcast:11 row_mask:0xf bank_mask:0xf
	v_fmac_f32_dpp v20, v48, v32 row_newbcast:12 row_mask:0xf bank_mask:0xf
	v_fmac_f32_dpp v21, v48, v32 row_newbcast:13 row_mask:0xf bank_mask:0xf
	v_fmac_f32_dpp v22, v48, v32 row_newbcast:14 row_mask:0xf bank_mask:0xf
	v_fmac_f32_dpp v23, v48, v32 row_newbcast:15 row_mask:0xf bank_mask:0xf
	v_fma_f32 v109, -v32, v68, v33
	v_fma_f32 v109, v66, v69, v109
	ds_write_b32 v107, v109 offset:13824
	v_cvt_pk_bf16_f32 v24, v8, v9
	v_cvt_pk_bf16_f32 v25, v10, v11
	v_cvt_pk_bf16_f32 v26, v12, v13
	v_cvt_pk_bf16_f32 v27, v14, v15
	v_cvt_pk_bf16_f32 v28, v16, v17
	v_cvt_pk_bf16_f32 v29, v18, v19
	s_waitcnt lgkmcnt(4)
	v_mfma_f32_16x16x32_bf16 v[32:35], v[70:73], v[24:27], 0
	v_cvt_pk_bf16_f32 v30, v20, v21
	v_cvt_pk_bf16_f32 v31, v22, v23
	v_fmac_f32_dpp v8, v95, v96 row_newbcast:0 row_mask:0xf bank_mask:0xf
	v_fmac_f32_dpp v9, v95, v96 row_newbcast:1 row_mask:0xf bank_mask:0xf
	v_mfma_f32_16x16x32_bf16 v[32:35], v[74:77], v[28:31], v[32:35]
	v_fmac_f32_dpp v10, v95, v96 row_newbcast:2 row_mask:0xf bank_mask:0xf
	v_fmac_f32_dpp v11, v95, v96 row_newbcast:3 row_mask:0xf bank_mask:0xf
	ds_read_b128 v[40:43], v104 offset:6144
	v_fmac_f32_dpp v12, v95, v96 row_newbcast:4 row_mask:0xf bank_mask:0xf
	v_fmac_f32_dpp v13, v95, v96 row_newbcast:5 row_mask:0xf bank_mask:0xf
	ds_read_b128 v[44:47], v104 offset:6160
	v_fmac_f32_dpp v14, v95, v96 row_newbcast:6 row_mask:0xf bank_mask:0xf
	v_fmac_f32_dpp v15, v95, v96 row_newbcast:7 row_mask:0xf bank_mask:0xf
	ds_read_b32 v65, v105 offset:22528
	v_fmac_f32_dpp v16, v95, v96 row_newbcast:8 row_mask:0xf bank_mask:0xf
	v_fmac_f32_dpp v17, v95, v96 row_newbcast:9 row_mask:0xf bank_mask:0xf
	ds_read_b32 v66, v107 offset:6144
	v_fmac_f32_dpp v18, v95, v96 row_newbcast:10 row_mask:0xf bank_mask:0xf
	v_fmac_f32_dpp v19, v95, v96 row_newbcast:11 row_mask:0xf bank_mask:0xf
	ds_read_b32 v48, v105 offset:14336
	v_fmac_f32_dpp v20, v95, v96 row_newbcast:12 row_mask:0xf bank_mask:0xf
	v_fmac_f32_dpp v21, v95, v96 row_newbcast:13 row_mask:0xf bank_mask:0xf
	ds_read_b64 v[68:69], v108 offset:49344
	v_fmac_f32_dpp v22, v95, v96 row_newbcast:14 row_mask:0xf bank_mask:0xf
	v_fmac_f32_dpp v23, v95, v96 row_newbcast:15 row_mask:0xf bank_mask:0xf
	s_waitcnt lgkmcnt(7)
	v_fmac_f32_dpp v8, v78, v32 row_newbcast:0 row_mask:0xf bank_mask:0xf
	v_fmac_f32_dpp v9, v78, v32 row_newbcast:1 row_mask:0xf bank_mask:0xf
	v_fmac_f32_dpp v10, v78, v32 row_newbcast:2 row_mask:0xf bank_mask:0xf
	v_fmac_f32_dpp v11, v78, v32 row_newbcast:3 row_mask:0xf bank_mask:0xf
	v_fmac_f32_dpp v12, v78, v32 row_newbcast:4 row_mask:0xf bank_mask:0xf
	v_fmac_f32_dpp v13, v78, v32 row_newbcast:5 row_mask:0xf bank_mask:0xf
	v_fmac_f32_dpp v14, v78, v32 row_newbcast:6 row_mask:0xf bank_mask:0xf
	v_fmac_f32_dpp v15, v78, v32 row_newbcast:7 row_mask:0xf bank_mask:0xf
	v_fmac_f32_dpp v16, v78, v32 row_newbcast:8 row_mask:0xf bank_mask:0xf
	v_fmac_f32_dpp v17, v78, v32 row_newbcast:9 row_mask:0xf bank_mask:0xf
	v_fmac_f32_dpp v18, v78, v32 row_newbcast:10 row_mask:0xf bank_mask:0xf
	v_fmac_f32_dpp v19, v78, v32 row_newbcast:11 row_mask:0xf bank_mask:0xf
	v_fmac_f32_dpp v20, v78, v32 row_newbcast:12 row_mask:0xf bank_mask:0xf
	v_fmac_f32_dpp v21, v78, v32 row_newbcast:13 row_mask:0xf bank_mask:0xf
	v_fmac_f32_dpp v22, v78, v32 row_newbcast:14 row_mask:0xf bank_mask:0xf
	v_fmac_f32_dpp v23, v78, v32 row_newbcast:15 row_mask:0xf bank_mask:0xf
	v_fma_f32 v109, -v32, v98, v33
	v_fma_f32 v109, v96, v99, v109
	v_mul_f32_dpp v8, v94, v8 row_newbcast:0 row_mask:0xf bank_mask:0xf
	v_mul_f32_dpp v9, v94, v9 row_newbcast:1 row_mask:0xf bank_mask:0xf
	v_mul_f32_dpp v10, v94, v10 row_newbcast:2 row_mask:0xf bank_mask:0xf
	v_mul_f32_dpp v11, v94, v11 row_newbcast:3 row_mask:0xf bank_mask:0xf
	v_mul_f32_dpp v12, v94, v12 row_newbcast:4 row_mask:0xf bank_mask:0xf
	v_mul_f32_dpp v13, v94, v13 row_newbcast:5 row_mask:0xf bank_mask:0xf
	v_mul_f32_dpp v14, v94, v14 row_newbcast:6 row_mask:0xf bank_mask:0xf
	v_mul_f32_dpp v15, v94, v15 row_newbcast:7 row_mask:0xf bank_mask:0xf
	v_mul_f32_dpp v16, v94, v16 row_newbcast:8 row_mask:0xf bank_mask:0xf
	v_mul_f32_dpp v17, v94, v17 row_newbcast:9 row_mask:0xf bank_mask:0xf
	v_mul_f32_dpp v18, v94, v18 row_newbcast:10 row_mask:0xf bank_mask:0xf
	v_mul_f32_dpp v19, v94, v19 row_newbcast:11 row_mask:0xf bank_mask:0xf
	v_mul_f32_dpp v20, v94, v20 row_newbcast:12 row_mask:0xf bank_mask:0xf
	v_mul_f32_dpp v21, v94, v21 row_newbcast:13 row_mask:0xf bank_mask:0xf
	v_mul_f32_dpp v22, v94, v22 row_newbcast:14 row_mask:0xf bank_mask:0xf
	v_mul_f32_dpp v23, v94, v23 row_newbcast:15 row_mask:0xf bank_mask:0xf
	ds_write_b32 v107, v109 offset:14080
	v_cvt_pk_bf16_f32 v24, v8, v9
	v_cvt_pk_bf16_f32 v25, v10, v11
	v_cvt_pk_bf16_f32 v26, v12, v13
	v_cvt_pk_bf16_f32 v27, v14, v15
	v_cvt_pk_bf16_f32 v28, v16, v17
	v_cvt_pk_bf16_f32 v29, v18, v19
	s_waitcnt lgkmcnt(3)
; __device__ __forceinline__ void phase_rwkv_scan(const Params& p, int l, const int tidx) {
;     ...
;       for (int s = 0; s < RTC; s++) {
;         const bf16x8 A0 = nA0, A1 = nA1;
;         const float wA[8] = {nw0.x, nw0.y, nw0.z, nw0.w, nw1.x, nw1.y, nw1.z, nw1.w};
;         const float wB[8] = {nw2.x, nw2.y, nw2.z, nw2.w, nw3.x, nw3.y, nw3.z, nw3.w};
;         const float kaA[8] = {nka0.x, nka0.y, nka0.z, nka0.w, nka1.x, nka1.y, nka1.z, nka1.w};
;         const float kaB[8] = {nka2.x, nka2.y, nka2.z, nka2.w, nka3.x, nka3.y, nka3.z, nka3.w};
;         const float kdA[8] = {nkd0.x, nkd0.y, nkd0.z, nkd0.w, nkd1.x, nkd1.y, nkd1.z, nkd1.w};
;         const float kdB[8] = {nkd2.x, nkd2.y, nkd2.z, nkd2.w, nkd3.x, nkd3.y, nkd3.z, nkd3.w};
;         const float v = nv;
;         float c1 = nc.x, c2 = nc.y;
;         asm volatile("" : "+v"(c1), "+v"(c2));
;         if (s + 1 < RTC) RW_LD(s + 1);
;         u32x4 pa = {pack2(Sa[0], Sa[1]), pack2(Sa[2], Sa[3]), pack2(Sa[4], Sa[5]), pack2(Sa[6], Sa[7])};
;         u32x4 pb = {pack2(Sb[0], Sb[1]), pack2(Sb[2], Sb[3]), pack2(Sb[4], Sb[5]), pack2(Sb[6], Sb[7])};
;         f32x4 acc = {0.f, 0.f, 0.f, 0.f};
;         acc = __builtin_amdgcn_mfma_f32_16x16x32_bf16(A0, __builtin_bit_cast(bf16x8, pa), acc, 0, 0, 0);
;         acc = __builtin_amdgcn_mfma_f32_16x16x32_bf16(A1, __builtin_bit_cast(bf16x8, pb), acc, 0, 0, 0);
;         float tA[8], tB[8];
; #pragma unroll
;         for (int c = 0; c < 8; c++) { tA[c] = Sa[c] * wA[c] + v * kdA[c]; tB[c] = Sb[c] * wB[c] + v * kdB[c]; }
;         const float sa = -acc[0];
;         const float yq = acc[1];
; #pragma unroll
;         for (int c = 0; c < 8; c++) { Sa[c] = tA[c] + sa * kaA[c]; Sb[c] = tB[c] + sa * kaB[c]; }
;         const float y = yq + sa * c1 + v * c2;
;         if (quad == 0) by[s * 64 + row] = y;
;       }
	v_mfma_f32_16x16x32_bf16 v[32:35], v[40:43], v[24:27], 0
	v_cvt_pk_bf16_f32 v30, v20, v21
	v_cvt_pk_bf16_f32 v31, v22, v23
	v_fmac_f32_dpp v8, v65, v66 row_newbcast:0 row_mask:0xf bank_mask:0xf
	v_fmac_f32_dpp v9, v65, v66 row_newbcast:1 row_mask:0xf bank_mask:0xf
	v_mfma_f32_16x16x32_bf16 v[32:35], v[44:47], v[28:31], v[32:35]
	v_fmac_f32_dpp v10, v65, v66 row_newbcast:2 row_mask:0xf bank_mask:0xf
	v_fmac_f32_dpp v11, v65, v66 row_newbcast:3 row_mask:0xf bank_mask:0xf
	ds_read_b128 v[70:73], v104 offset:6400
	v_fmac_f32_dpp v12, v65, v66 row_newbcast:4 row_mask:0xf bank_mask:0xf
	v_fmac_f32_dpp v13, v65, v66 row_newbcast:5 row_mask:0xf bank_mask:0xf
	ds_read_b128 v[74:77], v104 offset:6416
	v_fmac_f32_dpp v14, v65, v66 row_newbcast:6 row_mask:0xf bank_mask:0xf
	v_fmac_f32_dpp v15, v65, v66 row_newbcast:7 row_mask:0xf bank_mask:0xf
	ds_read_b32 v95, v105 offset:22784
	v_fmac_f32_dpp v16, v65, v66 row_newbcast:8 row_mask:0xf bank_mask:0xf
	v_fmac_f32_dpp v17, v65, v66 row_newbcast:9 row_mask:0xf bank_mask:0xf
	ds_read_b32 v96, v107 offset:6400
	v_fmac_f32_dpp v18, v65, v66 row_newbcast:10 row_mask:0xf bank_mask:0xf
	v_fmac_f32_dpp v19, v65, v66 row_newbcast:11 row_mask:0xf bank_mask:0xf
	ds_read_b32 v78, v105 offset:14592
	v_fmac_f32_dpp v20, v65, v66 row_newbcast:12 row_mask:0xf bank_mask:0xf
	v_fmac_f32_dpp v21, v65, v66 row_newbcast:13 row_mask:0xf bank_mask:0xf
	ds_read_b64 v[98:99], v108 offset:49352
	v_fmac_f32_dpp v22, v65, v66 row_newbcast:14 row_mask:0xf bank_mask:0xf
	v_fmac_f32_dpp v23, v65, v66 row_newbcast:15 row_mask:0xf bank_mask:0xf
	s_waitcnt lgkmcnt(7)
	v_fmac_f32_dpp v8, v48, v32 row_newbcast:0 row_mask:0xf bank_mask:0xf
	v_fmac_f32_dpp v9, v48, v32 row_newbcast:1 row_mask:0xf bank_mask:0xf
	v_fmac_f32_dpp v10, v48, v32 row_newbcast:2 row_mask:0xf bank_mask:0xf
	v_fmac_f32_dpp v11, v48, v32 row_newbcast:3 row_mask:0xf bank_mask:0xf
	v_fmac_f32_dpp v12, v48, v32 row_newbcast:4 row_mask:0xf bank_mask:0xf
	v_fmac_f32_dpp v13, v48, v32 row_newbcast:5 row_mask:0xf bank_mask:0xf
	v_fmac_f32_dpp v14, v48, v32 row_newbcast:6 row_mask:0xf bank_mask:0xf
	v_fmac_f32_dpp v15, v48, v32 row_newbcast:7 row_mask:0xf bank_mask:0xf
	v_fmac_f32_dpp v16, v48, v32 row_newbcast:8 row_mask:0xf bank_mask:0xf
	v_fmac_f32_dpp v17, v48, v32 row_newbcast:9 row_mask:0xf bank_mask:0xf
	v_fmac_f32_dpp v18, v48, v32 row_newbcast:10 row_mask:0xf bank_mask:0xf
	v_fmac_f32_dpp v19, v48, v32 row_newbcast:11 row_mask:0xf bank_mask:0xf
	v_fmac_f32_dpp v20, v48, v32 row_newbcast:12 row_mask:0xf bank_mask:0xf
	v_fmac_f32_dpp v21, v48, v32 row_newbcast:13 row_mask:0xf bank_mask:0xf
	v_fmac_f32_dpp v22, v48, v32 row_newbcast:14 row_mask:0xf bank_mask:0xf
	v_fmac_f32_dpp v23, v48, v32 row_newbcast:15 row_mask:0xf bank_mask:0xf
	v_fma_f32 v109, -v32, v68, v33
	v_fma_f32 v109, v66, v69, v109
	ds_write_b32 v107, v109 offset:14336
	v_cvt_pk_bf16_f32 v24, v8, v9
	v_cvt_pk_bf16_f32 v25, v10, v11
	v_cvt_pk_bf16_f32 v26, v12, v13
	v_cvt_pk_bf16_f32 v27, v14, v15
	v_cvt_pk_bf16_f32 v28, v16, v17
	v_cvt_pk_bf16_f32 v29, v18, v19
	s_waitcnt lgkmcnt(3)
	v_mfma_f32_16x16x32_bf16 v[32:35], v[70:73], v[24:27], 0
	v_cvt_pk_bf16_f32 v30, v20, v21
	v_cvt_pk_bf16_f32 v31, v22, v23
	v_fmac_f32_dpp v8, v95, v96 row_newbcast:0 row_mask:0xf bank_mask:0xf
	v_fmac_f32_dpp v9, v95, v96 row_newbcast:1 row_mask:0xf bank_mask:0xf
	v_mfma_f32_16x16x32_bf16 v[32:35], v[74:77], v[28:31], v[32:35]
	v_fmac_f32_dpp v10, v95, v96 row_newbcast:2 row_mask:0xf bank_mask:0xf
	v_fmac_f32_dpp v11, v95, v96 row_newbcast:3 row_mask:0xf bank_mask:0xf
	ds_read_b128 v[40:43], v104 offset:6656
	v_fmac_f32_dpp v12, v95, v96 row_newbcast:4 row_mask:0xf bank_mask:0xf
	v_fmac_f32_dpp v13, v95, v96 row_newbcast:5 row_mask:0xf bank_mask:0xf
	ds_read_b128 v[44:47], v104 offset:6672
	v_fmac_f32_dpp v14, v95, v96 row_newbcast:6 row_mask:0xf bank_mask:0xf
	v_fmac_f32_dpp v15, v95, v96 row_newbcast:7 row_mask:0xf bank_mask:0xf
	ds_read_b32 v65, v105 offset:23040
	v_fmac_f32_dpp v16, v95, v96 row_newbcast:8 row_mask:0xf bank_mask:0xf
	v_fmac_f32_dpp v17, v95, v96 row_newbcast:9 row_mask:0xf bank_mask:0xf
	ds_read_b32 v66, v107 offset:6656
	v_fmac_f32_dpp v18, v95, v96 row_newbcast:10 row_mask:0xf bank_mask:0xf
	v_fmac_f32_dpp v19, v95, v96 row_newbcast:11 row_mask:0xf bank_mask:0xf
	ds_read_b32 v48, v105 offset:14848
	v_fmac_f32_dpp v20, v95, v96 row_newbcast:12 row_mask:0xf bank_mask:0xf
	v_fmac_f32_dpp v21, v95, v96 row_newbcast:13 row_mask:0xf bank_mask:0xf
	ds_read_b64 v[68:69], v108 offset:49360
	v_fmac_f32_dpp v22, v95, v96 row_newbcast:14 row_mask:0xf bank_mask:0xf
	v_fmac_f32_dpp v23, v95, v96 row_newbcast:15 row_mask:0xf bank_mask:0xf
	s_waitcnt lgkmcnt(7)
	v_fmac_f32_dpp v8, v78, v32 row_newbcast:0 row_mask:0xf bank_mask:0xf
	v_fmac_f32_dpp v9, v78, v32 row_newbcast:1 row_mask:0xf bank_mask:0xf
	v_fmac_f32_dpp v10, v78, v32 row_newbcast:2 row_mask:0xf bank_mask:0xf
	v_fmac_f32_dpp v11, v78, v32 row_newbcast:3 row_mask:0xf bank_mask:0xf
	v_fmac_f32_dpp v12, v78, v32 row_newbcast:4 row_mask:0xf bank_mask:0xf
	v_fmac_f32_dpp v13, v78, v32 row_newbcast:5 row_mask:0xf bank_mask:0xf
	v_fmac_f32_dpp v14, v78, v32 row_newbcast:6 row_mask:0xf bank_mask:0xf
	v_fmac_f32_dpp v15, v78, v32 row_newbcast:7 row_mask:0xf bank_mask:0xf
	v_fmac_f32_dpp v16, v78, v32 row_newbcast:8 row_mask:0xf bank_mask:0xf
	v_fmac_f32_dpp v17, v78, v32 row_newbcast:9 row_mask:0xf bank_mask:0xf
	v_fmac_f32_dpp v18, v78, v32 row_newbcast:10 row_mask:0xf bank_mask:0xf
	v_fmac_f32_dpp v19, v78, v32 row_newbcast:11 row_mask:0xf bank_mask:0xf
	v_fmac_f32_dpp v20, v78, v32 row_newbcast:12 row_mask:0xf bank_mask:0xf
	v_fmac_f32_dpp v21, v78, v32 row_newbcast:13 row_mask:0xf bank_mask:0xf
	v_fmac_f32_dpp v22, v78, v32 row_newbcast:14 row_mask:0xf bank_mask:0xf
	v_fmac_f32_dpp v23, v78, v32 row_newbcast:15 row_mask:0xf bank_mask:0xf
	v_fma_f32 v109, -v32, v98, v33
	v_fma_f32 v109, v96, v99, v109
	ds_write_b32 v107, v109 offset:14592
	v_cvt_pk_bf16_f32 v24, v8, v9
	v_cvt_pk_bf16_f32 v25, v10, v11
	v_cvt_pk_bf16_f32 v26, v12, v13
	v_cvt_pk_bf16_f32 v27, v14, v15
	v_cvt_pk_bf16_f32 v28, v16, v17
	v_cvt_pk_bf16_f32 v29, v18, v19
	s_waitcnt lgkmcnt(3)
; __device__ __forceinline__ void phase_rwkv_scan(const Params& p, int l, const int tidx) {
;     ...
;       for (int s = 0; s < RTC; s++) {
;         const bf16x8 A0 = nA0, A1 = nA1;
;         const float wA[8] = {nw0.x, nw0.y, nw0.z, nw0.w, nw1.x, nw1.y, nw1.z, nw1.w};
;         const float wB[8] = {nw2.x, nw2.y, nw2.z, nw2.w, nw3.x, nw3.y, nw3.z, nw3.w};
;         const float kaA[8] = {nka0.x, nka0.y, nka0.z, nka0.w, nka1.x, nka1.y, nka1.z, nka1.w};
;         const float kaB[8] = {nka2.x, nka2.y, nka2.z, nka2.w, nka3.x, nka3.y, nka3.z, nka3.w};
;         const float kdA[8] = {nkd0.x, nkd0.y, nkd0.z, nkd0.w, nkd1.x, nkd1.y, nkd1.z, nkd1.w};
;         const float kdB[8] = {nkd2.x, nkd2.y, nkd2.z, nkd2.w, nkd3.x, nkd3.y, nkd3.z, nkd3.w};
;         const float v = nv;
;         float c1 = nc.x, c2 = nc.y;
;         asm volatile("" : "+v"(c1), "+v"(c2));
;         if (s + 1 < RTC) RW_LD(s + 1);
;         u32x4 pa = {pack2(Sa[0], Sa[1]), pack2(Sa[2], Sa[3]), pack2(Sa[4], Sa[5]), pack2(Sa[6], Sa[7])};
;         u32x4 pb = {pack2(Sb[0], Sb[1]), pack2(Sb[2], Sb[3]), pack2(Sb[4], Sb[5]), pack2(Sb[6], Sb[7])};
;         f32x4 acc = {0.f, 0.f, 0.f, 0.f};
;         acc = __builtin_amdgcn_mfma_f32_16x16x32_bf16(A0, __builtin_bit_cast(bf16x8, pa), acc, 0, 0, 0);
;         acc = __builtin_amdgcn_mfma_f32_16x16x32_bf16(A1, __builtin_bit_cast(bf16x8, pb), acc, 0, 0, 0);
;         float tA[8], tB[8];
; #pragma unroll
;         for (int c = 0; c < 8; c++) { tA[c] = Sa[c] * wA[c] + v * kdA[c]; tB[c] = Sb[c] * wB[c] + v * kdB[c]; }
;         const float sa = -acc[0];
;         const float yq = acc[1];
; #pragma unroll
;         for (int c = 0; c < 8; c++) { Sa[c] = tA[c] + sa * kaA[c]; Sb[c] = tB[c] + sa * kaB[c]; }
;         const float y = yq + sa * c1 + v * c2;
;         if (quad == 0) by[s * 64 + row] = y;
;       }
	v_mfma_f32_16x16x32_bf16 v[32:35], v[40:43], v[24:27], 0
	v_cvt_pk_bf16_f32 v30, v20, v21
	v_cvt_pk_bf16_f32 v31, v22, v23
	v_fmac_f32_dpp v8, v65, v66 row_newbcast:0 row_mask:0xf bank_mask:0xf
	v_fmac_f32_dpp v9, v65, v66 row_newbcast:1 row_mask:0xf bank_mask:0xf
	v_mfma_f32_16x16x32_bf16 v[32:35], v[44:47], v[28:31], v[32:35]
	v_fmac_f32_dpp v10, v65, v66 row_newbcast:2 row_mask:0xf bank_mask:0xf
	v_fmac_f32_dpp v11, v65, v66 row_newbcast:3 row_mask:0xf bank_mask:0xf
	ds_read_b128 v[70:73], v104 offset:6912
	v_fmac_f32_dpp v12, v65, v66 row_newbcast:4 row_mask:0xf bank_mask:0xf
	v_fmac_f32_dpp v13, v65, v66 row_newbcast:5 row_mask:0xf bank_mask:0xf
	ds_read_b128 v[74:77], v104 offset:6928
	v_fmac_f32_dpp v14, v65, v66 row_newbcast:6 row_mask:0xf bank_mask:0xf
	v_fmac_f32_dpp v15, v65, v66 row_newbcast:7 row_mask:0xf bank_mask:0xf
	ds_read_b32 v95, v105 offset:23296
	v_fmac_f32_dpp v16, v65, v66 row_newbcast:8 row_mask:0xf bank_mask:0xf
	v_fmac_f32_dpp v17, v65, v66 row_newbcast:9 row_mask:0xf bank_mask:0xf
	ds_read_b32 v96, v107 offset:6912
	v_fmac_f32_dpp v18, v65, v66 row_newbcast:10 row_mask:0xf bank_mask:0xf
	v_fmac_f32_dpp v19, v65, v66 row_newbcast:11 row_mask:0xf bank_mask:0xf
	ds_read_b32 v78, v105 offset:15104
	v_fmac_f32_dpp v20, v65, v66 row_newbcast:12 row_mask:0xf bank_mask:0xf
	v_fmac_f32_dpp v21, v65, v66 row_newbcast:13 row_mask:0xf bank_mask:0xf
	ds_read_b64 v[98:99], v108 offset:49368
	v_fmac_f32_dpp v22, v65, v66 row_newbcast:14 row_mask:0xf bank_mask:0xf
	v_fmac_f32_dpp v23, v65, v66 row_newbcast:15 row_mask:0xf bank_mask:0xf
	s_waitcnt lgkmcnt(7)
	v_fmac_f32_dpp v8, v48, v32 row_newbcast:0 row_mask:0xf bank_mask:0xf
	v_fmac_f32_dpp v9, v48, v32 row_newbcast:1 row_mask:0xf bank_mask:0xf
	v_fmac_f32_dpp v10, v48, v32 row_newbcast:2 row_mask:0xf bank_mask:0xf
	v_fmac_f32_dpp v11, v48, v32 row_newbcast:3 row_mask:0xf bank_mask:0xf
	v_fmac_f32_dpp v12, v48, v32 row_newbcast:4 row_mask:0xf bank_mask:0xf
	v_fmac_f32_dpp v13, v48, v32 row_newbcast:5 row_mask:0xf bank_mask:0xf
	v_fmac_f32_dpp v14, v48, v32 row_newbcast:6 row_mask:0xf bank_mask:0xf
	v_fmac_f32_dpp v15, v48, v32 row_newbcast:7 row_mask:0xf bank_mask:0xf
	v_fmac_f32_dpp v16, v48, v32 row_newbcast:8 row_mask:0xf bank_mask:0xf
	v_fmac_f32_dpp v17, v48, v32 row_newbcast:9 row_mask:0xf bank_mask:0xf
	v_fmac_f32_dpp v18, v48, v32 row_newbcast:10 row_mask:0xf bank_mask:0xf
	v_fmac_f32_dpp v19, v48, v32 row_newbcast:11 row_mask:0xf bank_mask:0xf
	v_fmac_f32_dpp v20, v48, v32 row_newbcast:12 row_mask:0xf bank_mask:0xf
	v_fmac_f32_dpp v21, v48, v32 row_newbcast:13 row_mask:0xf bank_mask:0xf
	v_fmac_f32_dpp v22, v48, v32 row_newbcast:14 row_mask:0xf bank_mask:0xf
	v_fmac_f32_dpp v23, v48, v32 row_newbcast:15 row_mask:0xf bank_mask:0xf
	v_fma_f32 v109, -v32, v68, v33
	v_fma_f32 v109, v66, v69, v109
	ds_write_b32 v107, v109 offset:14848
	v_cvt_pk_bf16_f32 v24, v8, v9
	v_cvt_pk_bf16_f32 v25, v10, v11
	v_cvt_pk_bf16_f32 v26, v12, v13
	v_cvt_pk_bf16_f32 v27, v14, v15
	v_cvt_pk_bf16_f32 v28, v16, v17
	v_cvt_pk_bf16_f32 v29, v18, v19
	s_waitcnt lgkmcnt(3)
	v_mfma_f32_16x16x32_bf16 v[32:35], v[70:73], v[24:27], 0
	v_cvt_pk_bf16_f32 v30, v20, v21
	v_cvt_pk_bf16_f32 v31, v22, v23
	v_fmac_f32_dpp v8, v95, v96 row_newbcast:0 row_mask:0xf bank_mask:0xf
	v_fmac_f32_dpp v9, v95, v96 row_newbcast:1 row_mask:0xf bank_mask:0xf
	v_mfma_f32_16x16x32_bf16 v[32:35], v[74:77], v[28:31], v[32:35]
	v_fmac_f32_dpp v10, v95, v96 row_newbcast:2 row_mask:0xf bank_mask:0xf
	v_fmac_f32_dpp v11, v95, v96 row_newbcast:3 row_mask:0xf bank_mask:0xf
	ds_read_b128 v[40:43], v104 offset:7168
	v_fmac_f32_dpp v12, v95, v96 row_newbcast:4 row_mask:0xf bank_mask:0xf
	v_fmac_f32_dpp v13, v95, v96 row_newbcast:5 row_mask:0xf bank_mask:0xf
	ds_read_b128 v[44:47], v104 offset:7184
	v_fmac_f32_dpp v14, v95, v96 row_newbcast:6 row_mask:0xf bank_mask:0xf
	v_fmac_f32_dpp v15, v95, v96 row_newbcast:7 row_mask:0xf bank_mask:0xf
	ds_read_b32 v65, v105 offset:23552
	v_fmac_f32_dpp v16, v95, v96 row_newbcast:8 row_mask:0xf bank_mask:0xf
	v_fmac_f32_dpp v17, v95, v96 row_newbcast:9 row_mask:0xf bank_mask:0xf
	ds_read_b32 v66, v107 offset:7168
	v_fmac_f32_dpp v18, v95, v96 row_newbcast:10 row_mask:0xf bank_mask:0xf
	v_fmac_f32_dpp v19, v95, v96 row_newbcast:11 row_mask:0xf bank_mask:0xf
	ds_read_b32 v48, v105 offset:15360
	v_fmac_f32_dpp v20, v95, v96 row_newbcast:12 row_mask:0xf bank_mask:0xf
	v_fmac_f32_dpp v21, v95, v96 row_newbcast:13 row_mask:0xf bank_mask:0xf
	ds_read_b64 v[68:69], v108 offset:49376
	v_fmac_f32_dpp v22, v95, v96 row_newbcast:14 row_mask:0xf bank_mask:0xf
	v_fmac_f32_dpp v23, v95, v96 row_newbcast:15 row_mask:0xf bank_mask:0xf
	s_waitcnt lgkmcnt(7)
	v_fmac_f32_dpp v8, v78, v32 row_newbcast:0 row_mask:0xf bank_mask:0xf
	v_fmac_f32_dpp v9, v78, v32 row_newbcast:1 row_mask:0xf bank_mask:0xf
	v_fmac_f32_dpp v10, v78, v32 row_newbcast:2 row_mask:0xf bank_mask:0xf
	v_fmac_f32_dpp v11, v78, v32 row_newbcast:3 row_mask:0xf bank_mask:0xf
	v_fmac_f32_dpp v12, v78, v32 row_newbcast:4 row_mask:0xf bank_mask:0xf
	v_fmac_f32_dpp v13, v78, v32 row_newbcast:5 row_mask:0xf bank_mask:0xf
	v_fmac_f32_dpp v14, v78, v32 row_newbcast:6 row_mask:0xf bank_mask:0xf
	v_fmac_f32_dpp v15, v78, v32 row_newbcast:7 row_mask:0xf bank_mask:0xf
	v_fmac_f32_dpp v16, v78, v32 row_newbcast:8 row_mask:0xf bank_mask:0xf
	v_fmac_f32_dpp v17, v78, v32 row_newbcast:9 row_mask:0xf bank_mask:0xf
	v_fmac_f32_dpp v18, v78, v32 row_newbcast:10 row_mask:0xf bank_mask:0xf
	v_fmac_f32_dpp v19, v78, v32 row_newbcast:11 row_mask:0xf bank_mask:0xf
	v_fmac_f32_dpp v20, v78, v32 row_newbcast:12 row_mask:0xf bank_mask:0xf
	v_fmac_f32_dpp v21, v78, v32 row_newbcast:13 row_mask:0xf bank_mask:0xf
	v_fmac_f32_dpp v22, v78, v32 row_newbcast:14 row_mask:0xf bank_mask:0xf
	v_fmac_f32_dpp v23, v78, v32 row_newbcast:15 row_mask:0xf bank_mask:0xf
	v_fma_f32 v109, -v32, v98, v33
	v_fma_f32 v109, v96, v99, v109
	ds_write_b32 v107, v109 offset:15104
	v_cvt_pk_bf16_f32 v24, v8, v9
	v_cvt_pk_bf16_f32 v25, v10, v11
	v_cvt_pk_bf16_f32 v26, v12, v13
	v_cvt_pk_bf16_f32 v27, v14, v15
	v_cvt_pk_bf16_f32 v28, v16, v17
	v_cvt_pk_bf16_f32 v29, v18, v19
	s_waitcnt lgkmcnt(3)
; __device__ __forceinline__ void phase_rwkv_scan(const Params& p, int l, const int tidx) {
;     ...
;       for (int s = 0; s < RTC; s++) {
;         const bf16x8 A0 = nA0, A1 = nA1;
;         const float wA[8] = {nw0.x, nw0.y, nw0.z, nw0.w, nw1.x, nw1.y, nw1.z, nw1.w};
;         const float wB[8] = {nw2.x, nw2.y, nw2.z, nw2.w, nw3.x, nw3.y, nw3.z, nw3.w};
;         const float kaA[8] = {nka0.x, nka0.y, nka0.z, nka0.w, nka1.x, nka1.y, nka1.z, nka1.w};
;         const float kaB[8] = {nka2.x, nka2.y, nka2.z, nka2.w, nka3.x, nka3.y, nka3.z, nka3.w};
;         const float kdA[8] = {nkd0.x, nkd0.y, nkd0.z, nkd0.w, nkd1.x, nkd1.y, nkd1.z, nkd1.w};
;         const float kdB[8] = {nkd2.x, nkd2.y, nkd2.z, nkd2.w, nkd3.x, nkd3.y, nkd3.z, nkd3.w};
;         const float v = nv;
;         float c1 = nc.x, c2 = nc.y;
;         asm volatile("" : "+v"(c1), "+v"(c2));
;         if (s + 1 < RTC) RW_LD(s + 1);
;         u32x4 pa = {pack2(Sa[0], Sa[1]), pack2(Sa[2], Sa[3]), pack2(Sa[4], Sa[5]), pack2(Sa[6], Sa[7])};
;         u32x4 pb = {pack2(Sb[0], Sb[1]), pack2(Sb[2], Sb[3]), pack2(Sb[4], Sb[5]), pack2(Sb[6], Sb[7])};
;         f32x4 acc = {0.f, 0.f, 0.f, 0.f};
;         acc = __builtin_amdgcn_mfma_f32_16x16x32_bf16(A0, __builtin_bit_cast(bf16x8, pa), acc, 0, 0, 0);
;         acc = __builtin_amdgcn_mfma_f32_16x16x32_bf16(A1, __builtin_bit_cast(bf16x8, pb), acc, 0, 0, 0);
;         float tA[8], tB[8];
; #pragma unroll
;         for (int c = 0; c < 8; c++) { tA[c] = Sa[c] * wA[c] + v * kdA[c]; tB[c] = Sb[c] * wB[c] + v * kdB[c]; }
;         const float sa = -acc[0];
;         const float yq = acc[1];
; #pragma unroll
;         for (int c = 0; c < 8; c++) { Sa[c] = tA[c] + sa * kaA[c]; Sb[c] = tB[c] + sa * kaB[c]; }
;         const float y = yq + sa * c1 + v * c2;
;         if (quad == 0) by[s * 64 + row] = y;
;       }
	v_mfma_f32_16x16x32_bf16 v[32:35], v[40:43], v[24:27], 0
	v_cvt_pk_bf16_f32 v30, v20, v21
	v_cvt_pk_bf16_f32 v31, v22, v23
	v_fmac_f32_dpp v8, v65, v66 row_newbcast:0 row_mask:0xf bank_mask:0xf
	v_fmac_f32_dpp v9, v65, v66 row_newbcast:1 row_mask:0xf bank_mask:0xf
	v_mfma_f32_16x16x32_bf16 v[32:35], v[44:47], v[28:31], v[32:35]
	v_fmac_f32_dpp v10, v65, v66 row_newbcast:2 row_mask:0xf bank_mask:0xf
	v_fmac_f32_dpp v11, v65, v66 row_newbcast:3 row_mask:0xf bank_mask:0xf
	ds_read_b128 v[70:73], v104 offset:7424
	v_fmac_f32_dpp v12, v65, v66 row_newbcast:4 row_mask:0xf bank_mask:0xf
	v_fmac_f32_dpp v13, v65, v66 row_newbcast:5 row_mask:0xf bank_mask:0xf
	ds_read_b128 v[74:77], v104 offset:7440
	v_fmac_f32_dpp v14, v65, v66 row_newbcast:6 row_mask:0xf bank_mask:0xf
	v_fmac_f32_dpp v15, v65, v66 row_newbcast:7 row_mask:0xf bank_mask:0xf
	ds_read_b32 v95, v105 offset:23808
	v_fmac_f32_dpp v16, v65, v66 row_newbcast:8 row_mask:0xf bank_mask:0xf
	v_fmac_f32_dpp v17, v65, v66 row_newbcast:9 row_mask:0xf bank_mask:0xf
	ds_read_b32 v96, v107 offset:7424
	v_fmac_f32_dpp v18, v65, v66 row_newbcast:10 row_mask:0xf bank_mask:0xf
	v_fmac_f32_dpp v19, v65, v66 row_newbcast:11 row_mask:0xf bank_mask:0xf
	ds_read_b32 v78, v105 offset:15616
	v_fmac_f32_dpp v20, v65, v66 row_newbcast:12 row_mask:0xf bank_mask:0xf
	v_fmac_f32_dpp v21, v65, v66 row_newbcast:13 row_mask:0xf bank_mask:0xf
	ds_read_b64 v[98:99], v108 offset:49384
	v_fmac_f32_dpp v22, v65, v66 row_newbcast:14 row_mask:0xf bank_mask:0xf
	v_fmac_f32_dpp v23, v65, v66 row_newbcast:15 row_mask:0xf bank_mask:0xf
	s_waitcnt lgkmcnt(7)
	v_fmac_f32_dpp v8, v48, v32 row_newbcast:0 row_mask:0xf bank_mask:0xf
	v_fmac_f32_dpp v9, v48, v32 row_newbcast:1 row_mask:0xf bank_mask:0xf
	v_fmac_f32_dpp v10, v48, v32 row_newbcast:2 row_mask:0xf bank_mask:0xf
	v_fmac_f32_dpp v11, v48, v32 row_newbcast:3 row_mask:0xf bank_mask:0xf
	v_fmac_f32_dpp v12, v48, v32 row_newbcast:4 row_mask:0xf bank_mask:0xf
	v_fmac_f32_dpp v13, v48, v32 row_newbcast:5 row_mask:0xf bank_mask:0xf
	v_fmac_f32_dpp v14, v48, v32 row_newbcast:6 row_mask:0xf bank_mask:0xf
	v_fmac_f32_dpp v15, v48, v32 row_newbcast:7 row_mask:0xf bank_mask:0xf
	v_fmac_f32_dpp v16, v48, v32 row_newbcast:8 row_mask:0xf bank_mask:0xf
	v_fmac_f32_dpp v17, v48, v32 row_newbcast:9 row_mask:0xf bank_mask:0xf
	v_fmac_f32_dpp v18, v48, v32 row_newbcast:10 row_mask:0xf bank_mask:0xf
	v_fmac_f32_dpp v19, v48, v32 row_newbcast:11 row_mask:0xf bank_mask:0xf
	v_fmac_f32_dpp v20, v48, v32 row_newbcast:12 row_mask:0xf bank_mask:0xf
	v_fmac_f32_dpp v21, v48, v32 row_newbcast:13 row_mask:0xf bank_mask:0xf
	v_fmac_f32_dpp v22, v48, v32 row_newbcast:14 row_mask:0xf bank_mask:0xf
	v_fmac_f32_dpp v23, v48, v32 row_newbcast:15 row_mask:0xf bank_mask:0xf
	v_fma_f32 v109, -v32, v68, v33
	v_fma_f32 v109, v66, v69, v109
	ds_write_b32 v107, v109 offset:15360
	v_cvt_pk_bf16_f32 v24, v8, v9
	v_cvt_pk_bf16_f32 v25, v10, v11
	v_cvt_pk_bf16_f32 v26, v12, v13
	v_cvt_pk_bf16_f32 v27, v14, v15
	v_cvt_pk_bf16_f32 v28, v16, v17
	v_cvt_pk_bf16_f32 v29, v18, v19
	s_waitcnt lgkmcnt(3)
	v_mfma_f32_16x16x32_bf16 v[32:35], v[70:73], v[24:27], 0
	v_cvt_pk_bf16_f32 v30, v20, v21
	v_cvt_pk_bf16_f32 v31, v22, v23
	v_fmac_f32_dpp v8, v95, v96 row_newbcast:0 row_mask:0xf bank_mask:0xf
	v_fmac_f32_dpp v9, v95, v96 row_newbcast:1 row_mask:0xf bank_mask:0xf
	v_mfma_f32_16x16x32_bf16 v[32:35], v[74:77], v[28:31], v[32:35]
	v_fmac_f32_dpp v10, v95, v96 row_newbcast:2 row_mask:0xf bank_mask:0xf
	v_fmac_f32_dpp v11, v95, v96 row_newbcast:3 row_mask:0xf bank_mask:0xf
	ds_read_b128 v[40:43], v104 offset:7680
	v_fmac_f32_dpp v12, v95, v96 row_newbcast:4 row_mask:0xf bank_mask:0xf
	v_fmac_f32_dpp v13, v95, v96 row_newbcast:5 row_mask:0xf bank_mask:0xf
	ds_read_b128 v[44:47], v104 offset:7696
	v_fmac_f32_dpp v14, v95, v96 row_newbcast:6 row_mask:0xf bank_mask:0xf
	v_fmac_f32_dpp v15, v95, v96 row_newbcast:7 row_mask:0xf bank_mask:0xf
	ds_read_b32 v65, v105 offset:24064
	v_fmac_f32_dpp v16, v95, v96 row_newbcast:8 row_mask:0xf bank_mask:0xf
	v_fmac_f32_dpp v17, v95, v96 row_newbcast:9 row_mask:0xf bank_mask:0xf
	ds_read_b32 v66, v107 offset:7680
	v_fmac_f32_dpp v18, v95, v96 row_newbcast:10 row_mask:0xf bank_mask:0xf
	v_fmac_f32_dpp v19, v95, v96 row_newbcast:11 row_mask:0xf bank_mask:0xf
	ds_read_b32 v48, v105 offset:15872
	v_fmac_f32_dpp v20, v95, v96 row_newbcast:12 row_mask:0xf bank_mask:0xf
	v_fmac_f32_dpp v21, v95, v96 row_newbcast:13 row_mask:0xf bank_mask:0xf
	ds_read_b64 v[68:69], v108 offset:49392
	v_fmac_f32_dpp v22, v95, v96 row_newbcast:14 row_mask:0xf bank_mask:0xf
	v_fmac_f32_dpp v23, v95, v96 row_newbcast:15 row_mask:0xf bank_mask:0xf
	s_waitcnt lgkmcnt(7)
	v_fmac_f32_dpp v8, v78, v32 row_newbcast:0 row_mask:0xf bank_mask:0xf
	v_fmac_f32_dpp v9, v78, v32 row_newbcast:1 row_mask:0xf bank_mask:0xf
	v_fmac_f32_dpp v10, v78, v32 row_newbcast:2 row_mask:0xf bank_mask:0xf
	v_fmac_f32_dpp v11, v78, v32 row_newbcast:3 row_mask:0xf bank_mask:0xf
	v_fmac_f32_dpp v12, v78, v32 row_newbcast:4 row_mask:0xf bank_mask:0xf
	v_fmac_f32_dpp v13, v78, v32 row_newbcast:5 row_mask:0xf bank_mask:0xf
	v_fmac_f32_dpp v14, v78, v32 row_newbcast:6 row_mask:0xf bank_mask:0xf
	v_fmac_f32_dpp v15, v78, v32 row_newbcast:7 row_mask:0xf bank_mask:0xf
	v_fmac_f32_dpp v16, v78, v32 row_newbcast:8 row_mask:0xf bank_mask:0xf
	v_fmac_f32_dpp v17, v78, v32 row_newbcast:9 row_mask:0xf bank_mask:0xf
	v_fmac_f32_dpp v18, v78, v32 row_newbcast:10 row_mask:0xf bank_mask:0xf
	v_fmac_f32_dpp v19, v78, v32 row_newbcast:11 row_mask:0xf bank_mask:0xf
	v_fmac_f32_dpp v20, v78, v32 row_newbcast:12 row_mask:0xf bank_mask:0xf
	v_fmac_f32_dpp v21, v78, v32 row_newbcast:13 row_mask:0xf bank_mask:0xf
	v_fmac_f32_dpp v22, v78, v32 row_newbcast:14 row_mask:0xf bank_mask:0xf
	v_fmac_f32_dpp v23, v78, v32 row_newbcast:15 row_mask:0xf bank_mask:0xf
	v_fma_f32 v109, -v32, v98, v33
	v_fma_f32 v109, v96, v99, v109
	ds_write_b32 v107, v109 offset:15616
	v_cvt_pk_bf16_f32 v24, v8, v9
	v_cvt_pk_bf16_f32 v25, v10, v11
	v_cvt_pk_bf16_f32 v26, v12, v13
	v_cvt_pk_bf16_f32 v27, v14, v15
	v_cvt_pk_bf16_f32 v28, v16, v17
	v_cvt_pk_bf16_f32 v29, v18, v19
	s_waitcnt lgkmcnt(3)
; __device__ __forceinline__ void phase_rwkv_scan(const Params& p, int l, const int tidx) {
;     ...
;       for (int s = 0; s < RTC; s++) {
;         const bf16x8 A0 = nA0, A1 = nA1;
;         const float wA[8] = {nw0.x, nw0.y, nw0.z, nw0.w, nw1.x, nw1.y, nw1.z, nw1.w};
;         const float wB[8] = {nw2.x, nw2.y, nw2.z, nw2.w, nw3.x, nw3.y, nw3.z, nw3.w};
;         const float kaA[8] = {nka0.x, nka0.y, nka0.z, nka0.w, nka1.x, nka1.y, nka1.z, nka1.w};
;         const float kaB[8] = {nka2.x, nka2.y, nka2.z, nka2.w, nka3.x, nka3.y, nka3.z, nka3.w};
;         const float kdA[8] = {nkd0.x, nkd0.y, nkd0.z, nkd0.w, nkd1.x, nkd1.y, nkd1.z, nkd1.w};
;         const float kdB[8] = {nkd2.x, nkd2.y, nkd2.z, nkd2.w, nkd3.x, nkd3.y, nkd3.z, nkd3.w};
;         const float v = nv;
;         float c1 = nc.x, c2 = nc.y;
;         asm volatile("" : "+v"(c1), "+v"(c2));
;         if (s + 1 < RTC) RW_LD(s + 1);
;         u32x4 pa = {pack2(Sa[0], Sa[1]), pack2(Sa[2], Sa[3]), pack2(Sa[4], Sa[5]), pack2(Sa[6], Sa[7])};
;         u32x4 pb = {pack2(Sb[0], Sb[1]), pack2(Sb[2], Sb[3]), pack2(Sb[4], Sb[5]), pack2(Sb[6], Sb[7])};
;         f32x4 acc = {0.f, 0.f, 0.f, 0.f};
;         acc = __builtin_amdgcn_mfma_f32_16x16x32_bf16(A0, __builtin_bit_cast(bf16x8, pa), acc, 0, 0, 0);
;         acc = __builtin_amdgcn_mfma_f32_16x16x32_bf16(A1, __builtin_bit_cast(bf16x8, pb), acc, 0, 0, 0);
;         float tA[8], tB[8];
; #pragma unroll
;         for (int c = 0; c < 8; c++) { tA[c] = Sa[c] * wA[c] + v * kdA[c]; tB[c] = Sb[c] * wB[c] + v * kdB[c]; }
;         const float sa = -acc[0];
;         const float yq = acc[1];
; #pragma unroll
;         for (int c = 0; c < 8; c++) { Sa[c] = tA[c] + sa * kaA[c]; Sb[c] = tB[c] + sa * kaB[c]; }
;         const float y = yq + sa * c1 + v * c2;
;         if (quad == 0) by[s * 64 + row] = y;
;       }
;     ...
;       __syncthreads();
;     }
	v_mfma_f32_16x16x32_bf16 v[32:35], v[40:43], v[24:27], 0
	v_cvt_pk_bf16_f32 v30, v20, v21
	v_cvt_pk_bf16_f32 v31, v22, v23
	v_fmac_f32_dpp v8, v65, v66 row_newbcast:0 row_mask:0xf bank_mask:0xf
	v_fmac_f32_dpp v9, v65, v66 row_newbcast:1 row_mask:0xf bank_mask:0xf
	v_mfma_f32_16x16x32_bf16 v[32:35], v[44:47], v[28:31], v[32:35]
	v_fmac_f32_dpp v10, v65, v66 row_newbcast:2 row_mask:0xf bank_mask:0xf
	v_fmac_f32_dpp v11, v65, v66 row_newbcast:3 row_mask:0xf bank_mask:0xf
	ds_read_b128 v[70:73], v104 offset:7936
	v_fmac_f32_dpp v12, v65, v66 row_newbcast:4 row_mask:0xf bank_mask:0xf
	v_fmac_f32_dpp v13, v65, v66 row_newbcast:5 row_mask:0xf bank_mask:0xf
	ds_read_b128 v[74:77], v104 offset:7952
	v_fmac_f32_dpp v14, v65, v66 row_newbcast:6 row_mask:0xf bank_mask:0xf
	v_fmac_f32_dpp v15, v65, v66 row_newbcast:7 row_mask:0xf bank_mask:0xf
	ds_read_b32 v95, v105 offset:24320
	v_fmac_f32_dpp v16, v65, v66 row_newbcast:8 row_mask:0xf bank_mask:0xf
	v_fmac_f32_dpp v17, v65, v66 row_newbcast:9 row_mask:0xf bank_mask:0xf
	ds_read_b32 v96, v107 offset:7936
	v_fmac_f32_dpp v18, v65, v66 row_newbcast:10 row_mask:0xf bank_mask:0xf
	v_fmac_f32_dpp v19, v65, v66 row_newbcast:11 row_mask:0xf bank_mask:0xf
	ds_read_b32 v94, v105 offset:7936
	v_fmac_f32_dpp v20, v65, v66 row_newbcast:12 row_mask:0xf bank_mask:0xf
	v_fmac_f32_dpp v21, v65, v66 row_newbcast:13 row_mask:0xf bank_mask:0xf
	ds_read_b32 v78, v105 offset:16128
	v_fmac_f32_dpp v22, v65, v66 row_newbcast:14 row_mask:0xf bank_mask:0xf
	v_fmac_f32_dpp v23, v65, v66 row_newbcast:15 row_mask:0xf bank_mask:0xf
	ds_read_b64 v[98:99], v108 offset:49400
	s_waitcnt lgkmcnt(8)
	v_fmac_f32_dpp v8, v48, v32 row_newbcast:0 row_mask:0xf bank_mask:0xf
	v_fmac_f32_dpp v9, v48, v32 row_newbcast:1 row_mask:0xf bank_mask:0xf
	v_fmac_f32_dpp v10, v48, v32 row_newbcast:2 row_mask:0xf bank_mask:0xf
	v_fmac_f32_dpp v11, v48, v32 row_newbcast:3 row_mask:0xf bank_mask:0xf
	v_fmac_f32_dpp v12, v48, v32 row_newbcast:4 row_mask:0xf bank_mask:0xf
	v_fmac_f32_dpp v13, v48, v32 row_newbcast:5 row_mask:0xf bank_mask:0xf
	v_fmac_f32_dpp v14, v48, v32 row_newbcast:6 row_mask:0xf bank_mask:0xf
	v_fmac_f32_dpp v15, v48, v32 row_newbcast:7 row_mask:0xf bank_mask:0xf
	v_fmac_f32_dpp v16, v48, v32 row_newbcast:8 row_mask:0xf bank_mask:0xf
	v_fmac_f32_dpp v17, v48, v32 row_newbcast:9 row_mask:0xf bank_mask:0xf
	v_fmac_f32_dpp v18, v48, v32 row_newbcast:10 row_mask:0xf bank_mask:0xf
	v_fmac_f32_dpp v19, v48, v32 row_newbcast:11 row_mask:0xf bank_mask:0xf
	v_fmac_f32_dpp v20, v48, v32 row_newbcast:12 row_mask:0xf bank_mask:0xf
	v_fmac_f32_dpp v21, v48, v32 row_newbcast:13 row_mask:0xf bank_mask:0xf
	v_fmac_f32_dpp v22, v48, v32 row_newbcast:14 row_mask:0xf bank_mask:0xf
	v_fmac_f32_dpp v23, v48, v32 row_newbcast:15 row_mask:0xf bank_mask:0xf
	v_fma_f32 v109, -v32, v68, v33
	v_fma_f32 v109, v66, v69, v109
	ds_write_b32 v107, v109 offset:15872
	v_cvt_pk_bf16_f32 v24, v8, v9
	v_cvt_pk_bf16_f32 v25, v10, v11
	v_cvt_pk_bf16_f32 v26, v12, v13
	v_cvt_pk_bf16_f32 v27, v14, v15
	v_cvt_pk_bf16_f32 v28, v16, v17
	v_cvt_pk_bf16_f32 v29, v18, v19
	s_waitcnt lgkmcnt(4)
	v_mfma_f32_16x16x32_bf16 v[32:35], v[70:73], v[24:27], 0
	v_cvt_pk_bf16_f32 v30, v20, v21
	v_cvt_pk_bf16_f32 v31, v22, v23
	v_fmac_f32_dpp v8, v95, v96 row_newbcast:0 row_mask:0xf bank_mask:0xf
	v_fmac_f32_dpp v9, v95, v96 row_newbcast:1 row_mask:0xf bank_mask:0xf
	v_mfma_f32_16x16x32_bf16 v[32:35], v[74:77], v[28:31], v[32:35]
	v_fmac_f32_dpp v10, v95, v96 row_newbcast:2 row_mask:0xf bank_mask:0xf
	v_fmac_f32_dpp v11, v95, v96 row_newbcast:3 row_mask:0xf bank_mask:0xf
	v_fmac_f32_dpp v12, v95, v96 row_newbcast:4 row_mask:0xf bank_mask:0xf
	v_fmac_f32_dpp v13, v95, v96 row_newbcast:5 row_mask:0xf bank_mask:0xf
	v_fmac_f32_dpp v14, v95, v96 row_newbcast:6 row_mask:0xf bank_mask:0xf
	v_fmac_f32_dpp v15, v95, v96 row_newbcast:7 row_mask:0xf bank_mask:0xf
	v_fmac_f32_dpp v16, v95, v96 row_newbcast:8 row_mask:0xf bank_mask:0xf
	v_fmac_f32_dpp v17, v95, v96 row_newbcast:9 row_mask:0xf bank_mask:0xf
	v_fmac_f32_dpp v18, v95, v96 row_newbcast:10 row_mask:0xf bank_mask:0xf
	v_fmac_f32_dpp v19, v95, v96 row_newbcast:11 row_mask:0xf bank_mask:0xf
	v_fmac_f32_dpp v20, v95, v96 row_newbcast:12 row_mask:0xf bank_mask:0xf
	v_fmac_f32_dpp v21, v95, v96 row_newbcast:13 row_mask:0xf bank_mask:0xf
	v_fmac_f32_dpp v22, v95, v96 row_newbcast:14 row_mask:0xf bank_mask:0xf
	v_fmac_f32_dpp v23, v95, v96 row_newbcast:15 row_mask:0xf bank_mask:0xf
	s_waitcnt lgkmcnt(1)
	v_fmac_f32_dpp v8, v78, v32 row_newbcast:0 row_mask:0xf bank_mask:0xf
	v_fmac_f32_dpp v9, v78, v32 row_newbcast:1 row_mask:0xf bank_mask:0xf
	v_fmac_f32_dpp v10, v78, v32 row_newbcast:2 row_mask:0xf bank_mask:0xf
	v_fmac_f32_dpp v11, v78, v32 row_newbcast:3 row_mask:0xf bank_mask:0xf
	v_fmac_f32_dpp v12, v78, v32 row_newbcast:4 row_mask:0xf bank_mask:0xf
	v_fmac_f32_dpp v13, v78, v32 row_newbcast:5 row_mask:0xf bank_mask:0xf
	v_fmac_f32_dpp v14, v78, v32 row_newbcast:6 row_mask:0xf bank_mask:0xf
	v_fmac_f32_dpp v15, v78, v32 row_newbcast:7 row_mask:0xf bank_mask:0xf
	v_fmac_f32_dpp v16, v78, v32 row_newbcast:8 row_mask:0xf bank_mask:0xf
	v_fmac_f32_dpp v17, v78, v32 row_newbcast:9 row_mask:0xf bank_mask:0xf
	v_fmac_f32_dpp v18, v78, v32 row_newbcast:10 row_mask:0xf bank_mask:0xf
	v_fmac_f32_dpp v19, v78, v32 row_newbcast:11 row_mask:0xf bank_mask:0xf
	v_fmac_f32_dpp v20, v78, v32 row_newbcast:12 row_mask:0xf bank_mask:0xf
	v_fmac_f32_dpp v21, v78, v32 row_newbcast:13 row_mask:0xf bank_mask:0xf
	v_fmac_f32_dpp v22, v78, v32 row_newbcast:14 row_mask:0xf bank_mask:0xf
	v_fmac_f32_dpp v23, v78, v32 row_newbcast:15 row_mask:0xf bank_mask:0xf
	v_fma_f32 v109, -v32, v98, v33
	v_fma_f32 v109, v96, v99, v109
	v_mul_f32_dpp v8, v94, v8 row_newbcast:0 row_mask:0xf bank_mask:0xf
	v_mul_f32_dpp v9, v94, v9 row_newbcast:1 row_mask:0xf bank_mask:0xf
	v_mul_f32_dpp v10, v94, v10 row_newbcast:2 row_mask:0xf bank_mask:0xf
	v_mul_f32_dpp v11, v94, v11 row_newbcast:3 row_mask:0xf bank_mask:0xf
	v_mul_f32_dpp v12, v94, v12 row_newbcast:4 row_mask:0xf bank_mask:0xf
	v_mul_f32_dpp v13, v94, v13 row_newbcast:5 row_mask:0xf bank_mask:0xf
	v_mul_f32_dpp v14, v94, v14 row_newbcast:6 row_mask:0xf bank_mask:0xf
	v_mul_f32_dpp v15, v94, v15 row_newbcast:7 row_mask:0xf bank_mask:0xf
	v_mul_f32_dpp v16, v94, v16 row_newbcast:8 row_mask:0xf bank_mask:0xf
	v_mul_f32_dpp v17, v94, v17 row_newbcast:9 row_mask:0xf bank_mask:0xf
	v_mul_f32_dpp v18, v94, v18 row_newbcast:10 row_mask:0xf bank_mask:0xf
	v_mul_f32_dpp v19, v94, v19 row_newbcast:11 row_mask:0xf bank_mask:0xf
	v_mul_f32_dpp v20, v94, v20 row_newbcast:12 row_mask:0xf bank_mask:0xf
	v_mul_f32_dpp v21, v94, v21 row_newbcast:13 row_mask:0xf bank_mask:0xf
	v_mul_f32_dpp v22, v94, v22 row_newbcast:14 row_mask:0xf bank_mask:0xf
	v_mul_f32_dpp v23, v94, v23 row_newbcast:15 row_mask:0xf bank_mask:0xf
	ds_write_b32 v107, v109 offset:16128
	s_add_i32 s0, s0, 1
	s_cmpk_eq_i32 s0, 0x80
	s_waitcnt lgkmcnt(0)
	s_barrier
	s_cbranch_scc0 .Lrw_chunk

; __device__ __forceinline__ void hyena_filter_task(const Params& p, int l, int t, const int tidx) {
;     ...
;     __syncthreads();
; #pragma unroll 8
;     for (int i = 0; i < 64; i++) {
;       int idx = tidx + NT * i;
;       int k = idx >> 9, n = idx & 511;
;       sWo[k * 520 + n] = f2bf(wo[(size_t)k * 1024 + half * 512 + n]);
;     }
;     __syncthreads();
;     float acc0[8], acc1[8];
; #pragma unroll
;     for (int i = 0; i < 8; i++) { acc0[i] = 0.f; acc1[i] = 0.f; }
.LBB0_694:
	s_lshl_b32 s17, s12, 9
	s_lshl_b32 s16, s0, 9
	v_add_u32_e32 v0, s17, v150
	v_add_u32_e32 v10, s16, v3
	v_ashrrev_i32_e32 v12, 9, v0
	v_ashrrev_i32_e32 v10, 9, v10
	v_ashrrev_i32_e32 v13, 31, v12
	v_ashrrev_i32_e32 v11, 31, v10
	v_lshlrev_b64 v[76:77], 12, v[12:13]
	v_lshlrev_b64 v[14:15], 12, v[10:11]
	v_lshl_add_u64 v[76:77], v[8:9], 0, v[76:77]
	v_lshl_add_u64 v[14:15], v[8:9], 0, v[14:15]
	global_load_dword v200, v[76:77], off
	global_load_dword v201, v[14:15], off
	v_mad_i32_i24 v220, v12, s97, v97
	v_mad_i32_i24 v221, v10, s97, v97
	v_add_u32_e32 v0, s17, v36
	v_add_u32_e32 v10, s16, v37
	v_ashrrev_i32_e32 v12, 9, v0
	v_ashrrev_i32_e32 v10, 9, v10
	v_ashrrev_i32_e32 v13, 31, v12
	v_ashrrev_i32_e32 v11, 31, v10
	v_lshlrev_b64 v[76:77], 12, v[12:13]
	v_lshlrev_b64 v[14:15], 12, v[10:11]
	v_lshl_add_u64 v[76:77], v[8:9], 0, v[76:77]
	v_lshl_add_u64 v[14:15], v[8:9], 0, v[14:15]
	global_load_dword v202, v[76:77], off
	global_load_dword v203, v[14:15], off
	v_mad_i32_i24 v222, v12, s97, v97
	v_mad_i32_i24 v223, v10, s97, v97
	v_add_u32_e32 v0, s17, v38
	v_add_u32_e32 v10, s16, v39
	v_ashrrev_i32_e32 v12, 9, v0
	v_ashrrev_i32_e32 v10, 9, v10
	v_ashrrev_i32_e32 v13, 31, v12
	v_ashrrev_i32_e32 v11, 31, v10
	v_lshlrev_b64 v[76:77], 12, v[12:13]
	v_lshlrev_b64 v[14:15], 12, v[10:11]
	v_lshl_add_u64 v[76:77], v[8:9], 0, v[76:77]
	v_lshl_add_u64 v[14:15], v[8:9], 0, v[14:15]
	global_load_dword v204, v[76:77], off
	global_load_dword v205, v[14:15], off
	v_mad_i32_i24 v224, v12, s97, v97
	v_mad_i32_i24 v225, v10, s97, v97
	v_add_u32_e32 v0, s17, v40
	v_add_u32_e32 v10, s16, v41
	v_ashrrev_i32_e32 v12, 9, v0
	v_ashrrev_i32_e32 v10, 9, v10
	v_ashrrev_i32_e32 v13, 31, v12
	v_ashrrev_i32_e32 v11, 31, v10
	v_lshlrev_b64 v[76:77], 12, v[12:13]
	v_lshlrev_b64 v[14:15], 12, v[10:11]
	v_lshl_add_u64 v[76:77], v[8:9], 0, v[76:77]
	v_lshl_add_u64 v[14:15], v[8:9], 0, v[14:15]
	global_load_dword v206, v[76:77], off
	global_load_dword v207, v[14:15], off
	v_mad_i32_i24 v226, v12, s97, v97
	v_mad_i32_i24 v227, v10, s97, v97
	v_add_u32_e32 v0, s17, v60
	v_add_u32_e32 v10, s16, v61
	v_ashrrev_i32_e32 v12, 9, v0
	v_ashrrev_i32_e32 v10, 9, v10
	v_ashrrev_i32_e32 v13, 31, v12
	v_ashrrev_i32_e32 v11, 31, v10
	v_lshlrev_b64 v[76:77], 12, v[12:13]
	v_lshlrev_b64 v[14:15], 12, v[10:11]
	v_lshl_add_u64 v[76:77], v[8:9], 0, v[76:77]
	v_lshl_add_u64 v[14:15], v[8:9], 0, v[14:15]
	global_load_dword v208, v[76:77], off
	global_load_dword v209, v[14:15], off
	v_mad_i32_i24 v228, v12, s97, v97
	v_mad_i32_i24 v229, v10, s97, v97
	v_add_u32_e32 v0, s17, v62
	v_add_u32_e32 v10, s16, v63
	v_ashrrev_i32_e32 v12, 9, v0
	v_ashrrev_i32_e32 v10, 9, v10
	v_ashrrev_i32_e32 v13, 31, v12
	v_ashrrev_i32_e32 v11, 31, v10
	v_lshlrev_b64 v[76:77], 12, v[12:13]
	v_lshlrev_b64 v[14:15], 12, v[10:11]
	v_lshl_add_u64 v[76:77], v[8:9], 0, v[76:77]
	v_lshl_add_u64 v[14:15], v[8:9], 0, v[14:15]
	global_load_dword v210, v[76:77], off
	global_load_dword v211, v[14:15], off
	v_mad_i32_i24 v230, v12, s97, v97
	v_mad_i32_i24 v231, v10, s97, v97
	v_add_u32_e32 v0, s17, v64
	v_add_u32_e32 v10, s16, v65
	v_ashrrev_i32_e32 v12, 9, v0
	v_ashrrev_i32_e32 v10, 9, v10
	v_ashrrev_i32_e32 v13, 31, v12
	v_ashrrev_i32_e32 v11, 31, v10
	v_lshlrev_b64 v[76:77], 12, v[12:13]
	v_lshlrev_b64 v[14:15], 12, v[10:11]
	v_lshl_add_u64 v[76:77], v[8:9], 0, v[76:77]
	v_lshl_add_u64 v[14:15], v[8:9], 0, v[14:15]
	global_load_dword v212, v[76:77], off
	global_load_dword v213, v[14:15], off
	v_mad_i32_i24 v232, v12, s97, v97
	v_mad_i32_i24 v233, v10, s97, v97
	v_add_u32_e32 v0, s17, v66
	v_add_u32_e32 v10, s16, v67
	v_ashrrev_i32_e32 v12, 9, v0
	v_ashrrev_i32_e32 v10, 9, v10
	v_ashrrev_i32_e32 v13, 31, v12
	v_ashrrev_i32_e32 v11, 31, v10
	v_lshlrev_b64 v[76:77], 12, v[12:13]
	v_lshlrev_b64 v[14:15], 12, v[10:11]
	v_lshl_add_u64 v[76:77], v[8:9], 0, v[76:77]
	v_lshl_add_u64 v[14:15], v[8:9], 0, v[14:15]
	global_load_dword v214, v[76:77], off
	global_load_dword v215, v[14:15], off
	v_mad_i32_i24 v234, v12, s97, v97
	v_mad_i32_i24 v235, v10, s97, v97
	s_add_i32 s12, s12, 16
	s_add_i32 s0, s0, 16
	s_add_i32 s13, s13, -16
	s_waitcnt vmcnt(0)
	v_cvt_pk_bf16_f32 v200, v200, v201
	ds_write_b16 v220, v200 offset:41216
	ds_write_b16_d16_hi v221, v200 offset:41216
	v_cvt_pk_bf16_f32 v202, v202, v203
	ds_write_b16 v222, v202 offset:41216
	ds_write_b16_d16_hi v223, v202 offset:41216
	v_cvt_pk_bf16_f32 v204, v204, v205
	ds_write_b16 v224, v204 offset:41216
	ds_write_b16_d16_hi v225, v204 offset:41216
	v_cvt_pk_bf16_f32 v206, v206, v207
	ds_write_b16 v226, v206 offset:41216
	ds_write_b16_d16_hi v227, v206 offset:41216
	v_cvt_pk_bf16_f32 v208, v208, v209
	ds_write_b16 v228, v208 offset:41216
	ds_write_b16_d16_hi v229, v208 offset:41216
	v_cvt_pk_bf16_f32 v210, v210, v211
	ds_write_b16 v230, v210 offset:41216
	ds_write_b16_d16_hi v231, v210 offset:41216
	v_cvt_pk_bf16_f32 v212, v212, v213
	ds_write_b16 v232, v212 offset:41216
	ds_write_b16_d16_hi v233, v212 offset:41216
	v_cvt_pk_bf16_f32 v214, v214, v215
	ds_write_b16 v234, v214 offset:41216
	ds_write_b16_d16_hi v235, v214 offset:41216
	s_cmp_lg_u32 s13, 0
	s_cbranch_scc1 .LBB0_694
	v_mov_b32_e32 v90, 0
	s_mov_b32 s0, 0
	v_mov_b32_e32 v0, v133
	v_mov_b32_e32 v88, 0
	v_mov_b32_e32 v86, 0
	v_mov_b32_e32 v84, 0
	v_mov_b32_e32 v82, 0
	v_mov_b32_e32 v80, 0
	v_mov_b32_e32 v78, 0
	v_mov_b32_e32 v76, 0
	v_mov_b32_e32 v91, v90
	v_mov_b32_e32 v89, v90
	v_mov_b32_e32 v87, v90
	v_mov_b32_e32 v85, v90
	v_mov_b32_e32 v83, v90
	v_mov_b32_e32 v81, v90
	v_mov_b32_e32 v79, v90
	v_mov_b32_e32 v77, v90
	s_waitcnt lgkmcnt(0)
	s_barrier

; __device__ __forceinline__ void transpose_tile(const float* __restrict__ src, int N, bf16_t* __restrict__ dst, int K, int k0, int n0,
;                                float scale, const int tidx) {
;     ...
;   __syncthreads();
; #pragma unroll
;   for (int i = 0; i < 8; i++) {
;     int e = tid + NT * i;
;     int kr = e >> 6, nc = e & 63;
;     tile[kr * 65 + nc] = src[(size_t)(k0 + kr) * N + n0 + nc];
;   }
;   __syncthreads();
; #pragma unroll
;   for (int i = 0; i < 8; i++) {
;     int e = tid + NT * i;
;     int nr = e >> 6, kc = e & 63;
;     dst[(size_t)(n0 + nr) * K + k0 + kc] = f2bf(tile[kc * 65 + nr] * scale);
;   }
.LBB0_738:
	s_andn2_b64 vcc, exec, s[12:13]
	s_cbranch_vccnz .LBB0_740
	s_lshl_b32 s0, s49, 6
	s_and_b32 s12, s0, 0x3c0
	s_lshl_b32 s0, s49, 2
	s_and_b32 s0, s0, 0x3fc0
	v_add_u32_e32 v10, s12, v92
	s_addk_i32 s0, 0xcf00
	v_ashrrev_i32_e32 v11, 31, v10
	s_waitcnt lgkmcnt(0)
	v_lshl_add_u64 v[8:9], s[0:1], 2, v[18:19]
	v_lshlrev_b64 v[10:11], 12, v[10:11]
	v_lshl_add_u64 v[10:11], v[8:9], 0, v[10:11]
	s_barrier
	global_load_dword v200, v[10:11], off
	v_add_u32_e32 v210, v94, v101
	s_mov_b32 s13, s1
	v_add_u32_e32 v10, s12, v102
	v_ashrrev_i32_e32 v11, 31, v10
	v_lshlrev_b64 v[10:11], 12, v[10:11]
	v_lshl_add_u64 v[10:11], v[8:9], 0, v[10:11]
	global_load_dword v201, v[10:11], off
	v_add_u32_e32 v211, v94, v103
	v_add_u32_e32 v10, s12, v104
	v_ashrrev_i32_e32 v11, 31, v10
	v_lshlrev_b64 v[10:11], 12, v[10:11]
	v_lshl_add_u64 v[10:11], v[8:9], 0, v[10:11]
	global_load_dword v202, v[10:11], off
	v_add_u32_e32 v212, v94, v105
	v_add_u32_e32 v10, s12, v106
	v_ashrrev_i32_e32 v11, 31, v10
	v_lshlrev_b64 v[10:11], 12, v[10:11]
	v_lshl_add_u64 v[10:11], v[8:9], 0, v[10:11]
	global_load_dword v203, v[10:11], off
	v_add_u32_e32 v213, v94, v107
	v_add_u32_e32 v10, s12, v108
	v_ashrrev_i32_e32 v11, 31, v10
	v_lshlrev_b64 v[10:11], 12, v[10:11]
	v_lshl_add_u64 v[10:11], v[8:9], 0, v[10:11]
	global_load_dword v204, v[10:11], off
	v_add_u32_e32 v214, v94, v109
	v_add_u32_e32 v10, s12, v110
	v_ashrrev_i32_e32 v11, 31, v10
	v_lshlrev_b64 v[10:11], 12, v[10:11]
	v_lshl_add_u64 v[10:11], v[8:9], 0, v[10:11]
	global_load_dword v205, v[10:11], off
	v_add_u32_e32 v215, v94, v111
	v_add_u32_e32 v10, s12, v112
	v_ashrrev_i32_e32 v11, 31, v10
	v_lshlrev_b64 v[10:11], 12, v[10:11]
	v_lshl_add_u64 v[10:11], v[8:9], 0, v[10:11]
	global_load_dword v206, v[10:11], off
	v_add_u32_e32 v216, v94, v113
	v_add_u32_e32 v10, s12, v114
	v_ashrrev_i32_e32 v11, 31, v10
	v_lshlrev_b64 v[10:11], 12, v[10:11]
	v_lshl_add_u64 v[8:9], v[8:9], 0, v[10:11]
	global_load_dword v207, v[8:9], off
	v_add_u32_e32 v217, v94, v115
	v_add_u32_e32 v10, s0, v92
	s_lshl_b32 s12, s12, 1
	v_ashrrev_i32_e32 v11, 31, v10
	v_lshlrev_b64 v[10:11], 11, v[10:11]
	s_waitcnt vmcnt(0)
	ds_write_b32 v210, v200
	ds_write_b32 v211, v201
	ds_write_b32 v212, v202
	ds_write_b32 v213, v203
	ds_write_b32 v214, v204
	ds_write_b32 v215, v205
	ds_write_b32 v216, v206
	ds_write_b32 v217, v207
	s_waitcnt lgkmcnt(0)
	s_barrier
	ds_read_b32 v0, v116
	v_lshl_add_u64 v[8:9], v[42:43], 0, s[12:13]
	v_lshl_add_u64 v[10:11], v[8:9], 0, v[10:11]
	s_waitcnt lgkmcnt(0)
	v_cvt_pk_bf16_f32 v0, v0, s0
	global_store_short v[10:11], v0, off
	ds_read_b32 v0, v117
	v_add_u32_e32 v10, s0, v102
	v_ashrrev_i32_e32 v11, 31, v10
	v_lshlrev_b64 v[10:11], 11, v[10:11]
	v_lshl_add_u64 v[10:11], v[8:9], 0, v[10:11]
	s_waitcnt lgkmcnt(0)
	v_cvt_pk_bf16_f32 v0, v0, s0
	global_store_short v[10:11], v0, off
	ds_read_b32 v0, v118
	v_add_u32_e32 v10, s0, v104
	v_ashrrev_i32_e32 v11, 31, v10
	v_lshlrev_b64 v[10:11], 11, v[10:11]
	v_lshl_add_u64 v[10:11], v[8:9], 0, v[10:11]
	s_waitcnt lgkmcnt(0)
	v_cvt_pk_bf16_f32 v0, v0, s0
	global_store_short v[10:11], v0, off
	ds_read_b32 v0, v119
	v_add_u32_e32 v10, s0, v106
	v_ashrrev_i32_e32 v11, 31, v10
	v_lshlrev_b64 v[10:11], 11, v[10:11]
	v_lshl_add_u64 v[10:11], v[8:9], 0, v[10:11]
	s_waitcnt lgkmcnt(0)
	v_cvt_pk_bf16_f32 v0, v0, s0
	global_store_short v[10:11], v0, off
	ds_read_b32 v0, v120
	v_add_u32_e32 v10, s0, v108
	v_ashrrev_i32_e32 v11, 31, v10
	v_lshlrev_b64 v[10:11], 11, v[10:11]
	v_lshl_add_u64 v[10:11], v[8:9], 0, v[10:11]
	s_waitcnt lgkmcnt(0)
	v_cvt_pk_bf16_f32 v0, v0, s0
	global_store_short v[10:11], v0, off
	ds_read_b32 v0, v121
	v_add_u32_e32 v10, s0, v110
	v_ashrrev_i32_e32 v11, 31, v10
	v_lshlrev_b64 v[10:11], 11, v[10:11]
	v_lshl_add_u64 v[10:11], v[8:9], 0, v[10:11]
	s_waitcnt lgkmcnt(0)
	v_cvt_pk_bf16_f32 v0, v0, s0
	global_store_short v[10:11], v0, off
	ds_read_b32 v0, v122
	v_add_u32_e32 v10, s0, v112
	v_ashrrev_i32_e32 v11, 31, v10
	v_lshlrev_b64 v[10:11], 11, v[10:11]
	v_lshl_add_u64 v[10:11], v[8:9], 0, v[10:11]
	s_waitcnt lgkmcnt(0)
	v_cvt_pk_bf16_f32 v0, v0, s0
	global_store_short v[10:11], v0, off
	ds_read_b32 v0, v123
	v_add_u32_e32 v10, s0, v114
	v_ashrrev_i32_e32 v11, 31, v10
	v_lshlrev_b64 v[10:11], 11, v[10:11]
	v_lshl_add_u64 v[8:9], v[8:9], 0, v[10:11]
	s_waitcnt lgkmcnt(0)
	v_cvt_pk_bf16_f32 v0, v0, s0
	global_store_short v[8:9], v0, off

; __device__ __forceinline__ void transpose_tile(const float* __restrict__ src, int N, bf16_t* __restrict__ dst, int K, int k0, int n0,
;                                float scale, const int tidx) {
;     ...
;   __syncthreads();
; #pragma unroll
;   for (int i = 0; i < 8; i++) {
;     int e = tid + NT * i;
;     int kr = e >> 6, nc = e & 63;
;     tile[kr * 65 + nc] = src[(size_t)(k0 + kr) * N + n0 + nc];
;   }
;   __syncthreads();
; #pragma unroll
;   for (int i = 0; i < 8; i++) {
;     int e = tid + NT * i;
;     int nr = e >> 6, kc = e & 63;
;     dst[(size_t)(n0 + nr) * K + k0 + kc] = f2bf(tile[kc * 65 + nr] * scale);
;   }
.LBB0_741:
	s_andn2_b64 vcc, exec, s[12:13]
	s_cbranch_vccnz .LBB0_743
	s_lshl_b32 s0, s49, 6
	s_and_b32 s12, s0, 0x3c0
	s_lshl_b32 s0, s49, 2
	s_and_b32 s0, s0, 0x3fc0
	v_add_u32_e32 v10, s12, v92
	s_addk_i32 s0, 0xd300
	v_ashrrev_i32_e32 v11, 31, v10
	s_waitcnt lgkmcnt(0)
	v_lshl_add_u64 v[8:9], s[0:1], 2, v[20:21]
	v_lshlrev_b64 v[10:11], 12, v[10:11]
	v_lshl_add_u64 v[10:11], v[8:9], 0, v[10:11]
	s_barrier
	global_load_dword v200, v[10:11], off
	v_add_u32_e32 v210, v94, v101
	s_mov_b32 s13, s1
	v_add_u32_e32 v10, s12, v102
	v_ashrrev_i32_e32 v11, 31, v10
	v_lshlrev_b64 v[10:11], 12, v[10:11]
	v_lshl_add_u64 v[10:11], v[8:9], 0, v[10:11]
	global_load_dword v201, v[10:11], off
	v_add_u32_e32 v211, v94, v103
	v_add_u32_e32 v10, s12, v104
	v_ashrrev_i32_e32 v11, 31, v10
	v_lshlrev_b64 v[10:11], 12, v[10:11]
	v_lshl_add_u64 v[10:11], v[8:9], 0, v[10:11]
	global_load_dword v202, v[10:11], off
	v_add_u32_e32 v212, v94, v105
	v_add_u32_e32 v10, s12, v106
	v_ashrrev_i32_e32 v11, 31, v10
	v_lshlrev_b64 v[10:11], 12, v[10:11]
	v_lshl_add_u64 v[10:11], v[8:9], 0, v[10:11]
	global_load_dword v203, v[10:11], off
	v_add_u32_e32 v213, v94, v107
	v_add_u32_e32 v10, s12, v108
	v_ashrrev_i32_e32 v11, 31, v10
	v_lshlrev_b64 v[10:11], 12, v[10:11]
	v_lshl_add_u64 v[10:11], v[8:9], 0, v[10:11]
	global_load_dword v204, v[10:11], off
	v_add_u32_e32 v214, v94, v109
	v_add_u32_e32 v10, s12, v110
	v_ashrrev_i32_e32 v11, 31, v10
	v_lshlrev_b64 v[10:11], 12, v[10:11]
	v_lshl_add_u64 v[10:11], v[8:9], 0, v[10:11]
	global_load_dword v205, v[10:11], off
	v_add_u32_e32 v215, v94, v111
	v_add_u32_e32 v10, s12, v112
	v_ashrrev_i32_e32 v11, 31, v10
	v_lshlrev_b64 v[10:11], 12, v[10:11]
	v_lshl_add_u64 v[10:11], v[8:9], 0, v[10:11]
	global_load_dword v206, v[10:11], off
	v_add_u32_e32 v216, v94, v113
	v_add_u32_e32 v10, s12, v114
	v_ashrrev_i32_e32 v11, 31, v10
	v_lshlrev_b64 v[10:11], 12, v[10:11]
	v_lshl_add_u64 v[8:9], v[8:9], 0, v[10:11]
	global_load_dword v207, v[8:9], off
	v_add_u32_e32 v217, v94, v115
	v_add_u32_e32 v10, s0, v92
	s_lshl_b32 s12, s12, 1
	v_ashrrev_i32_e32 v11, 31, v10
	v_lshlrev_b64 v[10:11], 11, v[10:11]
	s_waitcnt vmcnt(0)
	ds_write_b32 v210, v200
	ds_write_b32 v211, v201
	ds_write_b32 v212, v202
	ds_write_b32 v213, v203
	ds_write_b32 v214, v204
	ds_write_b32 v215, v205
	ds_write_b32 v216, v206
	ds_write_b32 v217, v207
	s_waitcnt lgkmcnt(0)
	s_barrier
	ds_read_b32 v0, v116
	v_lshl_add_u64 v[8:9], v[44:45], 0, s[12:13]
	v_lshl_add_u64 v[10:11], v[8:9], 0, v[10:11]
	s_waitcnt lgkmcnt(0)
	v_cvt_pk_bf16_f32 v0, v0, s0
	global_store_short v[10:11], v0, off
	ds_read_b32 v0, v117
	v_add_u32_e32 v10, s0, v102
	v_ashrrev_i32_e32 v11, 31, v10
	v_lshlrev_b64 v[10:11], 11, v[10:11]
	v_lshl_add_u64 v[10:11], v[8:9], 0, v[10:11]
	s_waitcnt lgkmcnt(0)
	v_cvt_pk_bf16_f32 v0, v0, s0
	global_store_short v[10:11], v0, off
	ds_read_b32 v0, v118
	v_add_u32_e32 v10, s0, v104
	v_ashrrev_i32_e32 v11, 31, v10
	v_lshlrev_b64 v[10:11], 11, v[10:11]
	v_lshl_add_u64 v[10:11], v[8:9], 0, v[10:11]
	s_waitcnt lgkmcnt(0)
	v_cvt_pk_bf16_f32 v0, v0, s0
	global_store_short v[10:11], v0, off
	ds_read_b32 v0, v119
	v_add_u32_e32 v10, s0, v106
	v_ashrrev_i32_e32 v11, 31, v10
	v_lshlrev_b64 v[10:11], 11, v[10:11]
	v_lshl_add_u64 v[10:11], v[8:9], 0, v[10:11]
	s_waitcnt lgkmcnt(0)
	v_cvt_pk_bf16_f32 v0, v0, s0
	global_store_short v[10:11], v0, off
	ds_read_b32 v0, v120
	v_add_u32_e32 v10, s0, v108
	v_ashrrev_i32_e32 v11, 31, v10
	v_lshlrev_b64 v[10:11], 11, v[10:11]
	v_lshl_add_u64 v[10:11], v[8:9], 0, v[10:11]
	s_waitcnt lgkmcnt(0)
	v_cvt_pk_bf16_f32 v0, v0, s0
	global_store_short v[10:11], v0, off
	ds_read_b32 v0, v121
	v_add_u32_e32 v10, s0, v110
	v_ashrrev_i32_e32 v11, 31, v10
	v_lshlrev_b64 v[10:11], 11, v[10:11]
	v_lshl_add_u64 v[10:11], v[8:9], 0, v[10:11]
	s_waitcnt lgkmcnt(0)
	v_cvt_pk_bf16_f32 v0, v0, s0
	global_store_short v[10:11], v0, off
	ds_read_b32 v0, v122
	v_add_u32_e32 v10, s0, v112
	v_ashrrev_i32_e32 v11, 31, v10
	v_lshlrev_b64 v[10:11], 11, v[10:11]
	v_lshl_add_u64 v[10:11], v[8:9], 0, v[10:11]
	s_waitcnt lgkmcnt(0)
	v_cvt_pk_bf16_f32 v0, v0, s0
	global_store_short v[10:11], v0, off
	ds_read_b32 v0, v123
	v_add_u32_e32 v10, s0, v114
	v_ashrrev_i32_e32 v11, 31, v10
	v_lshlrev_b64 v[10:11], 11, v[10:11]
	v_lshl_add_u64 v[8:9], v[8:9], 0, v[10:11]
	s_waitcnt lgkmcnt(0)
	v_cvt_pk_bf16_f32 v0, v0, s0
	global_store_short v[8:9], v0, off

; __device__ __forceinline__ void transpose_tile(const float* __restrict__ src, int N, bf16_t* __restrict__ dst, int K, int k0, int n0,
;                                float scale, const int tidx) {
;     ...
;   __syncthreads();
; #pragma unroll
;   for (int i = 0; i < 8; i++) {
;     int e = tid + NT * i;
;     int kr = e >> 6, nc = e & 63;
;     tile[kr * 65 + nc] = src[(size_t)(k0 + kr) * N + n0 + nc];
;   }
;   __syncthreads();
; #pragma unroll
;   for (int i = 0; i < 8; i++) {
;     int e = tid + NT * i;
;     int nr = e >> 6, kc = e & 63;
;     dst[(size_t)(n0 + nr) * K + k0 + kc] = f2bf(tile[kc * 65 + nr] * scale);
;   }
.LBB0_744:
	s_andn2_b64 vcc, exec, s[12:13]
	s_cbranch_vccnz .LBB0_746
	s_lshl_b32 s0, s49, 6
	s_and_b32 s12, s0, 0x1c0
	s_lshl_b32 s0, s49, 3
	s_and_b32 s0, s0, 0x7fc0
	v_add_u32_e32 v10, s12, v92
	s_addk_i32 s0, 0xaa00
	v_ashrrev_i32_e32 v11, 31, v10
	s_waitcnt lgkmcnt(0)
	v_lshl_add_u64 v[8:9], s[0:1], 2, v[22:23]
	v_lshlrev_b64 v[10:11], 12, v[10:11]
	v_lshl_add_u64 v[10:11], v[8:9], 0, v[10:11]
	s_barrier
	global_load_dword v200, v[10:11], off
	v_add_u32_e32 v210, v94, v101
	s_mov_b32 s13, s1
	v_add_u32_e32 v10, s12, v102
	v_ashrrev_i32_e32 v11, 31, v10
	v_lshlrev_b64 v[10:11], 12, v[10:11]
	v_lshl_add_u64 v[10:11], v[8:9], 0, v[10:11]
	global_load_dword v201, v[10:11], off
	v_add_u32_e32 v211, v94, v103
	v_add_u32_e32 v10, s12, v104
	v_ashrrev_i32_e32 v11, 31, v10
	v_lshlrev_b64 v[10:11], 12, v[10:11]
	v_lshl_add_u64 v[10:11], v[8:9], 0, v[10:11]
	global_load_dword v202, v[10:11], off
	v_add_u32_e32 v212, v94, v105
	v_add_u32_e32 v10, s12, v106
	v_ashrrev_i32_e32 v11, 31, v10
	v_lshlrev_b64 v[10:11], 12, v[10:11]
	v_lshl_add_u64 v[10:11], v[8:9], 0, v[10:11]
	global_load_dword v203, v[10:11], off
	v_add_u32_e32 v213, v94, v107
	v_add_u32_e32 v10, s12, v108
	v_ashrrev_i32_e32 v11, 31, v10
	v_lshlrev_b64 v[10:11], 12, v[10:11]
	v_lshl_add_u64 v[10:11], v[8:9], 0, v[10:11]
	global_load_dword v204, v[10:11], off
	v_add_u32_e32 v214, v94, v109
	v_add_u32_e32 v10, s12, v110
	v_ashrrev_i32_e32 v11, 31, v10
	v_lshlrev_b64 v[10:11], 12, v[10:11]
	v_lshl_add_u64 v[10:11], v[8:9], 0, v[10:11]
	global_load_dword v205, v[10:11], off
	v_add_u32_e32 v215, v94, v111
	v_add_u32_e32 v10, s12, v112
	v_ashrrev_i32_e32 v11, 31, v10
	v_lshlrev_b64 v[10:11], 12, v[10:11]
	v_lshl_add_u64 v[10:11], v[8:9], 0, v[10:11]
	global_load_dword v206, v[10:11], off
	v_add_u32_e32 v216, v94, v113
	v_add_u32_e32 v10, s12, v114
	v_ashrrev_i32_e32 v11, 31, v10
	v_lshlrev_b64 v[10:11], 12, v[10:11]
	v_lshl_add_u64 v[8:9], v[8:9], 0, v[10:11]
	global_load_dword v207, v[8:9], off
	v_add_u32_e32 v217, v94, v115
	v_add_u32_e32 v10, s0, v92
	s_lshl_b32 s12, s12, 1
	v_ashrrev_i32_e32 v11, 31, v10
	v_lshlrev_b64 v[10:11], 10, v[10:11]
	s_waitcnt vmcnt(0)
	ds_write_b32 v210, v200
	ds_write_b32 v211, v201
	ds_write_b32 v212, v202
	ds_write_b32 v213, v203
	ds_write_b32 v214, v204
	ds_write_b32 v215, v205
	ds_write_b32 v216, v206
	ds_write_b32 v217, v207
	s_waitcnt lgkmcnt(0)
	s_barrier
	ds_read_b32 v0, v116
	v_lshl_add_u64 v[8:9], v[46:47], 0, s[12:13]
	v_lshl_add_u64 v[10:11], v[8:9], 0, v[10:11]
	s_waitcnt lgkmcnt(0)
	v_cvt_pk_bf16_f32 v0, v0, s0
	global_store_short v[10:11], v0, off
	ds_read_b32 v0, v117
	v_add_u32_e32 v10, s0, v102
	v_ashrrev_i32_e32 v11, 31, v10
	v_lshlrev_b64 v[10:11], 10, v[10:11]
	v_lshl_add_u64 v[10:11], v[8:9], 0, v[10:11]
	s_waitcnt lgkmcnt(0)
	v_cvt_pk_bf16_f32 v0, v0, s0
	global_store_short v[10:11], v0, off
	ds_read_b32 v0, v118
	v_add_u32_e32 v10, s0, v104
	v_ashrrev_i32_e32 v11, 31, v10
	v_lshlrev_b64 v[10:11], 10, v[10:11]
	v_lshl_add_u64 v[10:11], v[8:9], 0, v[10:11]
	s_waitcnt lgkmcnt(0)
	v_cvt_pk_bf16_f32 v0, v0, s0
	global_store_short v[10:11], v0, off
	ds_read_b32 v0, v119
	v_add_u32_e32 v10, s0, v106
	v_ashrrev_i32_e32 v11, 31, v10
	v_lshlrev_b64 v[10:11], 10, v[10:11]
	v_lshl_add_u64 v[10:11], v[8:9], 0, v[10:11]
	s_waitcnt lgkmcnt(0)
	v_cvt_pk_bf16_f32 v0, v0, s0
	global_store_short v[10:11], v0, off
	ds_read_b32 v0, v120
	v_add_u32_e32 v10, s0, v108
	v_ashrrev_i32_e32 v11, 31, v10
	v_lshlrev_b64 v[10:11], 10, v[10:11]
	v_lshl_add_u64 v[10:11], v[8:9], 0, v[10:11]
	s_waitcnt lgkmcnt(0)
	v_cvt_pk_bf16_f32 v0, v0, s0
	global_store_short v[10:11], v0, off
	ds_read_b32 v0, v121
	v_add_u32_e32 v10, s0, v110
	v_ashrrev_i32_e32 v11, 31, v10
	v_lshlrev_b64 v[10:11], 10, v[10:11]
	v_lshl_add_u64 v[10:11], v[8:9], 0, v[10:11]
	s_waitcnt lgkmcnt(0)
	v_cvt_pk_bf16_f32 v0, v0, s0
	global_store_short v[10:11], v0, off
	ds_read_b32 v0, v122
	v_add_u32_e32 v10, s0, v112
	v_ashrrev_i32_e32 v11, 31, v10
	v_lshlrev_b64 v[10:11], 10, v[10:11]
	v_lshl_add_u64 v[10:11], v[8:9], 0, v[10:11]
	s_waitcnt lgkmcnt(0)
	v_cvt_pk_bf16_f32 v0, v0, s0
	global_store_short v[10:11], v0, off
	ds_read_b32 v0, v123
	v_add_u32_e32 v10, s0, v114
	v_ashrrev_i32_e32 v11, 31, v10
	v_lshlrev_b64 v[10:11], 10, v[10:11]
	v_lshl_add_u64 v[8:9], v[8:9], 0, v[10:11]
	s_waitcnt lgkmcnt(0)
	v_cvt_pk_bf16_f32 v0, v0, s0
	global_store_short v[8:9], v0, off

; __device__ __forceinline__ void transpose_tile(const float* __restrict__ src, int N, bf16_t* __restrict__ dst, int K, int k0, int n0,
;                                float scale, const int tidx) {
;     ...
;   __syncthreads();
; #pragma unroll
;   for (int i = 0; i < 8; i++) {
;     int e = tid + NT * i;
;     int kr = e >> 6, nc = e & 63;
;     tile[kr * 65 + nc] = src[(size_t)(k0 + kr) * N + n0 + nc];
;   }
;   __syncthreads();
; #pragma unroll
;   for (int i = 0; i < 8; i++) {
;     int e = tid + NT * i;
;     int nr = e >> 6, kc = e & 63;
;     dst[(size_t)(n0 + nr) * K + k0 + kc] = f2bf(tile[kc * 65 + nr] * scale);
;   }
.LBB0_747:
	s_andn2_b64 vcc, exec, s[12:13]
	s_cbranch_vccnz .LBB0_749
	s_lshl_b32 s0, s49, 6
	s_and_b32 s12, s0, 0x1c0
	s_lshl_b32 s0, s49, 3
	s_and_b32 s0, s0, 0x7fc0
	v_add_u32_e32 v10, s12, v92
	s_addk_i32 s0, 0xae00
	v_ashrrev_i32_e32 v11, 31, v10
	s_waitcnt lgkmcnt(0)
	v_lshl_add_u64 v[8:9], s[0:1], 2, v[24:25]
	v_lshlrev_b64 v[10:11], 12, v[10:11]
	v_lshl_add_u64 v[10:11], v[8:9], 0, v[10:11]
	s_barrier
	global_load_dword v200, v[10:11], off
	v_add_u32_e32 v210, v94, v101
	s_mov_b32 s13, s1
	v_add_u32_e32 v10, s12, v102
	v_ashrrev_i32_e32 v11, 31, v10
	v_lshlrev_b64 v[10:11], 12, v[10:11]
	v_lshl_add_u64 v[10:11], v[8:9], 0, v[10:11]
	global_load_dword v201, v[10:11], off
	v_add_u32_e32 v211, v94, v103
	v_add_u32_e32 v10, s12, v104
	v_ashrrev_i32_e32 v11, 31, v10
	v_lshlrev_b64 v[10:11], 12, v[10:11]
	v_lshl_add_u64 v[10:11], v[8:9], 0, v[10:11]
	global_load_dword v202, v[10:11], off
	v_add_u32_e32 v212, v94, v105
	v_add_u32_e32 v10, s12, v106
	v_ashrrev_i32_e32 v11, 31, v10
	v_lshlrev_b64 v[10:11], 12, v[10:11]
	v_lshl_add_u64 v[10:11], v[8:9], 0, v[10:11]
	global_load_dword v203, v[10:11], off
	v_add_u32_e32 v213, v94, v107
	v_add_u32_e32 v10, s12, v108
	v_ashrrev_i32_e32 v11, 31, v10
	v_lshlrev_b64 v[10:11], 12, v[10:11]
	v_lshl_add_u64 v[10:11], v[8:9], 0, v[10:11]
	global_load_dword v204, v[10:11], off
	v_add_u32_e32 v214, v94, v109
	v_add_u32_e32 v10, s12, v110
	v_ashrrev_i32_e32 v11, 31, v10
	v_lshlrev_b64 v[10:11], 12, v[10:11]
	v_lshl_add_u64 v[10:11], v[8:9], 0, v[10:11]
	global_load_dword v205, v[10:11], off
	v_add_u32_e32 v215, v94, v111
	v_add_u32_e32 v10, s12, v112
	v_ashrrev_i32_e32 v11, 31, v10
	v_lshlrev_b64 v[10:11], 12, v[10:11]
	v_lshl_add_u64 v[10:11], v[8:9], 0, v[10:11]
	global_load_dword v206, v[10:11], off
	v_add_u32_e32 v216, v94, v113
	v_add_u32_e32 v10, s12, v114
	v_ashrrev_i32_e32 v11, 31, v10
	v_lshlrev_b64 v[10:11], 12, v[10:11]
	v_lshl_add_u64 v[8:9], v[8:9], 0, v[10:11]
	global_load_dword v207, v[8:9], off
	v_add_u32_e32 v217, v94, v115
	v_add_u32_e32 v10, s0, v92
	s_lshl_b32 s12, s12, 1
	v_ashrrev_i32_e32 v11, 31, v10
	v_lshlrev_b64 v[10:11], 10, v[10:11]
	s_waitcnt vmcnt(0)
	ds_write_b32 v210, v200
	ds_write_b32 v211, v201
	ds_write_b32 v212, v202
	ds_write_b32 v213, v203
	ds_write_b32 v214, v204
	ds_write_b32 v215, v205
	ds_write_b32 v216, v206
	ds_write_b32 v217, v207
	s_waitcnt lgkmcnt(0)
	s_barrier
	ds_read_b32 v0, v116
	v_lshl_add_u64 v[8:9], v[48:49], 0, s[12:13]
	v_lshl_add_u64 v[10:11], v[8:9], 0, v[10:11]
	s_waitcnt lgkmcnt(0)
	v_cvt_pk_bf16_f32 v0, v0, s0
	global_store_short v[10:11], v0, off
	ds_read_b32 v0, v117
	v_add_u32_e32 v10, s0, v102
	v_ashrrev_i32_e32 v11, 31, v10
	v_lshlrev_b64 v[10:11], 10, v[10:11]
	v_lshl_add_u64 v[10:11], v[8:9], 0, v[10:11]
	s_waitcnt lgkmcnt(0)
	v_cvt_pk_bf16_f32 v0, v0, s0
	global_store_short v[10:11], v0, off
	ds_read_b32 v0, v118
	v_add_u32_e32 v10, s0, v104
	v_ashrrev_i32_e32 v11, 31, v10
	v_lshlrev_b64 v[10:11], 10, v[10:11]
	v_lshl_add_u64 v[10:11], v[8:9], 0, v[10:11]
	s_waitcnt lgkmcnt(0)
	v_cvt_pk_bf16_f32 v0, v0, s0
	global_store_short v[10:11], v0, off
	ds_read_b32 v0, v119
	v_add_u32_e32 v10, s0, v106
	v_ashrrev_i32_e32 v11, 31, v10
	v_lshlrev_b64 v[10:11], 10, v[10:11]
	v_lshl_add_u64 v[10:11], v[8:9], 0, v[10:11]
	s_waitcnt lgkmcnt(0)
	v_cvt_pk_bf16_f32 v0, v0, s0
	global_store_short v[10:11], v0, off
	ds_read_b32 v0, v120
	v_add_u32_e32 v10, s0, v108
	v_ashrrev_i32_e32 v11, 31, v10
	v_lshlrev_b64 v[10:11], 10, v[10:11]
	v_lshl_add_u64 v[10:11], v[8:9], 0, v[10:11]
	s_waitcnt lgkmcnt(0)
	v_cvt_pk_bf16_f32 v0, v0, s0
	global_store_short v[10:11], v0, off
	ds_read_b32 v0, v121
	v_add_u32_e32 v10, s0, v110
	v_ashrrev_i32_e32 v11, 31, v10
	v_lshlrev_b64 v[10:11], 10, v[10:11]
	v_lshl_add_u64 v[10:11], v[8:9], 0, v[10:11]
	s_waitcnt lgkmcnt(0)
	v_cvt_pk_bf16_f32 v0, v0, s0
	global_store_short v[10:11], v0, off
	ds_read_b32 v0, v122
	v_add_u32_e32 v10, s0, v112
	v_ashrrev_i32_e32 v11, 31, v10
	v_lshlrev_b64 v[10:11], 10, v[10:11]
	v_lshl_add_u64 v[10:11], v[8:9], 0, v[10:11]
	s_waitcnt lgkmcnt(0)
	v_cvt_pk_bf16_f32 v0, v0, s0
	global_store_short v[10:11], v0, off
	ds_read_b32 v0, v123
	v_add_u32_e32 v10, s0, v114
	v_ashrrev_i32_e32 v11, 31, v10
	v_lshlrev_b64 v[10:11], 10, v[10:11]
	v_lshl_add_u64 v[8:9], v[8:9], 0, v[10:11]
	s_waitcnt lgkmcnt(0)
	v_cvt_pk_bf16_f32 v0, v0, s0
	global_store_short v[8:9], v0, off

; __device__ __forceinline__ void transpose_tile(const float* __restrict__ src, int N, bf16_t* __restrict__ dst, int K, int k0, int n0,
;                                float scale, const int tidx) {
;   float* tile = (float*)smem_raw;
;   const int tid = tidx;
;   __syncthreads();
; #pragma unroll
;   for (int i = 0; i < 8; i++) {
;     int e = tid + NT * i;
;     int kr = e >> 6, nc = e & 63;
;     tile[kr * 65 + nc] = src[(size_t)(k0 + kr) * N + n0 + nc];
;   }
;   __syncthreads();
; #pragma unroll
;   for (int i = 0; i < 8; i++) {
;     int e = tid + NT * i;
;     int nr = e >> 6, kc = e & 63;
;     dst[(size_t)(n0 + nr) * K + k0 + kc] = f2bf(tile[kc * 65 + nr] * scale);
;   }
; }
.LBB0_750:
	s_andn2_b64 vcc, exec, s[12:13]
	s_cbranch_vccnz .LBB0_595
	s_ashr_i32 s0, s49, 31
	s_lshr_b32 s0, s0, 28
	s_add_i32 s0, s49, s0
	s_and_b32 s12, s0, 0x3fffff0
	s_lshl_b32 s0, s0, 2
	s_sub_i32 s12, s49, s12
	s_and_b32 s26, s0, 0xffffffc0
	s_lshl_b32 s12, s12, 6
	s_ashr_i32 s27, s26, 31
	s_waitcnt lgkmcnt(0)
	v_lshl_add_u64 v[8:9], s[26:27], 2, v[26:27]
	v_add_u32_e32 v0, s12, v92
	s_mov_b32 s0, 0xa400
	v_mad_i64_i32 v[10:11], s[16:17], v0, s0, v[8:9]
	s_barrier
	global_load_dword v200, v[10:11], off
	v_add_u32_e32 v210, v94, v101
	s_ashr_i32 s13, s12, 31
	v_add_u32_e32 v0, s12, v102
	v_mad_i64_i32 v[10:11], s[16:17], v0, s0, v[8:9]
	global_load_dword v201, v[10:11], off
	v_add_u32_e32 v211, v94, v103
	v_add_u32_e32 v0, s12, v104
	v_mad_i64_i32 v[10:11], s[16:17], v0, s0, v[8:9]
	global_load_dword v202, v[10:11], off
	v_add_u32_e32 v212, v94, v105
	v_add_u32_e32 v0, s12, v106
	v_mad_i64_i32 v[10:11], s[16:17], v0, s0, v[8:9]
	global_load_dword v203, v[10:11], off
	v_add_u32_e32 v213, v94, v107
	v_add_u32_e32 v0, s12, v108
	v_mad_i64_i32 v[10:11], s[16:17], v0, s0, v[8:9]
	global_load_dword v204, v[10:11], off
	v_add_u32_e32 v214, v94, v109
	v_add_u32_e32 v0, s12, v110
	v_mad_i64_i32 v[10:11], s[16:17], v0, s0, v[8:9]
	global_load_dword v205, v[10:11], off
	v_add_u32_e32 v215, v94, v111
	v_add_u32_e32 v0, s12, v112
	v_mad_i64_i32 v[10:11], s[16:17], v0, s0, v[8:9]
	global_load_dword v206, v[10:11], off
	v_add_u32_e32 v216, v94, v113
	v_add_u32_e32 v0, s12, v114
	v_mad_i64_i32 v[8:9], s[16:17], v0, s0, v[8:9]
	global_load_dword v207, v[8:9], off
	v_add_u32_e32 v217, v94, v115
	v_add_u32_e32 v10, s26, v92
	v_ashrrev_i32_e32 v11, 31, v10
	v_lshlrev_b64 v[10:11], 11, v[10:11]
	s_waitcnt vmcnt(0)
	ds_write_b32 v210, v200
	ds_write_b32 v211, v201
	ds_write_b32 v212, v202
	ds_write_b32 v213, v203
	ds_write_b32 v214, v204
	ds_write_b32 v215, v205
	ds_write_b32 v216, v206
	ds_write_b32 v217, v207
	s_waitcnt lgkmcnt(0)
	s_barrier
	ds_read_b32 v0, v116
	v_lshl_add_u64 v[8:9], s[12:13], 1, v[50:51]
	v_lshl_add_u64 v[10:11], v[8:9], 0, v[10:11]
	s_waitcnt lgkmcnt(0)
	v_cvt_pk_bf16_f32 v0, v0, s0
	global_store_short v[10:11], v0, off
	ds_read_b32 v0, v117
	v_add_u32_e32 v10, s26, v102
	v_ashrrev_i32_e32 v11, 31, v10
	v_lshlrev_b64 v[10:11], 11, v[10:11]
	v_lshl_add_u64 v[10:11], v[8:9], 0, v[10:11]
	s_waitcnt lgkmcnt(0)
	v_cvt_pk_bf16_f32 v0, v0, s0
	global_store_short v[10:11], v0, off
	ds_read_b32 v0, v118
	v_add_u32_e32 v10, s26, v104
	v_ashrrev_i32_e32 v11, 31, v10
	v_lshlrev_b64 v[10:11], 11, v[10:11]
	v_lshl_add_u64 v[10:11], v[8:9], 0, v[10:11]
	s_waitcnt lgkmcnt(0)
	v_cvt_pk_bf16_f32 v0, v0, s0
	global_store_short v[10:11], v0, off
	ds_read_b32 v0, v119
	v_add_u32_e32 v10, s26, v106
	v_ashrrev_i32_e32 v11, 31, v10
	v_lshlrev_b64 v[10:11], 11, v[10:11]
	v_lshl_add_u64 v[10:11], v[8:9], 0, v[10:11]
	s_waitcnt lgkmcnt(0)
	v_cvt_pk_bf16_f32 v0, v0, s0
	global_store_short v[10:11], v0, off
	ds_read_b32 v0, v120
	v_add_u32_e32 v10, s26, v108
	v_ashrrev_i32_e32 v11, 31, v10
	v_lshlrev_b64 v[10:11], 11, v[10:11]
	v_lshl_add_u64 v[10:11], v[8:9], 0, v[10:11]
	s_waitcnt lgkmcnt(0)
	v_cvt_pk_bf16_f32 v0, v0, s0
	global_store_short v[10:11], v0, off
	ds_read_b32 v0, v121
	v_add_u32_e32 v10, s26, v110
	v_ashrrev_i32_e32 v11, 31, v10
	v_lshlrev_b64 v[10:11], 11, v[10:11]
	v_lshl_add_u64 v[10:11], v[8:9], 0, v[10:11]
	s_waitcnt lgkmcnt(0)
	v_cvt_pk_bf16_f32 v0, v0, s0
	global_store_short v[10:11], v0, off
	ds_read_b32 v0, v122
	v_add_u32_e32 v10, s26, v112
	v_ashrrev_i32_e32 v11, 31, v10
	v_lshlrev_b64 v[10:11], 11, v[10:11]
	v_lshl_add_u64 v[10:11], v[8:9], 0, v[10:11]
	s_waitcnt lgkmcnt(0)
	v_cvt_pk_bf16_f32 v0, v0, s0
	global_store_short v[10:11], v0, off
	ds_read_b32 v0, v123
	v_add_u32_e32 v10, s26, v114
	v_ashrrev_i32_e32 v11, 31, v10
	v_lshlrev_b64 v[10:11], 11, v[10:11]
	v_lshl_add_u64 v[8:9], v[8:9], 0, v[10:11]
	s_waitcnt lgkmcnt(0)
	v_cvt_pk_bf16_f32 v0, v0, s0
	global_store_short v[8:9], v0, off
	s_branch .LBB0_595

; __device__ __forceinline__ void phase_norm(const Params& p, int l, int mode, const int tidx) {
;     ...
;   for (int row0 = gw; row0 < T; row0 += 2 * nw) {
;     float4 xv[2][4];
;     u32x2 ov[2][4];
;     float rsv[2];
; #pragma unroll
;     for (int u = 0; u < 2; u++) {
;       const int row = row0 + u * nw;
; #pragma unroll
;       for (int i = 0; i < 4; i++) xv[u][i] = *(const float4*)(src + (size_t)row * 1024 + i * 256 + lane * 4);
;       if (do_res) {
;         float rs = 0.f;
; #pragma unroll
;         for (int n = 0; n < 16; n++) rs += rss[(size_t)n * T + row];
;         rsv[u] = rs;
; #pragma unroll
;         for (int i = 0; i < 4; i++) ov[u][i] = *(const u32x2*)(P + (size_t)row * NP + OFF_OUT + i * 256 + lane * 4);
;       }
.LBB0_756:
	v_lshl_add_u64 v[8:9], v[66:67], 0, v[64:65]
	global_load_dwordx4 v[32:35], v[8:9], off
	global_load_dwordx4 v[28:31], v[8:9], off offset:1024
	global_load_dwordx4 v[36:39], v[8:9], off offset:2048
	global_load_dwordx4 v[20:23], v[8:9], off offset:3072
	v_cndmask_b32_e64 v0, 0, 1, s[16:17]
	v_cmp_ne_u32_e64 s[10:11], 1, v0
	s_andn2_b64 vcc, exec, s[16:17]
	s_cbranch_vccnz .LBB0_758
	v_lshl_add_u64 v[8:9], s[94:95], 0, v[58:59]
	v_add_co_u32_e32 v10, vcc, 0x27e50000, v8
	s_nop 1
	v_addc_co_u32_e32 v11, vcc, 0, v9, vcc
	global_load_dword v0, v[10:11], off
	v_add_co_u32_e32 v10, vcc, 0x27e70000, v8
	s_nop 1
	v_addc_co_u32_e32 v11, vcc, 0, v9, vcc
	global_load_dword v3, v[10:11], off
	v_add_co_u32_e32 v10, vcc, 0x27e90000, v8
	s_nop 1
	v_addc_co_u32_e32 v11, vcc, 0, v9, vcc
	global_load_dword v12, v[10:11], off
	v_add_co_u32_e32 v10, vcc, 0x27eb0000, v8
	s_nop 1
	v_addc_co_u32_e32 v11, vcc, 0, v9, vcc
	global_load_dword v13, v[10:11], off
	v_add_co_u32_e32 v10, vcc, 0x27ed0000, v8
	s_nop 1
	v_addc_co_u32_e32 v11, vcc, 0, v9, vcc
	global_load_dword v14, v[10:11], off
	v_add_co_u32_e32 v10, vcc, 0x27ef0000, v8
	s_nop 1
	v_addc_co_u32_e32 v11, vcc, 0, v9, vcc
	global_load_dword v15, v[10:11], off
	v_add_co_u32_e32 v10, vcc, 0x27f10000, v8
	s_nop 1
	v_addc_co_u32_e32 v11, vcc, 0, v9, vcc
	global_load_dword v16, v[10:11], off
	v_add_co_u32_e32 v10, vcc, 0x27f30000, v8
	s_nop 1
	v_addc_co_u32_e32 v11, vcc, 0, v9, vcc
	global_load_dword v17, v[10:11], off
	v_add_co_u32_e32 v10, vcc, 0x27f50000, v8
	s_nop 1
	v_addc_co_u32_e32 v11, vcc, 0, v9, vcc
	global_load_dword v18, v[10:11], off
	v_add_co_u32_e32 v10, vcc, 0x27f70000, v8
	s_nop 1
	v_addc_co_u32_e32 v11, vcc, 0, v9, vcc
	global_load_dword v19, v[10:11], off
	v_add_co_u32_e32 v10, vcc, 0x27f90000, v8
	s_nop 1
	v_addc_co_u32_e32 v11, vcc, 0, v9, vcc
	global_load_dword v24, v[10:11], off
	v_add_co_u32_e32 v10, vcc, 0x27fb0000, v8
	s_nop 1
	v_addc_co_u32_e32 v11, vcc, 0, v9, vcc
	global_load_dword v25, v[10:11], off
	v_add_co_u32_e32 v10, vcc, 0x27fd0000, v8
	s_nop 1
	v_addc_co_u32_e32 v11, vcc, 0, v9, vcc
	global_load_dword v26, v[10:11], off
	v_add_co_u32_e32 v10, vcc, 0x27ff0000, v8
	s_nop 1
	v_addc_co_u32_e32 v11, vcc, 0, v9, vcc
	global_load_dword v27, v[10:11], off
	v_add_co_u32_e32 v10, vcc, 0x28010000, v8
	s_nop 1
	v_addc_co_u32_e32 v11, vcc, 0, v9, vcc
	global_load_dword v10, v[10:11], off
	v_add_co_u32_e32 v8, vcc, 0x28030000, v8
	s_nop 1
	v_addc_co_u32_e32 v9, vcc, 0, v9, vcc
	global_load_dword v11, v[8:9], off
	v_lshl_add_u64 v[8:9], s[94:95], 0, v[60:61]
	v_add_co_u32_e32 v8, vcc, s65, v8
	s_nop 1
	v_addc_co_u32_e32 v9, vcc, 0, v9, vcc
	global_load_dwordx2 v[78:79], v[8:9], off
	global_load_dwordx2 v[76:77], v[8:9], off offset:512
	global_load_dwordx2 v[74:75], v[8:9], off offset:1024
	global_load_dwordx2 v[72:73], v[8:9], off offset:1536
	s_waitcnt vmcnt(4)
	v_add_f32_e32 v0, 0, v0
	v_add_f32_e32 v0, v0, v3
	v_add_f32_e32 v0, v0, v12
	v_add_f32_e32 v0, v0, v13
	v_add_f32_e32 v0, v0, v14
	v_add_f32_e32 v0, v0, v15
	v_add_f32_e32 v0, v0, v16
	v_add_f32_e32 v0, v0, v17
	v_add_f32_e32 v0, v0, v18
	v_add_f32_e32 v0, v0, v19
	v_add_f32_e32 v0, v0, v24
	v_add_f32_e32 v0, v0, v25
	v_add_f32_e32 v0, v0, v26
	v_add_f32_e32 v0, v0, v27
	v_add_f32_e32 v0, v0, v10
	v_add_f32_e32 v70, v0, v11
